# K-loop load segments: LDS-DMA issue ahead of the fragment ds_reads (48 segments)
# baseline (speedup 1.0000x reference)
; #define PG8_STAGE(bufoff, gbase, voff) do { _Pragma("unroll") for (int _i = 0; _i < 2; ++_i) \
;         __builtin_amdgcn_global_load_lds((const unsigned*)((const char*)(gbase) + (voff)[_i]), (LAS unsigned*)(lds + (bufoff) + ldsw + _i * 8192), 16, 0, 0); } while (0)
; #define PG8_LDA(dst, b, h) do { _Pragma("unroll") for (int m = 0; m < 4; ++m) _Pragma("unroll") for (int k = 0; k < 2; ++k) dst[m][k] = *(const LAS bf16x8*)(lds + PG8_SA(b, h) + aoff + m * 2048 + k * 1024); } while (0)
; #define PG8_LDB(dst, b, h) do { _Pragma("unroll") for (int n = 0; n < 2; ++n) _Pragma("unroll") for (int k = 0; k < 2; ++k) dst[n][k] = *(const LAS bf16x8*)(lds + PG8_SB(b, h) + boff + n * 2048 + k * 1024); } while (0)
; #define PG8_MMA(ai, bj, At, Bt) do { __builtin_amdgcn_s_setprio(1); _Pragma("unroll") for (int m = 0; m < 4; ++m) _Pragma("unroll") for (int n = 0; n < 2; ++n) _Pragma("unroll") for (int k = 0; k < 2; ++k) \
;         acc[ai][bj][m][n] = __builtin_amdgcn_mfma_f32_16x16x32_bf16(Bt[n][k], At[m][k], acc[ai][bj][m][n], 0, 0, 0); __builtin_amdgcn_s_setprio(0); } while (0)
; #define PG8_WAIT_V(n) asm volatile("s_waitcnt vmcnt(" #n ")" ::: "memory")
; #define PG8_WAIT_L(n) asm volatile("s_waitcnt lgkmcnt(" #n ")" ::: "memory")
; #define PG8_BAR __builtin_amdgcn_s_barrier()
; #define PG8_SCHED __builtin_amdgcn_sched_barrier(0)
; template <class Epi, bool ALIGN_EPI>
; __device__ __forceinline__ void gemm_phase(LAS unsigned char* lds, const Gemm g, const StaticOrder& S, const Epi& E) {
;     ...
;         for (int t = 0; t < nt; t += 2) {
;             const bool last = (t == nt - 2);
;             const char* a1 = cA + (size_t)(t + 1) * kstepA;
;             const char* a2 = last ? nA : cA + (size_t)(t + 2) * kstepA; const char* b2 = last ? nB : cB + (size_t)(t + 2) * kstep;
;             const char* a3 = a2 + kstepA; const char* b3 = b2 + kstep;
;             PG8_LDB(B0, 0, 0); PG8_LDB(B1, 0, 1); PG8_SCHED; PG8_LDA(At, 0, 0); PG8_STAGE(PG8_SA(1, 1), a1 + hsA, voffA);
;             PG8_WAIT_V(8); PG8_WAIT_L(0); PG8_BAR; PG8_MMA(0, 0, At, B0); PG8_MMA(0, 1, At, B1); PG8_BAR; PG8_SCHED;
;             PG8_LDA(At, 0, 1); PG8_STAGE(PG8_SB(0, 0), b2, voffB); PG8_STAGE(PG8_SB(0, 1), b2 + hsB, voffB); PG8_STAGE(PG8_SA(0, 0), a2, voffA);
;             PG8_WAIT_V(8); PG8_WAIT_L(0); PG8_BAR; PG8_MMA(1, 0, At, B0); PG8_MMA(1, 1, At, B1); PG8_BAR; PG8_SCHED;
.LBB0_156:
	s_add_u32 s28, s26, 0xfffc0080
	s_addc_u32 s29, s27, -1
	s_cmp_eq_u32 s54, 12
	s_cselect_b32 s31, s17, s29
	s_cselect_b32 s30, s50, s28
	s_cselect_b32 s29, s19, s53
	s_cselect_b32 s28, s51, s52
	v_lshl_add_u64 v[220:221], s[26:27], 0, v[140:141]
	s_add_i32 m0, s25, 0xc000
	s_nop 0
	global_load_lds_dwordx4 v[220:221], off
	v_lshl_add_u64 v[220:221], s[26:27], 0, v[142:143]
	s_add_i32 m0, s25, 0xe000
	s_nop 0
	global_load_lds_dwordx4 v[220:221], off
	ds_read_b128 v[156:159], v151
	ds_read_b128 v[160:163], v151 offset:1024
	ds_read_b128 v[164:167], v151 offset:2048
	ds_read_b128 v[168:171], v151 offset:3072
	ds_read_b128 v[172:175], v152
	ds_read_b128 v[176:179], v152 offset:1024
	ds_read_b128 v[180:183], v152 offset:2048
	ds_read_b128 v[184:187], v152 offset:3072
	ds_read_b128 v[188:191], v153
	ds_read_b128 v[192:195], v153 offset:1024
	ds_read_b128 v[196:199], v153 offset:2048
	ds_read_b128 v[200:203], v153 offset:3072
	ds_read_b128 v[204:207], v153 offset:4096
	ds_read_b128 v[208:211], v153 offset:5120
	ds_read_b128 v[212:215], v153 offset:6144
	ds_read_b128 v[216:219], v153 offset:7168
	s_waitcnt vmcnt(8)
	s_waitcnt lgkmcnt(0)
	s_barrier
	s_waitcnt lgkmcnt(0)
	v_mfma_f32_16x16x32_bf16 v[118:121], v[156:159], v[188:191], v[118:121]
	v_mfma_f32_16x16x32_bf16 v[114:117], v[164:167], v[188:191], v[114:117]
	v_mfma_f32_16x16x32_bf16 v[106:109], v[156:159], v[196:199], v[106:109]
	v_mfma_f32_16x16x32_bf16 v[102:105], v[164:167], v[196:199], v[102:105]
	v_mfma_f32_16x16x32_bf16 v[94:97], v[156:159], v[204:207], v[94:97]
	v_mfma_f32_16x16x32_bf16 v[90:93], v[164:167], v[204:207], v[90:93]
	v_mfma_f32_16x16x32_bf16 v[78:81], v[156:159], v[212:215], v[78:81]
	v_mfma_f32_16x16x32_bf16 v[74:77], v[164:167], v[212:215], v[74:77]
	v_mfma_f32_16x16x32_bf16 v[118:121], v[160:163], v[192:195], v[118:121]
	v_mfma_f32_16x16x32_bf16 v[114:117], v[168:171], v[192:195], v[114:117]
	v_mfma_f32_16x16x32_bf16 v[106:109], v[160:163], v[200:203], v[106:109]
	v_mfma_f32_16x16x32_bf16 v[102:105], v[168:171], v[200:203], v[102:105]
	v_mfma_f32_16x16x32_bf16 v[94:97], v[160:163], v[208:211], v[94:97]
	v_mfma_f32_16x16x32_bf16 v[90:93], v[168:171], v[208:211], v[90:93]
	v_mfma_f32_16x16x32_bf16 v[78:81], v[160:163], v[216:219], v[78:81]
	v_mfma_f32_16x16x32_bf16 v[74:77], v[168:171], v[216:219], v[74:77]
	v_mfma_f32_16x16x32_bf16 v[126:129], v[172:175], v[188:191], v[126:129]
	v_mfma_f32_16x16x32_bf16 v[122:125], v[180:183], v[188:191], v[122:125]
	v_mfma_f32_16x16x32_bf16 v[110:113], v[172:175], v[196:199], v[110:113]
	v_mfma_f32_16x16x32_bf16 v[98:101], v[180:183], v[196:199], v[98:101]
	v_mfma_f32_16x16x32_bf16 v[86:89], v[172:175], v[204:207], v[86:89]
	v_mfma_f32_16x16x32_bf16 v[82:85], v[180:183], v[204:207], v[82:85]
	v_mfma_f32_16x16x32_bf16 v[70:73], v[172:175], v[212:215], v[70:73]
	v_mfma_f32_16x16x32_bf16 v[66:69], v[180:183], v[212:215], v[66:69]
	v_mfma_f32_16x16x32_bf16 v[126:129], v[176:179], v[192:195], v[126:129]
	v_mfma_f32_16x16x32_bf16 v[122:125], v[184:187], v[192:195], v[122:125]
	v_mfma_f32_16x16x32_bf16 v[110:113], v[176:179], v[200:203], v[110:113]
	v_mfma_f32_16x16x32_bf16 v[98:101], v[184:187], v[200:203], v[98:101]
	v_mfma_f32_16x16x32_bf16 v[86:89], v[176:179], v[208:211], v[86:89]
	v_mfma_f32_16x16x32_bf16 v[82:85], v[184:187], v[208:211], v[82:85]
	v_mfma_f32_16x16x32_bf16 v[70:73], v[176:179], v[216:219], v[70:73]
	v_mfma_f32_16x16x32_bf16 v[66:69], v[184:187], v[216:219], v[66:69]
	s_barrier
	s_add_i32 s55, s46, s33
	v_lshl_add_u64 v[220:221], s[28:29], 0, v[134:135]
	s_mov_b32 m0, s55
	s_nop 0
	global_load_lds_dwordx4 v[220:221], off
	s_add_i32 m0, s55, 0x2000
	s_add_u32 s56, s28, 0x40000
	v_lshl_add_u64 v[222:223], s[28:29], 0, v[130:131]
	s_addc_u32 s57, s29, 0
	s_add_i32 s55, s47, s33
	global_load_lds_dwordx4 v[222:223], off
	v_lshl_add_u64 v[224:225], s[56:57], 0, v[134:135]
	s_mov_b32 m0, s55
	v_lshl_add_u64 v[226:227], s[30:31], 0, v[132:133]
	global_load_lds_dwordx4 v[224:225], off
	v_lshl_add_u64 v[224:225], s[56:57], 0, v[130:131]
	s_add_i32 m0, s55, 0x2000
	s_nop 0
	global_load_lds_dwordx4 v[224:225], off
	v_lshl_add_u64 v[224:225], s[30:31], 0, v[136:137]
	s_mov_b32 m0, s25
	s_nop 0
	global_load_lds_dwordx4 v[224:225], off
	s_mov_b32 m0, s36
	s_nop 0
	global_load_lds_dwordx4 v[226:227], off
	ds_read_b128 v[188:191], v153 offset:16384
	ds_read_b128 v[192:195], v153 offset:17408
	ds_read_b128 v[196:199], v153 offset:18432
	ds_read_b128 v[200:203], v153 offset:19456
	ds_read_b128 v[204:207], v153 offset:20480
	ds_read_b128 v[208:211], v153 offset:21504
	ds_read_b128 v[212:215], v153 offset:22528
	ds_read_b128 v[216:219], v153 offset:23552
	s_waitcnt vmcnt(8)
	s_waitcnt lgkmcnt(0)
	s_barrier
; #define PG8_STAGE(bufoff, gbase, voff) do { _Pragma("unroll") for (int _i = 0; _i < 2; ++_i) \
;         __builtin_amdgcn_global_load_lds((const unsigned*)((const char*)(gbase) + (voff)[_i]), (LAS unsigned*)(lds + (bufoff) + ldsw + _i * 8192), 16, 0, 0); } while (0)
; #define PG8_LDA(dst, b, h) do { _Pragma("unroll") for (int m = 0; m < 4; ++m) _Pragma("unroll") for (int k = 0; k < 2; ++k) dst[m][k] = *(const LAS bf16x8*)(lds + PG8_SA(b, h) + aoff + m * 2048 + k * 1024); } while (0)
; #define PG8_LDB(dst, b, h) do { _Pragma("unroll") for (int n = 0; n < 2; ++n) _Pragma("unroll") for (int k = 0; k < 2; ++k) dst[n][k] = *(const LAS bf16x8*)(lds + PG8_SB(b, h) + boff + n * 2048 + k * 1024); } while (0)
; #define PG8_MMA(ai, bj, At, Bt) do { __builtin_amdgcn_s_setprio(1); _Pragma("unroll") for (int m = 0; m < 4; ++m) _Pragma("unroll") for (int n = 0; n < 2; ++n) _Pragma("unroll") for (int k = 0; k < 2; ++k) \
;         acc[ai][bj][m][n] = __builtin_amdgcn_mfma_f32_16x16x32_bf16(Bt[n][k], At[m][k], acc[ai][bj][m][n], 0, 0, 0); __builtin_amdgcn_s_setprio(0); } while (0)
; #define PG8_WAIT_V(n) asm volatile("s_waitcnt vmcnt(" #n ")" ::: "memory")
; #define PG8_WAIT_L(n) asm volatile("s_waitcnt lgkmcnt(" #n ")" ::: "memory")
; #define PG8_BAR __builtin_amdgcn_s_barrier()
; #define PG8_SCHED __builtin_amdgcn_sched_barrier(0)
; template <class Epi, bool ALIGN_EPI>
; __device__ __forceinline__ void gemm_phase(LAS unsigned char* lds, const Gemm g, const StaticOrder& S, const Epi& E) {
;     ...
;             PG8_WAIT_V(8); PG8_WAIT_L(0); PG8_BAR; PG8_MMA(1, 0, At, B0); PG8_MMA(1, 1, At, B1); PG8_BAR; PG8_SCHED;
;             PG8_LDB(B0, 1, 0); PG8_LDB(B1, 1, 1); PG8_SCHED; PG8_LDA(At, 1, 0); PG8_STAGE(PG8_SA(0, 1), a2 + hsA, voffA);
;             PG8_WAIT_V(8); PG8_WAIT_L(0); PG8_BAR; PG8_MMA(0, 0, At, B0); PG8_MMA(0, 1, At, B1); PG8_BAR; PG8_SCHED;
	s_waitcnt lgkmcnt(0)
	v_mfma_f32_16x16x32_bf16 v[62:65], v[156:159], v[188:191], v[62:65]
	v_mfma_f32_16x16x32_bf16 v[58:61], v[164:167], v[188:191], v[58:61]
	v_mfma_f32_16x16x32_bf16 v[46:49], v[156:159], v[196:199], v[46:49]
	v_mfma_f32_16x16x32_bf16 v[42:45], v[164:167], v[196:199], v[42:45]
	v_mfma_f32_16x16x32_bf16 v[30:33], v[156:159], v[204:207], v[30:33]
	v_mfma_f32_16x16x32_bf16 v[26:29], v[164:167], v[204:207], v[26:29]
	v_mfma_f32_16x16x32_bf16 v[14:17], v[156:159], v[212:215], v[14:17]
	v_mfma_f32_16x16x32_bf16 v[10:13], v[164:167], v[212:215], v[10:13]
	v_mfma_f32_16x16x32_bf16 v[62:65], v[160:163], v[192:195], v[62:65]
	v_mfma_f32_16x16x32_bf16 v[58:61], v[168:171], v[192:195], v[58:61]
	v_mfma_f32_16x16x32_bf16 v[46:49], v[160:163], v[200:203], v[46:49]
	v_mfma_f32_16x16x32_bf16 v[42:45], v[168:171], v[200:203], v[42:45]
	v_mfma_f32_16x16x32_bf16 v[30:33], v[160:163], v[208:211], v[30:33]
	v_mfma_f32_16x16x32_bf16 v[26:29], v[168:171], v[208:211], v[26:29]
	v_mfma_f32_16x16x32_bf16 v[14:17], v[160:163], v[216:219], v[14:17]
	v_mfma_f32_16x16x32_bf16 v[10:13], v[168:171], v[216:219], v[10:13]
	v_mfma_f32_16x16x32_bf16 v[54:57], v[172:175], v[188:191], v[54:57]
	v_mfma_f32_16x16x32_bf16 v[50:53], v[180:183], v[188:191], v[50:53]
	v_mfma_f32_16x16x32_bf16 v[38:41], v[172:175], v[196:199], v[38:41]
	v_mfma_f32_16x16x32_bf16 v[34:37], v[180:183], v[196:199], v[34:37]
	v_mfma_f32_16x16x32_bf16 v[22:25], v[172:175], v[204:207], v[22:25]
	v_mfma_f32_16x16x32_bf16 v[18:21], v[180:183], v[204:207], v[18:21]
	v_mfma_f32_16x16x32_bf16 v[6:9], v[172:175], v[212:215], v[6:9]
	v_mfma_f32_16x16x32_bf16 v[2:5], v[180:183], v[212:215], v[2:5]
	v_mfma_f32_16x16x32_bf16 v[54:57], v[176:179], v[192:195], v[54:57]
	v_mfma_f32_16x16x32_bf16 v[50:53], v[184:187], v[192:195], v[50:53]
	v_mfma_f32_16x16x32_bf16 v[38:41], v[176:179], v[200:203], v[38:41]
	v_mfma_f32_16x16x32_bf16 v[34:37], v[184:187], v[200:203], v[34:37]
	v_mfma_f32_16x16x32_bf16 v[22:25], v[176:179], v[208:211], v[22:25]
	v_mfma_f32_16x16x32_bf16 v[18:21], v[184:187], v[208:211], v[18:21]
	v_mfma_f32_16x16x32_bf16 v[6:9], v[176:179], v[216:219], v[6:9]
	v_mfma_f32_16x16x32_bf16 v[2:5], v[184:187], v[216:219], v[2:5]
	s_barrier
	s_add_i32 s55, 0, 0x18000
	s_add_i32 s56, 0, 0x1c000
	s_add_u32 s30, s30, 0x40000
	s_addc_u32 s31, s31, 0
	s_mov_b32 m0, s37
	v_lshl_add_u64 v[228:229], s[30:31], 0, v[136:137]
	global_load_lds_dwordx4 v[228:229], off
	v_lshl_add_u64 v[228:229], s[30:31], 0, v[132:133]
	s_mov_b32 m0, s38
	s_nop 0
	global_load_lds_dwordx4 v[228:229], off
	v_add_u32_e32 v138, s55, v150
	ds_read_b128 v[156:159], v138
	ds_read_b128 v[160:163], v138 offset:1024
	ds_read_b128 v[164:167], v138 offset:2048
	ds_read_b128 v[168:171], v138 offset:3072
	v_add_u32_e32 v138, s56, v150
	ds_read_b128 v[172:175], v138
	ds_read_b128 v[176:179], v138 offset:1024
	ds_read_b128 v[180:183], v138 offset:2048
	ds_read_b128 v[184:187], v138 offset:3072
	ds_read_b128 v[188:191], v153 offset:32768
	ds_read_b128 v[192:195], v153 offset:33792
	ds_read_b128 v[196:199], v153 offset:34816
	ds_read_b128 v[200:203], v153 offset:35840
	ds_read_b128 v[204:207], v153 offset:36864
	ds_read_b128 v[208:211], v153 offset:37888
	ds_read_b128 v[212:215], v153 offset:38912
	ds_read_b128 v[216:219], v153 offset:39936
	s_waitcnt vmcnt(8)
	s_waitcnt lgkmcnt(0)
	s_barrier
	s_waitcnt lgkmcnt(0)
	v_mfma_f32_16x16x32_bf16 v[118:121], v[156:159], v[188:191], v[118:121]
	v_mfma_f32_16x16x32_bf16 v[114:117], v[164:167], v[188:191], v[114:117]
	v_mfma_f32_16x16x32_bf16 v[106:109], v[156:159], v[196:199], v[106:109]
	v_mfma_f32_16x16x32_bf16 v[102:105], v[164:167], v[196:199], v[102:105]
	v_mfma_f32_16x16x32_bf16 v[94:97], v[156:159], v[204:207], v[94:97]
	v_mfma_f32_16x16x32_bf16 v[90:93], v[164:167], v[204:207], v[90:93]
	v_mfma_f32_16x16x32_bf16 v[78:81], v[156:159], v[212:215], v[78:81]
	v_mfma_f32_16x16x32_bf16 v[74:77], v[164:167], v[212:215], v[74:77]
	v_mfma_f32_16x16x32_bf16 v[118:121], v[160:163], v[192:195], v[118:121]
	v_mfma_f32_16x16x32_bf16 v[114:117], v[168:171], v[192:195], v[114:117]
	v_mfma_f32_16x16x32_bf16 v[106:109], v[160:163], v[200:203], v[106:109]
	v_mfma_f32_16x16x32_bf16 v[102:105], v[168:171], v[200:203], v[102:105]
	v_mfma_f32_16x16x32_bf16 v[94:97], v[160:163], v[208:211], v[94:97]
	v_mfma_f32_16x16x32_bf16 v[90:93], v[168:171], v[208:211], v[90:93]
	v_mfma_f32_16x16x32_bf16 v[78:81], v[160:163], v[216:219], v[78:81]
	v_mfma_f32_16x16x32_bf16 v[74:77], v[168:171], v[216:219], v[74:77]
	v_mfma_f32_16x16x32_bf16 v[126:129], v[172:175], v[188:191], v[126:129]
	v_mfma_f32_16x16x32_bf16 v[122:125], v[180:183], v[188:191], v[122:125]
	v_mfma_f32_16x16x32_bf16 v[110:113], v[172:175], v[196:199], v[110:113]
	v_mfma_f32_16x16x32_bf16 v[98:101], v[180:183], v[196:199], v[98:101]
	v_mfma_f32_16x16x32_bf16 v[86:89], v[172:175], v[204:207], v[86:89]
	v_mfma_f32_16x16x32_bf16 v[82:85], v[180:183], v[204:207], v[82:85]
	v_mfma_f32_16x16x32_bf16 v[70:73], v[172:175], v[212:215], v[70:73]
	v_mfma_f32_16x16x32_bf16 v[66:69], v[180:183], v[212:215], v[66:69]
	v_mfma_f32_16x16x32_bf16 v[126:129], v[176:179], v[192:195], v[126:129]
	v_mfma_f32_16x16x32_bf16 v[122:125], v[184:187], v[192:195], v[122:125]
	v_mfma_f32_16x16x32_bf16 v[110:113], v[176:179], v[200:203], v[110:113]
	v_mfma_f32_16x16x32_bf16 v[98:101], v[184:187], v[200:203], v[98:101]
	v_mfma_f32_16x16x32_bf16 v[86:89], v[176:179], v[208:211], v[86:89]
	v_mfma_f32_16x16x32_bf16 v[82:85], v[184:187], v[208:211], v[82:85]
	v_mfma_f32_16x16x32_bf16 v[70:73], v[176:179], v[216:219], v[70:73]
	v_mfma_f32_16x16x32_bf16 v[66:69], v[184:187], v[216:219], v[66:69]
	s_barrier
; #define PG8_STAGE(bufoff, gbase, voff) do { _Pragma("unroll") for (int _i = 0; _i < 2; ++_i) \
;         __builtin_amdgcn_global_load_lds((const unsigned*)((const char*)(gbase) + (voff)[_i]), (LAS unsigned*)(lds + (bufoff) + ldsw + _i * 8192), 16, 0, 0); } while (0)
; #define PG8_LDA(dst, b, h) do { _Pragma("unroll") for (int m = 0; m < 4; ++m) _Pragma("unroll") for (int k = 0; k < 2; ++k) dst[m][k] = *(const LAS bf16x8*)(lds + PG8_SA(b, h) + aoff + m * 2048 + k * 1024); } while (0)
; #define PG8_MMA(ai, bj, At, Bt) do { __builtin_amdgcn_s_setprio(1); _Pragma("unroll") for (int m = 0; m < 4; ++m) _Pragma("unroll") for (int n = 0; n < 2; ++n) _Pragma("unroll") for (int k = 0; k < 2; ++k) \
;         acc[ai][bj][m][n] = __builtin_amdgcn_mfma_f32_16x16x32_bf16(Bt[n][k], At[m][k], acc[ai][bj][m][n], 0, 0, 0); __builtin_amdgcn_s_setprio(0); } while (0)
; #define PG8_WAIT_V(n) asm volatile("s_waitcnt vmcnt(" #n ")" ::: "memory")
; #define PG8_WAIT_L(n) asm volatile("s_waitcnt lgkmcnt(" #n ")" ::: "memory")
; #define PG8_BAR __builtin_amdgcn_s_barrier()
; #define PG8_SCHED __builtin_amdgcn_sched_barrier(0)
; template <class Epi, bool ALIGN_EPI>
; __device__ __forceinline__ void gemm_phase(LAS unsigned char* lds, const Gemm g, const StaticOrder& S, const Epi& E) {
;     ...
;             PG8_LDA(At, 1, 1); PG8_STAGE(PG8_SB(1, 0), b3, voffB); PG8_STAGE(PG8_SB(1, 1), b3 + hsB, voffB); PG8_STAGE(PG8_SA(1, 0), a3, voffA);
;             PG8_WAIT_V(8); PG8_WAIT_L(0); PG8_BAR; PG8_MMA(1, 0, At, B0); PG8_MMA(1, 1, At, B1); PG8_BAR; PG8_SCHED;
;         }
	s_add_i32 s30, s55, s33
	v_lshl_add_u64 v[220:221], v[220:221], 0, s[12:13]
	s_mov_b32 m0, s30
	s_nop 0
	global_load_lds_dwordx4 v[220:221], off
	s_add_i32 m0, s30, 0x2000
	s_add_u32 s28, s28, 0x40080
	v_lshl_add_u64 v[220:221], v[222:223], 0, s[12:13]
	s_addc_u32 s29, s29, 0
	s_add_i32 s30, s56, s33
	global_load_lds_dwordx4 v[220:221], off
	v_lshl_add_u64 v[220:221], s[28:29], 0, v[134:135]
	s_mov_b32 m0, s30
	s_nop 0
	global_load_lds_dwordx4 v[220:221], off
	v_lshl_add_u64 v[220:221], s[28:29], 0, v[130:131]
	s_add_i32 m0, s30, 0x2000
	s_nop 0
	global_load_lds_dwordx4 v[220:221], off
	v_lshl_add_u64 v[220:221], v[224:225], 0, s[12:13]
	s_mov_b32 m0, s42
	s_nop 0
	global_load_lds_dwordx4 v[220:221], off
	v_lshl_add_u64 v[220:221], v[226:227], 0, s[12:13]
	s_mov_b32 m0, s43
	s_nop 0
	global_load_lds_dwordx4 v[220:221], off
	ds_read_b128 v[188:191], v153 offset:49152
	ds_read_b128 v[192:195], v153 offset:50176
	ds_read_b128 v[196:199], v153 offset:51200
	ds_read_b128 v[200:203], v153 offset:52224
	ds_read_b128 v[204:207], v153 offset:53248
	ds_read_b128 v[208:211], v153 offset:54272
	ds_read_b128 v[212:215], v153 offset:55296
	ds_read_b128 v[216:219], v153 offset:56320
	s_waitcnt vmcnt(8)
	s_waitcnt lgkmcnt(0)
	s_barrier
	s_waitcnt lgkmcnt(0)
	v_mfma_f32_16x16x32_bf16 v[62:65], v[156:159], v[188:191], v[62:65]
	v_mfma_f32_16x16x32_bf16 v[58:61], v[164:167], v[188:191], v[58:61]
	v_mfma_f32_16x16x32_bf16 v[46:49], v[156:159], v[196:199], v[46:49]
	v_mfma_f32_16x16x32_bf16 v[42:45], v[164:167], v[196:199], v[42:45]
	v_mfma_f32_16x16x32_bf16 v[30:33], v[156:159], v[204:207], v[30:33]
	v_mfma_f32_16x16x32_bf16 v[26:29], v[164:167], v[204:207], v[26:29]
	v_mfma_f32_16x16x32_bf16 v[14:17], v[156:159], v[212:215], v[14:17]
	v_mfma_f32_16x16x32_bf16 v[10:13], v[164:167], v[212:215], v[10:13]
	v_mfma_f32_16x16x32_bf16 v[62:65], v[160:163], v[192:195], v[62:65]
	v_mfma_f32_16x16x32_bf16 v[58:61], v[168:171], v[192:195], v[58:61]
	v_mfma_f32_16x16x32_bf16 v[46:49], v[160:163], v[200:203], v[46:49]
	v_mfma_f32_16x16x32_bf16 v[42:45], v[168:171], v[200:203], v[42:45]
	v_mfma_f32_16x16x32_bf16 v[30:33], v[160:163], v[208:211], v[30:33]
	v_mfma_f32_16x16x32_bf16 v[26:29], v[168:171], v[208:211], v[26:29]
	v_mfma_f32_16x16x32_bf16 v[14:17], v[160:163], v[216:219], v[14:17]
	v_mfma_f32_16x16x32_bf16 v[10:13], v[168:171], v[216:219], v[10:13]
	v_mfma_f32_16x16x32_bf16 v[54:57], v[172:175], v[188:191], v[54:57]
	v_mfma_f32_16x16x32_bf16 v[50:53], v[180:183], v[188:191], v[50:53]
	v_mfma_f32_16x16x32_bf16 v[38:41], v[172:175], v[196:199], v[38:41]
	v_mfma_f32_16x16x32_bf16 v[34:37], v[180:183], v[196:199], v[34:37]
	v_mfma_f32_16x16x32_bf16 v[22:25], v[172:175], v[204:207], v[22:25]
	v_mfma_f32_16x16x32_bf16 v[18:21], v[180:183], v[204:207], v[18:21]
	v_mfma_f32_16x16x32_bf16 v[6:9], v[172:175], v[212:215], v[6:9]
	v_mfma_f32_16x16x32_bf16 v[2:5], v[180:183], v[212:215], v[2:5]
	v_mfma_f32_16x16x32_bf16 v[54:57], v[176:179], v[192:195], v[54:57]
	v_mfma_f32_16x16x32_bf16 v[50:53], v[184:187], v[192:195], v[50:53]
	v_mfma_f32_16x16x32_bf16 v[38:41], v[176:179], v[200:203], v[38:41]
	v_mfma_f32_16x16x32_bf16 v[34:37], v[184:187], v[200:203], v[34:37]
	v_mfma_f32_16x16x32_bf16 v[22:25], v[176:179], v[208:211], v[22:25]
	v_mfma_f32_16x16x32_bf16 v[18:21], v[184:187], v[208:211], v[18:21]
	v_mfma_f32_16x16x32_bf16 v[6:9], v[176:179], v[216:219], v[6:9]
	v_mfma_f32_16x16x32_bf16 v[2:5], v[184:187], v[216:219], v[2:5]
	s_barrier
	s_add_i32 s54, s54, 2
	s_add_u32 s26, s26, 0x100
	s_addc_u32 s27, s27, 0
	s_add_u32 s52, s52, 0x100
	s_addc_u32 s53, s53, 0
	s_cmp_gt_u32 s54, 13
	s_cbranch_scc0 .LBB0_156
	s_and_b64 vcc, exec, s[14:15]
	s_cbranch_vccz .LBB0_159
	s_barrier

; #define PG8_STAGE(bufoff, gbase, voff) do { _Pragma("unroll") for (int _i = 0; _i < 2; ++_i) \
;         __builtin_amdgcn_global_load_lds((const unsigned*)((const char*)(gbase) + (voff)[_i]), (LAS unsigned*)(lds + (bufoff) + ldsw + _i * 8192), 16, 0, 0); } while (0)
; #define PG8_LDA(dst, b, h) do { _Pragma("unroll") for (int m = 0; m < 4; ++m) _Pragma("unroll") for (int k = 0; k < 2; ++k) dst[m][k] = *(const LAS bf16x8*)(lds + PG8_SA(b, h) + aoff + m * 2048 + k * 1024); } while (0)
; #define PG8_LDB(dst, b, h) do { _Pragma("unroll") for (int n = 0; n < 2; ++n) _Pragma("unroll") for (int k = 0; k < 2; ++k) dst[n][k] = *(const LAS bf16x8*)(lds + PG8_SB(b, h) + boff + n * 2048 + k * 1024); } while (0)
; #define PG8_MMA(ai, bj, At, Bt) do { __builtin_amdgcn_s_setprio(1); _Pragma("unroll") for (int m = 0; m < 4; ++m) _Pragma("unroll") for (int n = 0; n < 2; ++n) _Pragma("unroll") for (int k = 0; k < 2; ++k) \
;         acc[ai][bj][m][n] = __builtin_amdgcn_mfma_f32_16x16x32_bf16(Bt[n][k], At[m][k], acc[ai][bj][m][n], 0, 0, 0); __builtin_amdgcn_s_setprio(0); } while (0)
; #define PG8_WAIT_V(n) asm volatile("s_waitcnt vmcnt(" #n ")" ::: "memory")
; #define PG8_WAIT_L(n) asm volatile("s_waitcnt lgkmcnt(" #n ")" ::: "memory")
; #define PG8_BAR __builtin_amdgcn_s_barrier()
; #define PG8_SCHED __builtin_amdgcn_sched_barrier(0)
; template <class Epi, bool ALIGN_EPI>
; __device__ __forceinline__ void gemm_phase(LAS unsigned char* lds, const Gemm g, const StaticOrder& S, const Epi& E) {
;     ...
;         for (int t = 0; t < nt; t += 2) {
;             const bool last = (t == nt - 2);
;             const char* a1 = cA + (size_t)(t + 1) * kstepA;
;             const char* a2 = last ? nA : cA + (size_t)(t + 2) * kstepA; const char* b2 = last ? nB : cB + (size_t)(t + 2) * kstep;
;             const char* a3 = a2 + kstepA; const char* b3 = b2 + kstep;
;             PG8_LDB(B0, 0, 0); PG8_LDB(B1, 0, 1); PG8_SCHED; PG8_LDA(At, 0, 0); PG8_STAGE(PG8_SA(1, 1), a1 + hsA, voffA);
;             PG8_WAIT_V(8); PG8_WAIT_L(0); PG8_BAR; PG8_MMA(0, 0, At, B0); PG8_MMA(0, 1, At, B1); PG8_BAR; PG8_SCHED;
;             PG8_LDA(At, 0, 1); PG8_STAGE(PG8_SB(0, 0), b2, voffB); PG8_STAGE(PG8_SB(0, 1), b2 + hsB, voffB); PG8_STAGE(PG8_SA(0, 0), a2, voffA);
.LBB0_330:
	s_add_u32 s14, s12, 0x4000
	s_addc_u32 s15, s13, 0
	s_cmp_eq_u32 s48, 40
	s_cselect_b32 s18, s6, s14
	s_cselect_b32 s19, s7, s15
	s_cselect_b32 s16, s42, s46
	s_cselect_b32 s17, s43, s47
	s_add_u32 s14, s18, 0x8000
	s_addc_u32 s15, s19, 0
	v_lshl_add_u64 v[186:187], s[12:13], 0, v[162:163]
	s_add_i32 m0, s21, 0xc000
	s_nop 0
	global_load_lds_dwordx4 v[186:187], off
	v_lshl_add_u64 v[186:187], s[12:13], 0, v[164:165]
	s_add_i32 m0, s21, 0xe000
	s_nop 0
	global_load_lds_dwordx4 v[186:187], off
	ds_read_b128 v[118:121], v190
	ds_read_b128 v[126:129], v190 offset:1024
	ds_read_b128 v[138:141], v190 offset:2048
	ds_read_b128 v[142:145], v190 offset:3072
	ds_read_b128 v[146:149], v191
	ds_read_b128 v[150:153], v191 offset:1024
	ds_read_b128 v[170:173], v191 offset:2048
	ds_read_b128 v[174:177], v191 offset:3072
	ds_read_b128 v[178:181], v192
	ds_read_b128 v[182:185], v192 offset:1024
	ds_read_b128 v[194:197], v192 offset:2048
	ds_read_b128 v[198:201], v192 offset:3072
	ds_read_b128 v[202:205], v192 offset:4096
	ds_read_b128 v[206:209], v192 offset:5120
	ds_read_b128 v[210:213], v192 offset:6144
	ds_read_b128 v[214:217], v192 offset:7168
	s_waitcnt vmcnt(8)
	s_waitcnt lgkmcnt(0)
	s_barrier
	s_waitcnt lgkmcnt(0)
	v_mfma_f32_16x16x32_bf16 v[134:137], v[118:121], v[178:181], v[134:137]
	v_mfma_f32_16x16x32_bf16 v[130:133], v[138:141], v[178:181], v[130:133]
	v_mfma_f32_16x16x32_bf16 v[110:113], v[118:121], v[194:197], v[110:113]
	v_mfma_f32_16x16x32_bf16 v[106:109], v[138:141], v[194:197], v[106:109]
	v_mfma_f32_16x16x32_bf16 v[94:97], v[118:121], v[202:205], v[94:97]
	v_mfma_f32_16x16x32_bf16 v[90:93], v[138:141], v[202:205], v[90:93]
	v_mfma_f32_16x16x32_bf16 v[78:81], v[118:121], v[210:213], v[78:81]
	v_mfma_f32_16x16x32_bf16 v[74:77], v[138:141], v[210:213], v[74:77]
	v_mfma_f32_16x16x32_bf16 v[134:137], v[126:129], v[182:185], v[134:137]
	v_mfma_f32_16x16x32_bf16 v[130:133], v[142:145], v[182:185], v[130:133]
	v_mfma_f32_16x16x32_bf16 v[110:113], v[126:129], v[198:201], v[110:113]
	v_mfma_f32_16x16x32_bf16 v[106:109], v[142:145], v[198:201], v[106:109]
	v_mfma_f32_16x16x32_bf16 v[94:97], v[126:129], v[206:209], v[94:97]
	v_mfma_f32_16x16x32_bf16 v[90:93], v[142:145], v[206:209], v[90:93]
	v_mfma_f32_16x16x32_bf16 v[78:81], v[126:129], v[214:217], v[78:81]
	v_mfma_f32_16x16x32_bf16 v[74:77], v[142:145], v[214:217], v[74:77]
	v_mfma_f32_16x16x32_bf16 v[122:125], v[146:149], v[178:181], v[122:125]
	v_mfma_f32_16x16x32_bf16 v[114:117], v[170:173], v[178:181], v[114:117]
	v_mfma_f32_16x16x32_bf16 v[102:105], v[146:149], v[194:197], v[102:105]
	v_mfma_f32_16x16x32_bf16 v[98:101], v[170:173], v[194:197], v[98:101]
	v_mfma_f32_16x16x32_bf16 v[86:89], v[146:149], v[202:205], v[86:89]
	v_mfma_f32_16x16x32_bf16 v[82:85], v[170:173], v[202:205], v[82:85]
	v_mfma_f32_16x16x32_bf16 v[70:73], v[146:149], v[210:213], v[70:73]
	v_mfma_f32_16x16x32_bf16 v[66:69], v[170:173], v[210:213], v[66:69]
	v_mfma_f32_16x16x32_bf16 v[122:125], v[150:153], v[182:185], v[122:125]
	v_mfma_f32_16x16x32_bf16 v[114:117], v[174:177], v[182:185], v[114:117]
	v_mfma_f32_16x16x32_bf16 v[102:105], v[150:153], v[198:201], v[102:105]
	v_mfma_f32_16x16x32_bf16 v[98:101], v[174:177], v[198:201], v[98:101]
	v_mfma_f32_16x16x32_bf16 v[86:89], v[150:153], v[206:209], v[86:89]
	v_mfma_f32_16x16x32_bf16 v[82:85], v[174:177], v[206:209], v[82:85]
	v_mfma_f32_16x16x32_bf16 v[70:73], v[150:153], v[214:217], v[70:73]
	v_mfma_f32_16x16x32_bf16 v[66:69], v[174:177], v[214:217], v[66:69]
	s_barrier
	s_add_i32 s49, s31, s20
	v_lshl_add_u64 v[186:187], s[16:17], 0, v[156:157]
	s_mov_b32 m0, s49
	s_nop 0
	global_load_lds_dwordx4 v[186:187], off
	s_add_i32 m0, s49, 0x2000
	s_add_u32 s50, s16, 0xb0000
	v_lshl_add_u64 v[218:219], s[16:17], 0, v[160:161]
	s_addc_u32 s51, s17, 0
	s_add_i32 s49, s33, s20
	global_load_lds_dwordx4 v[218:219], off
	v_lshl_add_u64 v[220:221], s[50:51], 0, v[156:157]
	s_mov_b32 m0, s49
	s_nop 0
	global_load_lds_dwordx4 v[220:221], off
	v_lshl_add_u64 v[220:221], s[50:51], 0, v[160:161]
	s_add_i32 m0, s49, 0x2000
	s_nop 0
	global_load_lds_dwordx4 v[220:221], off
	v_lshl_add_u64 v[220:221], s[18:19], 0, v[154:155]
	s_mov_b32 m0, s21
	s_nop 0
	global_load_lds_dwordx4 v[220:221], off
	v_lshl_add_u64 v[220:221], s[18:19], 0, v[158:159]
	s_mov_b32 m0, s22
	s_nop 0
	global_load_lds_dwordx4 v[220:221], off
	ds_read_b128 v[178:181], v192 offset:16384
	ds_read_b128 v[182:185], v192 offset:17408
	ds_read_b128 v[194:197], v192 offset:18432
	ds_read_b128 v[198:201], v192 offset:19456
	ds_read_b128 v[202:205], v192 offset:20480
	ds_read_b128 v[206:209], v192 offset:21504
	ds_read_b128 v[210:213], v192 offset:22528
	ds_read_b128 v[214:217], v192 offset:23552
	s_waitcnt vmcnt(8)
	s_waitcnt lgkmcnt(0)
	s_barrier
; #define PG8_STAGE(bufoff, gbase, voff) do { _Pragma("unroll") for (int _i = 0; _i < 2; ++_i) \
;         __builtin_amdgcn_global_load_lds((const unsigned*)((const char*)(gbase) + (voff)[_i]), (LAS unsigned*)(lds + (bufoff) + ldsw + _i * 8192), 16, 0, 0); } while (0)
; #define PG8_LDA(dst, b, h) do { _Pragma("unroll") for (int m = 0; m < 4; ++m) _Pragma("unroll") for (int k = 0; k < 2; ++k) dst[m][k] = *(const LAS bf16x8*)(lds + PG8_SA(b, h) + aoff + m * 2048 + k * 1024); } while (0)
; #define PG8_LDB(dst, b, h) do { _Pragma("unroll") for (int n = 0; n < 2; ++n) _Pragma("unroll") for (int k = 0; k < 2; ++k) dst[n][k] = *(const LAS bf16x8*)(lds + PG8_SB(b, h) + boff + n * 2048 + k * 1024); } while (0)
; #define PG8_MMA(ai, bj, At, Bt) do { __builtin_amdgcn_s_setprio(1); _Pragma("unroll") for (int m = 0; m < 4; ++m) _Pragma("unroll") for (int n = 0; n < 2; ++n) _Pragma("unroll") for (int k = 0; k < 2; ++k) \
;         acc[ai][bj][m][n] = __builtin_amdgcn_mfma_f32_16x16x32_bf16(Bt[n][k], At[m][k], acc[ai][bj][m][n], 0, 0, 0); __builtin_amdgcn_s_setprio(0); } while (0)
; #define PG8_WAIT_V(n) asm volatile("s_waitcnt vmcnt(" #n ")" ::: "memory")
; #define PG8_WAIT_L(n) asm volatile("s_waitcnt lgkmcnt(" #n ")" ::: "memory")
; #define PG8_BAR __builtin_amdgcn_s_barrier()
; #define PG8_SCHED __builtin_amdgcn_sched_barrier(0)
; template <class Epi, bool ALIGN_EPI>
; __device__ __forceinline__ void gemm_phase(LAS unsigned char* lds, const Gemm g, const StaticOrder& S, const Epi& E) {
;     ...
;             PG8_WAIT_V(8); PG8_WAIT_L(0); PG8_BAR; PG8_MMA(1, 0, At, B0); PG8_MMA(1, 1, At, B1); PG8_BAR; PG8_SCHED;
;             PG8_LDB(B0, 1, 0); PG8_LDB(B1, 1, 1); PG8_SCHED; PG8_LDA(At, 1, 0); PG8_STAGE(PG8_SA(0, 1), a2 + hsA, voffA);
;             PG8_WAIT_V(8); PG8_WAIT_L(0); PG8_BAR; PG8_MMA(0, 0, At, B0); PG8_MMA(0, 1, At, B1); PG8_BAR; PG8_SCHED;
	s_waitcnt lgkmcnt(0)
	v_mfma_f32_16x16x32_bf16 v[62:65], v[118:121], v[178:181], v[62:65]
	v_mfma_f32_16x16x32_bf16 v[58:61], v[138:141], v[178:181], v[58:61]
	v_mfma_f32_16x16x32_bf16 v[46:49], v[118:121], v[194:197], v[46:49]
	v_mfma_f32_16x16x32_bf16 v[42:45], v[138:141], v[194:197], v[42:45]
	v_mfma_f32_16x16x32_bf16 v[30:33], v[118:121], v[202:205], v[30:33]
	v_mfma_f32_16x16x32_bf16 v[26:29], v[138:141], v[202:205], v[26:29]
	v_mfma_f32_16x16x32_bf16 v[14:17], v[118:121], v[210:213], v[14:17]
	v_mfma_f32_16x16x32_bf16 v[10:13], v[138:141], v[210:213], v[10:13]
	v_mfma_f32_16x16x32_bf16 v[62:65], v[126:129], v[182:185], v[62:65]
	v_mfma_f32_16x16x32_bf16 v[58:61], v[142:145], v[182:185], v[58:61]
	v_mfma_f32_16x16x32_bf16 v[46:49], v[126:129], v[198:201], v[46:49]
	v_mfma_f32_16x16x32_bf16 v[42:45], v[142:145], v[198:201], v[42:45]
	v_mfma_f32_16x16x32_bf16 v[30:33], v[126:129], v[206:209], v[30:33]
	v_mfma_f32_16x16x32_bf16 v[26:29], v[142:145], v[206:209], v[26:29]
	v_mfma_f32_16x16x32_bf16 v[14:17], v[126:129], v[214:217], v[14:17]
	v_mfma_f32_16x16x32_bf16 v[10:13], v[142:145], v[214:217], v[10:13]
	v_mfma_f32_16x16x32_bf16 v[54:57], v[146:149], v[178:181], v[54:57]
	v_mfma_f32_16x16x32_bf16 v[50:53], v[170:173], v[178:181], v[50:53]
	v_mfma_f32_16x16x32_bf16 v[38:41], v[146:149], v[194:197], v[38:41]
	v_mfma_f32_16x16x32_bf16 v[34:37], v[170:173], v[194:197], v[34:37]
	v_mfma_f32_16x16x32_bf16 v[22:25], v[146:149], v[202:205], v[22:25]
	v_mfma_f32_16x16x32_bf16 v[18:21], v[170:173], v[202:205], v[18:21]
	v_mfma_f32_16x16x32_bf16 v[6:9], v[146:149], v[210:213], v[6:9]
	v_mfma_f32_16x16x32_bf16 v[2:5], v[170:173], v[210:213], v[2:5]
	v_mfma_f32_16x16x32_bf16 v[54:57], v[150:153], v[182:185], v[54:57]
	v_mfma_f32_16x16x32_bf16 v[50:53], v[174:177], v[182:185], v[50:53]
	v_mfma_f32_16x16x32_bf16 v[38:41], v[150:153], v[198:201], v[38:41]
	v_mfma_f32_16x16x32_bf16 v[34:37], v[174:177], v[198:201], v[34:37]
	v_mfma_f32_16x16x32_bf16 v[22:25], v[150:153], v[206:209], v[22:25]
	v_mfma_f32_16x16x32_bf16 v[18:21], v[174:177], v[206:209], v[18:21]
	v_mfma_f32_16x16x32_bf16 v[6:9], v[150:153], v[214:217], v[6:9]
	v_mfma_f32_16x16x32_bf16 v[2:5], v[174:177], v[214:217], v[2:5]
	s_barrier
	s_add_i32 s49, 0, 0x18000
	s_add_i32 s50, 0, 0x1c000
	s_add_u32 s18, s18, 0x4000
	s_addc_u32 s19, s19, 0
	s_mov_b32 m0, s23
	v_lshl_add_u64 v[220:221], s[18:19], 0, v[154:155]
	global_load_lds_dwordx4 v[220:221], off
	v_lshl_add_u64 v[220:221], s[18:19], 0, v[158:159]
	s_mov_b32 m0, s24
	s_nop 0
	global_load_lds_dwordx4 v[220:221], off
	v_add_u32_e32 v142, s49, v188
	v_add_u32_e32 v174, s50, v188
	ds_read_b128 v[118:121], v142
	ds_read_b128 v[126:129], v142 offset:1024
	ds_read_b128 v[138:141], v142 offset:2048
	ds_read_b128 v[142:145], v142 offset:3072
	ds_read_b128 v[146:149], v174
	ds_read_b128 v[150:153], v174 offset:1024
	ds_read_b128 v[170:173], v174 offset:2048
	ds_read_b128 v[174:177], v174 offset:3072
	ds_read_b128 v[178:181], v192 offset:32768
	ds_read_b128 v[182:185], v192 offset:33792
	ds_read_b128 v[194:197], v192 offset:34816
	ds_read_b128 v[198:201], v192 offset:35840
	ds_read_b128 v[202:205], v192 offset:36864
	ds_read_b128 v[206:209], v192 offset:37888
	ds_read_b128 v[210:213], v192 offset:38912
	ds_read_b128 v[214:217], v192 offset:39936
	s_waitcnt vmcnt(8)
	s_waitcnt lgkmcnt(0)
	s_barrier
	s_waitcnt lgkmcnt(0)
	v_mfma_f32_16x16x32_bf16 v[134:137], v[118:121], v[178:181], v[134:137]
	v_mfma_f32_16x16x32_bf16 v[130:133], v[138:141], v[178:181], v[130:133]
	v_mfma_f32_16x16x32_bf16 v[110:113], v[118:121], v[194:197], v[110:113]
	v_mfma_f32_16x16x32_bf16 v[106:109], v[138:141], v[194:197], v[106:109]
	v_mfma_f32_16x16x32_bf16 v[94:97], v[118:121], v[202:205], v[94:97]
	v_mfma_f32_16x16x32_bf16 v[90:93], v[138:141], v[202:205], v[90:93]
	v_mfma_f32_16x16x32_bf16 v[78:81], v[118:121], v[210:213], v[78:81]
	v_mfma_f32_16x16x32_bf16 v[74:77], v[138:141], v[210:213], v[74:77]
	v_mfma_f32_16x16x32_bf16 v[134:137], v[126:129], v[182:185], v[134:137]
	v_mfma_f32_16x16x32_bf16 v[130:133], v[142:145], v[182:185], v[130:133]
	v_mfma_f32_16x16x32_bf16 v[110:113], v[126:129], v[198:201], v[110:113]
	v_mfma_f32_16x16x32_bf16 v[106:109], v[142:145], v[198:201], v[106:109]
	v_mfma_f32_16x16x32_bf16 v[94:97], v[126:129], v[206:209], v[94:97]
	v_mfma_f32_16x16x32_bf16 v[90:93], v[142:145], v[206:209], v[90:93]
	v_mfma_f32_16x16x32_bf16 v[78:81], v[126:129], v[214:217], v[78:81]
	v_mfma_f32_16x16x32_bf16 v[74:77], v[142:145], v[214:217], v[74:77]
	v_mfma_f32_16x16x32_bf16 v[122:125], v[146:149], v[178:181], v[122:125]
	v_mfma_f32_16x16x32_bf16 v[114:117], v[170:173], v[178:181], v[114:117]
	v_mfma_f32_16x16x32_bf16 v[102:105], v[146:149], v[194:197], v[102:105]
	v_mfma_f32_16x16x32_bf16 v[98:101], v[170:173], v[194:197], v[98:101]
	v_mfma_f32_16x16x32_bf16 v[86:89], v[146:149], v[202:205], v[86:89]
	v_mfma_f32_16x16x32_bf16 v[82:85], v[170:173], v[202:205], v[82:85]
	v_mfma_f32_16x16x32_bf16 v[70:73], v[146:149], v[210:213], v[70:73]
	v_mfma_f32_16x16x32_bf16 v[66:69], v[170:173], v[210:213], v[66:69]
	v_mfma_f32_16x16x32_bf16 v[122:125], v[150:153], v[182:185], v[122:125]
	v_mfma_f32_16x16x32_bf16 v[114:117], v[174:177], v[182:185], v[114:117]
	v_mfma_f32_16x16x32_bf16 v[102:105], v[150:153], v[198:201], v[102:105]
	v_mfma_f32_16x16x32_bf16 v[98:101], v[174:177], v[198:201], v[98:101]
	v_mfma_f32_16x16x32_bf16 v[86:89], v[150:153], v[206:209], v[86:89]
	v_mfma_f32_16x16x32_bf16 v[82:85], v[174:177], v[206:209], v[82:85]
	v_mfma_f32_16x16x32_bf16 v[70:73], v[150:153], v[214:217], v[70:73]
	v_mfma_f32_16x16x32_bf16 v[66:69], v[174:177], v[214:217], v[66:69]
	s_barrier
; #define PG8_STAGE(bufoff, gbase, voff) do { _Pragma("unroll") for (int _i = 0; _i < 2; ++_i) \
;         __builtin_amdgcn_global_load_lds((const unsigned*)((const char*)(gbase) + (voff)[_i]), (LAS unsigned*)(lds + (bufoff) + ldsw + _i * 8192), 16, 0, 0); } while (0)
; #define PG8_LDA(dst, b, h) do { _Pragma("unroll") for (int m = 0; m < 4; ++m) _Pragma("unroll") for (int k = 0; k < 2; ++k) dst[m][k] = *(const LAS bf16x8*)(lds + PG8_SA(b, h) + aoff + m * 2048 + k * 1024); } while (0)
; #define PG8_MMA(ai, bj, At, Bt) do { __builtin_amdgcn_s_setprio(1); _Pragma("unroll") for (int m = 0; m < 4; ++m) _Pragma("unroll") for (int n = 0; n < 2; ++n) _Pragma("unroll") for (int k = 0; k < 2; ++k) \
;         acc[ai][bj][m][n] = __builtin_amdgcn_mfma_f32_16x16x32_bf16(Bt[n][k], At[m][k], acc[ai][bj][m][n], 0, 0, 0); __builtin_amdgcn_s_setprio(0); } while (0)
; #define PG8_WAIT_V(n) asm volatile("s_waitcnt vmcnt(" #n ")" ::: "memory")
; #define PG8_WAIT_L(n) asm volatile("s_waitcnt lgkmcnt(" #n ")" ::: "memory")
; #define PG8_BAR __builtin_amdgcn_s_barrier()
; #define PG8_SCHED __builtin_amdgcn_sched_barrier(0)
; template <class Epi, bool ALIGN_EPI>
; __device__ __forceinline__ void gemm_phase(LAS unsigned char* lds, const Gemm g, const StaticOrder& S, const Epi& E) {
;     ...
;             PG8_LDA(At, 1, 1); PG8_STAGE(PG8_SB(1, 0), b3, voffB); PG8_STAGE(PG8_SB(1, 1), b3 + hsB, voffB); PG8_STAGE(PG8_SA(1, 0), a3, voffA);
;             PG8_WAIT_V(8); PG8_WAIT_L(0); PG8_BAR; PG8_MMA(1, 0, At, B0); PG8_MMA(1, 1, At, B1); PG8_BAR; PG8_SCHED;
;         }
	s_add_i32 s18, s49, s20
	v_lshl_add_u64 v[186:187], v[186:187], 0, s[38:39]
	s_mov_b32 m0, s18
	s_nop 0
	global_load_lds_dwordx4 v[186:187], off
	s_add_i32 m0, s18, 0x2000
	s_add_u32 s16, s16, 0xb0080
	v_lshl_add_u64 v[186:187], v[218:219], 0, s[38:39]
	s_addc_u32 s17, s17, 0
	s_add_i32 s18, s50, s20
	global_load_lds_dwordx4 v[186:187], off
	v_lshl_add_u64 v[186:187], s[16:17], 0, v[156:157]
	s_mov_b32 m0, s18
	s_nop 0
	global_load_lds_dwordx4 v[186:187], off
	v_lshl_add_u64 v[186:187], s[16:17], 0, v[160:161]
	s_add_i32 m0, s18, 0x2000
	s_nop 0
	global_load_lds_dwordx4 v[186:187], off
	v_lshl_add_u64 v[186:187], s[14:15], 0, v[154:155]
	s_mov_b32 m0, s26
	s_nop 0
	global_load_lds_dwordx4 v[186:187], off
	v_lshl_add_u64 v[186:187], s[14:15], 0, v[158:159]
	s_mov_b32 m0, s27
	s_nop 0
	global_load_lds_dwordx4 v[186:187], off
	ds_read_b128 v[178:181], v192 offset:49152
	ds_read_b128 v[182:185], v192 offset:50176
	ds_read_b128 v[194:197], v192 offset:51200
	ds_read_b128 v[198:201], v192 offset:52224
	ds_read_b128 v[202:205], v192 offset:53248
	ds_read_b128 v[206:209], v192 offset:54272
	ds_read_b128 v[210:213], v192 offset:55296
	ds_read_b128 v[214:217], v192 offset:56320
	s_waitcnt vmcnt(8)
	s_waitcnt lgkmcnt(0)
	s_barrier
	s_waitcnt lgkmcnt(0)
	v_mfma_f32_16x16x32_bf16 v[62:65], v[118:121], v[178:181], v[62:65]
	v_mfma_f32_16x16x32_bf16 v[58:61], v[138:141], v[178:181], v[58:61]
	v_mfma_f32_16x16x32_bf16 v[46:49], v[118:121], v[194:197], v[46:49]
	v_mfma_f32_16x16x32_bf16 v[42:45], v[138:141], v[194:197], v[42:45]
	v_mfma_f32_16x16x32_bf16 v[30:33], v[118:121], v[202:205], v[30:33]
	v_mfma_f32_16x16x32_bf16 v[26:29], v[138:141], v[202:205], v[26:29]
	v_mfma_f32_16x16x32_bf16 v[14:17], v[118:121], v[210:213], v[14:17]
	v_mfma_f32_16x16x32_bf16 v[10:13], v[138:141], v[210:213], v[10:13]
	v_mfma_f32_16x16x32_bf16 v[62:65], v[126:129], v[182:185], v[62:65]
	v_mfma_f32_16x16x32_bf16 v[58:61], v[142:145], v[182:185], v[58:61]
	v_mfma_f32_16x16x32_bf16 v[46:49], v[126:129], v[198:201], v[46:49]
	v_mfma_f32_16x16x32_bf16 v[42:45], v[142:145], v[198:201], v[42:45]
	v_mfma_f32_16x16x32_bf16 v[30:33], v[126:129], v[206:209], v[30:33]
	v_mfma_f32_16x16x32_bf16 v[26:29], v[142:145], v[206:209], v[26:29]
	v_mfma_f32_16x16x32_bf16 v[14:17], v[126:129], v[214:217], v[14:17]
	v_mfma_f32_16x16x32_bf16 v[10:13], v[142:145], v[214:217], v[10:13]
	v_mfma_f32_16x16x32_bf16 v[54:57], v[146:149], v[178:181], v[54:57]
	v_mfma_f32_16x16x32_bf16 v[50:53], v[170:173], v[178:181], v[50:53]
	v_mfma_f32_16x16x32_bf16 v[38:41], v[146:149], v[194:197], v[38:41]
	v_mfma_f32_16x16x32_bf16 v[34:37], v[170:173], v[194:197], v[34:37]
	v_mfma_f32_16x16x32_bf16 v[22:25], v[146:149], v[202:205], v[22:25]
	v_mfma_f32_16x16x32_bf16 v[18:21], v[170:173], v[202:205], v[18:21]
	v_mfma_f32_16x16x32_bf16 v[6:9], v[146:149], v[210:213], v[6:9]
	v_mfma_f32_16x16x32_bf16 v[2:5], v[170:173], v[210:213], v[2:5]
	v_mfma_f32_16x16x32_bf16 v[54:57], v[150:153], v[182:185], v[54:57]
	v_mfma_f32_16x16x32_bf16 v[50:53], v[174:177], v[182:185], v[50:53]
	v_mfma_f32_16x16x32_bf16 v[38:41], v[150:153], v[198:201], v[38:41]
	v_mfma_f32_16x16x32_bf16 v[34:37], v[174:177], v[198:201], v[34:37]
	v_mfma_f32_16x16x32_bf16 v[22:25], v[150:153], v[206:209], v[22:25]
	v_mfma_f32_16x16x32_bf16 v[18:21], v[174:177], v[206:209], v[18:21]
	v_mfma_f32_16x16x32_bf16 v[6:9], v[150:153], v[214:217], v[6:9]
	v_mfma_f32_16x16x32_bf16 v[2:5], v[174:177], v[214:217], v[2:5]
	s_barrier
	s_add_i32 s48, s48, 2
	s_add_u32 s12, s12, 0x10000
	s_addc_u32 s13, s13, 0
	s_add_u32 s46, s46, 0x100
	s_addc_u32 s47, s47, 0
	s_cmp_gt_u32 s48, 41
	s_cbranch_scc0 .LBB0_330
	s_and_b64 vcc, exec, s[40:41]
	s_cbranch_vccz .LBB0_333
	s_barrier

; #define PG8_STAGE(bufoff, gbase, voff) do { _Pragma("unroll") for (int _i = 0; _i < 2; ++_i) \
;         __builtin_amdgcn_global_load_lds((const unsigned*)((const char*)(gbase) + (voff)[_i]), (LAS unsigned*)(lds + (bufoff) + ldsw + _i * 8192), 16, 0, 0); } while (0)
; #define PG8_LDA(dst, b, h) do { _Pragma("unroll") for (int m = 0; m < 4; ++m) _Pragma("unroll") for (int k = 0; k < 2; ++k) dst[m][k] = *(const LAS bf16x8*)(lds + PG8_SA(b, h) + aoff + m * 2048 + k * 1024); } while (0)
; #define PG8_LDB(dst, b, h) do { _Pragma("unroll") for (int n = 0; n < 2; ++n) _Pragma("unroll") for (int k = 0; k < 2; ++k) dst[n][k] = *(const LAS bf16x8*)(lds + PG8_SB(b, h) + boff + n * 2048 + k * 1024); } while (0)
; #define PG8_MMA(ai, bj, At, Bt) do { __builtin_amdgcn_s_setprio(1); _Pragma("unroll") for (int m = 0; m < 4; ++m) _Pragma("unroll") for (int n = 0; n < 2; ++n) _Pragma("unroll") for (int k = 0; k < 2; ++k) \
;         acc[ai][bj][m][n] = __builtin_amdgcn_mfma_f32_16x16x32_bf16(Bt[n][k], At[m][k], acc[ai][bj][m][n], 0, 0, 0); __builtin_amdgcn_s_setprio(0); } while (0)
; #define PG8_WAIT_V(n) asm volatile("s_waitcnt vmcnt(" #n ")" ::: "memory")
; #define PG8_WAIT_L(n) asm volatile("s_waitcnt lgkmcnt(" #n ")" ::: "memory")
; #define PG8_BAR __builtin_amdgcn_s_barrier()
; #define PG8_SCHED __builtin_amdgcn_sched_barrier(0)
; template <class Epi, bool ALIGN_EPI>
; __device__ __forceinline__ void gemm_phase(LAS unsigned char* lds, const Gemm g, const StaticOrder& S, const Epi& E) {
;     ...
;         for (int t = 0; t < nt; t += 2) {
;             const bool last = (t == nt - 2);
;             const char* a1 = cA + (size_t)(t + 1) * kstepA;
;             const char* a2 = last ? nA : cA + (size_t)(t + 2) * kstepA; const char* b2 = last ? nB : cB + (size_t)(t + 2) * kstep;
;             const char* a3 = a2 + kstepA; const char* b3 = b2 + kstep;
;             PG8_LDB(B0, 0, 0); PG8_LDB(B1, 0, 1); PG8_SCHED; PG8_LDA(At, 0, 0); PG8_STAGE(PG8_SA(1, 1), a1 + hsA, voffA);
;             PG8_WAIT_V(8); PG8_WAIT_L(0); PG8_BAR; PG8_MMA(0, 0, At, B0); PG8_MMA(0, 1, At, B1); PG8_BAR; PG8_SCHED;
;             PG8_LDA(At, 0, 1); PG8_STAGE(PG8_SB(0, 0), b2, voffB); PG8_STAGE(PG8_SB(0, 1), b2 + hsB, voffB); PG8_STAGE(PG8_SA(0, 0), a2, voffA);
.LBB0_419:
	s_waitcnt vmcnt(0)
	s_add_u32 s12, s8, 0xfffc0080
	s_addc_u32 s13, s9, -1
	s_cmp_eq_u32 s43, 12
	s_cselect_b32 s15, s7, s13
	s_cselect_b32 s14, s33, s12
	s_cselect_b32 s13, s39, s42
	s_cselect_b32 s12, s40, s41
	v_lshl_add_u64 v[180:181], s[8:9], 0, v[152:153]
	s_add_i32 m0, s17, 0xc000
	s_nop 0
	global_load_lds_dwordx4 v[180:181], off
	v_lshl_add_u64 v[180:181], s[8:9], 0, v[154:155]
	s_add_i32 m0, s17, 0xe000
	s_nop 0
	global_load_lds_dwordx4 v[180:181], off
	ds_read_b128 v[130:133], v194
	ds_read_b128 v[160:163], v194 offset:1024
	ds_read_b128 v[164:167], v194 offset:2048
	ds_read_b128 v[168:171], v194 offset:3072
	ds_read_b128 v[172:175], v195
	ds_read_b128 v[176:179], v195 offset:1024
	ds_read_b128 v[200:203], v195 offset:2048
	ds_read_b128 v[204:207], v195 offset:3072
	ds_read_b128 v[208:211], v196
	ds_read_b128 v[212:215], v196 offset:1024
	ds_read_b128 v[216:219], v196 offset:2048
	ds_read_b128 v[220:223], v196 offset:3072
	ds_read_b128 v[224:227], v196 offset:4096
	ds_read_b128 v[228:231], v196 offset:5120
	ds_read_b128 v[232:235], v196 offset:6144
	ds_read_b128 v[236:239], v196 offset:7168
	s_waitcnt vmcnt(8)
	s_waitcnt lgkmcnt(0)
	s_barrier
	s_waitcnt lgkmcnt(0)
	v_mfma_f32_16x16x32_bf16 v[118:121], v[130:133], v[208:211], v[118:121]
	v_mfma_f32_16x16x32_bf16 v[126:129], v[164:167], v[208:211], v[126:129]
	v_mfma_f32_16x16x32_bf16 v[106:109], v[130:133], v[216:219], v[106:109]
	v_mfma_f32_16x16x32_bf16 v[110:113], v[164:167], v[216:219], v[110:113]
	v_mfma_f32_16x16x32_bf16 v[90:93], v[130:133], v[224:227], v[90:93]
	v_mfma_f32_16x16x32_bf16 v[94:97], v[164:167], v[224:227], v[94:97]
	v_mfma_f32_16x16x32_bf16 v[74:77], v[130:133], v[232:235], v[74:77]
	v_mfma_f32_16x16x32_bf16 v[78:81], v[164:167], v[232:235], v[78:81]
	v_mfma_f32_16x16x32_bf16 v[118:121], v[160:163], v[212:215], v[118:121]
	v_mfma_f32_16x16x32_bf16 v[126:129], v[168:171], v[212:215], v[126:129]
	v_mfma_f32_16x16x32_bf16 v[106:109], v[160:163], v[220:223], v[106:109]
	v_mfma_f32_16x16x32_bf16 v[110:113], v[168:171], v[220:223], v[110:113]
	v_mfma_f32_16x16x32_bf16 v[90:93], v[160:163], v[228:231], v[90:93]
	v_mfma_f32_16x16x32_bf16 v[94:97], v[168:171], v[228:231], v[94:97]
	v_mfma_f32_16x16x32_bf16 v[74:77], v[160:163], v[236:239], v[74:77]
	v_mfma_f32_16x16x32_bf16 v[78:81], v[168:171], v[236:239], v[78:81]
	v_mfma_f32_16x16x32_bf16 v[114:117], v[172:175], v[208:211], v[114:117]
	v_mfma_f32_16x16x32_bf16 v[122:125], v[200:203], v[208:211], v[122:125]
	v_mfma_f32_16x16x32_bf16 v[98:101], v[172:175], v[216:219], v[98:101]
	v_mfma_f32_16x16x32_bf16 v[102:105], v[200:203], v[216:219], v[102:105]
	v_mfma_f32_16x16x32_bf16 v[82:85], v[172:175], v[224:227], v[82:85]
	v_mfma_f32_16x16x32_bf16 v[86:89], v[200:203], v[224:227], v[86:89]
	v_mfma_f32_16x16x32_bf16 v[66:69], v[172:175], v[232:235], v[66:69]
	v_mfma_f32_16x16x32_bf16 v[70:73], v[200:203], v[232:235], v[70:73]
	v_mfma_f32_16x16x32_bf16 v[114:117], v[176:179], v[212:215], v[114:117]
	v_mfma_f32_16x16x32_bf16 v[122:125], v[204:207], v[212:215], v[122:125]
	v_mfma_f32_16x16x32_bf16 v[98:101], v[176:179], v[220:223], v[98:101]
	v_mfma_f32_16x16x32_bf16 v[102:105], v[204:207], v[220:223], v[102:105]
	v_mfma_f32_16x16x32_bf16 v[82:85], v[176:179], v[228:231], v[82:85]
	v_mfma_f32_16x16x32_bf16 v[86:89], v[204:207], v[228:231], v[86:89]
	v_mfma_f32_16x16x32_bf16 v[66:69], v[176:179], v[236:239], v[66:69]
	v_mfma_f32_16x16x32_bf16 v[70:73], v[204:207], v[236:239], v[70:73]
	s_barrier
	s_add_i32 s44, s31, s16
	v_lshl_add_u64 v[180:181], s[12:13], 0, v[136:137]
	s_mov_b32 m0, s44
	s_nop 0
	global_load_lds_dwordx4 v[180:181], off
	s_add_i32 m0, s44, 0x2000
	s_add_u32 s44, s12, 0x40000
	v_lshl_add_u64 v[240:241], s[12:13], 0, v[140:141]
	s_addc_u32 s45, s13, 0
	s_add_i32 s46, s34, s16
	global_load_lds_dwordx4 v[240:241], off
	v_lshl_add_u64 v[242:243], s[44:45], 0, v[136:137]
	s_mov_b32 m0, s46
	v_lshl_add_u64 v[244:245], s[14:15], 0, v[138:139]
	global_load_lds_dwordx4 v[242:243], off
	v_lshl_add_u64 v[242:243], s[44:45], 0, v[140:141]
	s_add_i32 m0, s46, 0x2000
	s_nop 0
	global_load_lds_dwordx4 v[242:243], off
	v_lshl_add_u64 v[242:243], s[14:15], 0, v[134:135]
	s_mov_b32 m0, s17
	s_nop 0
	global_load_lds_dwordx4 v[242:243], off
	s_mov_b32 m0, s18
	s_nop 0
	global_load_lds_dwordx4 v[244:245], off
	ds_read_b128 v[208:211], v196 offset:16384
	ds_read_b128 v[212:215], v196 offset:17408
	ds_read_b128 v[216:219], v196 offset:18432
	ds_read_b128 v[220:223], v196 offset:19456
	ds_read_b128 v[224:227], v196 offset:20480
	ds_read_b128 v[228:231], v196 offset:21504
	ds_read_b128 v[232:235], v196 offset:22528
	ds_read_b128 v[236:239], v196 offset:23552
	s_waitcnt vmcnt(8)
	s_waitcnt lgkmcnt(0)
	s_barrier
; #define PG8_STAGE(bufoff, gbase, voff) do { _Pragma("unroll") for (int _i = 0; _i < 2; ++_i) \
;         __builtin_amdgcn_global_load_lds((const unsigned*)((const char*)(gbase) + (voff)[_i]), (LAS unsigned*)(lds + (bufoff) + ldsw + _i * 8192), 16, 0, 0); } while (0)
; #define PG8_LDA(dst, b, h) do { _Pragma("unroll") for (int m = 0; m < 4; ++m) _Pragma("unroll") for (int k = 0; k < 2; ++k) dst[m][k] = *(const LAS bf16x8*)(lds + PG8_SA(b, h) + aoff + m * 2048 + k * 1024); } while (0)
; #define PG8_LDB(dst, b, h) do { _Pragma("unroll") for (int n = 0; n < 2; ++n) _Pragma("unroll") for (int k = 0; k < 2; ++k) dst[n][k] = *(const LAS bf16x8*)(lds + PG8_SB(b, h) + boff + n * 2048 + k * 1024); } while (0)
; #define PG8_MMA(ai, bj, At, Bt) do { __builtin_amdgcn_s_setprio(1); _Pragma("unroll") for (int m = 0; m < 4; ++m) _Pragma("unroll") for (int n = 0; n < 2; ++n) _Pragma("unroll") for (int k = 0; k < 2; ++k) \
;         acc[ai][bj][m][n] = __builtin_amdgcn_mfma_f32_16x16x32_bf16(Bt[n][k], At[m][k], acc[ai][bj][m][n], 0, 0, 0); __builtin_amdgcn_s_setprio(0); } while (0)
; #define PG8_WAIT_V(n) asm volatile("s_waitcnt vmcnt(" #n ")" ::: "memory")
; #define PG8_WAIT_L(n) asm volatile("s_waitcnt lgkmcnt(" #n ")" ::: "memory")
; #define PG8_BAR __builtin_amdgcn_s_barrier()
; #define PG8_SCHED __builtin_amdgcn_sched_barrier(0)
; template <class Epi, bool ALIGN_EPI>
; __device__ __forceinline__ void gemm_phase(LAS unsigned char* lds, const Gemm g, const StaticOrder& S, const Epi& E) {
;     ...
;             PG8_WAIT_V(8); PG8_WAIT_L(0); PG8_BAR; PG8_MMA(1, 0, At, B0); PG8_MMA(1, 1, At, B1); PG8_BAR; PG8_SCHED;
;             PG8_LDB(B0, 1, 0); PG8_LDB(B1, 1, 1); PG8_SCHED; PG8_LDA(At, 1, 0); PG8_STAGE(PG8_SA(0, 1), a2 + hsA, voffA);
;             PG8_WAIT_V(8); PG8_WAIT_L(0); PG8_BAR; PG8_MMA(0, 0, At, B0); PG8_MMA(0, 1, At, B1); PG8_BAR; PG8_SCHED;
	s_waitcnt lgkmcnt(0)
	v_mfma_f32_16x16x32_bf16 v[58:61], v[130:133], v[208:211], v[58:61]
	v_mfma_f32_16x16x32_bf16 v[62:65], v[164:167], v[208:211], v[62:65]
	v_mfma_f32_16x16x32_bf16 v[42:45], v[130:133], v[216:219], v[42:45]
	v_mfma_f32_16x16x32_bf16 v[46:49], v[164:167], v[216:219], v[46:49]
	v_mfma_f32_16x16x32_bf16 v[26:29], v[130:133], v[224:227], v[26:29]
	v_mfma_f32_16x16x32_bf16 v[30:33], v[164:167], v[224:227], v[30:33]
	v_mfma_f32_16x16x32_bf16 v[10:13], v[130:133], v[232:235], v[10:13]
	v_mfma_f32_16x16x32_bf16 v[14:17], v[164:167], v[232:235], v[14:17]
	v_mfma_f32_16x16x32_bf16 v[58:61], v[160:163], v[212:215], v[58:61]
	v_mfma_f32_16x16x32_bf16 v[62:65], v[168:171], v[212:215], v[62:65]
	v_mfma_f32_16x16x32_bf16 v[42:45], v[160:163], v[220:223], v[42:45]
	v_mfma_f32_16x16x32_bf16 v[46:49], v[168:171], v[220:223], v[46:49]
	v_mfma_f32_16x16x32_bf16 v[26:29], v[160:163], v[228:231], v[26:29]
	v_mfma_f32_16x16x32_bf16 v[30:33], v[168:171], v[228:231], v[30:33]
	v_mfma_f32_16x16x32_bf16 v[10:13], v[160:163], v[236:239], v[10:13]
	v_mfma_f32_16x16x32_bf16 v[14:17], v[168:171], v[236:239], v[14:17]
	v_mfma_f32_16x16x32_bf16 v[50:53], v[172:175], v[208:211], v[50:53]
	v_mfma_f32_16x16x32_bf16 v[54:57], v[200:203], v[208:211], v[54:57]
	v_mfma_f32_16x16x32_bf16 v[34:37], v[172:175], v[216:219], v[34:37]
	v_mfma_f32_16x16x32_bf16 v[38:41], v[200:203], v[216:219], v[38:41]
	v_mfma_f32_16x16x32_bf16 v[18:21], v[172:175], v[224:227], v[18:21]
	v_mfma_f32_16x16x32_bf16 v[22:25], v[200:203], v[224:227], v[22:25]
	v_mfma_f32_16x16x32_bf16 v[2:5], v[172:175], v[232:235], v[2:5]
	v_mfma_f32_16x16x32_bf16 v[6:9], v[200:203], v[232:235], v[6:9]
	v_mfma_f32_16x16x32_bf16 v[50:53], v[176:179], v[212:215], v[50:53]
	v_mfma_f32_16x16x32_bf16 v[54:57], v[204:207], v[212:215], v[54:57]
	v_mfma_f32_16x16x32_bf16 v[34:37], v[176:179], v[220:223], v[34:37]
	v_mfma_f32_16x16x32_bf16 v[38:41], v[204:207], v[220:223], v[38:41]
	v_mfma_f32_16x16x32_bf16 v[18:21], v[176:179], v[228:231], v[18:21]
	v_mfma_f32_16x16x32_bf16 v[22:25], v[204:207], v[228:231], v[22:25]
	v_mfma_f32_16x16x32_bf16 v[2:5], v[176:179], v[236:239], v[2:5]
	v_mfma_f32_16x16x32_bf16 v[6:9], v[204:207], v[236:239], v[6:9]
	s_barrier
	s_add_i32 s44, 0, 0x18000
	s_add_i32 s45, 0, 0x1c000
	s_add_u32 s14, s14, 0x40000
	s_addc_u32 s15, s15, 0
	s_mov_b32 m0, s19
	v_lshl_add_u64 v[246:247], s[14:15], 0, v[134:135]
	global_load_lds_dwordx4 v[246:247], off
	v_lshl_add_u64 v[246:247], s[14:15], 0, v[138:139]
	s_mov_b32 m0, s20
	s_nop 0
	global_load_lds_dwordx4 v[246:247], off
	v_add_u32_e32 v142, s44, v145
	ds_read_b128 v[130:133], v142
	ds_read_b128 v[160:163], v142 offset:1024
	ds_read_b128 v[164:167], v142 offset:2048
	ds_read_b128 v[168:171], v142 offset:3072
	v_add_u32_e32 v142, s45, v145
	ds_read_b128 v[172:175], v142
	ds_read_b128 v[176:179], v142 offset:1024
	ds_read_b128 v[200:203], v142 offset:2048
	ds_read_b128 v[204:207], v142 offset:3072
	ds_read_b128 v[208:211], v196 offset:32768
	ds_read_b128 v[212:215], v196 offset:33792
	ds_read_b128 v[216:219], v196 offset:34816
	ds_read_b128 v[220:223], v196 offset:35840
	ds_read_b128 v[224:227], v196 offset:36864
	ds_read_b128 v[228:231], v196 offset:37888
	ds_read_b128 v[232:235], v196 offset:38912
	ds_read_b128 v[236:239], v196 offset:39936
	s_waitcnt vmcnt(8)
	s_waitcnt lgkmcnt(0)
	s_barrier
	s_waitcnt lgkmcnt(0)
	v_mfma_f32_16x16x32_bf16 v[118:121], v[130:133], v[208:211], v[118:121]
	v_mfma_f32_16x16x32_bf16 v[126:129], v[164:167], v[208:211], v[126:129]
	v_mfma_f32_16x16x32_bf16 v[106:109], v[130:133], v[216:219], v[106:109]
	v_mfma_f32_16x16x32_bf16 v[110:113], v[164:167], v[216:219], v[110:113]
	v_mfma_f32_16x16x32_bf16 v[90:93], v[130:133], v[224:227], v[90:93]
	v_mfma_f32_16x16x32_bf16 v[94:97], v[164:167], v[224:227], v[94:97]
	v_mfma_f32_16x16x32_bf16 v[74:77], v[130:133], v[232:235], v[74:77]
	v_mfma_f32_16x16x32_bf16 v[78:81], v[164:167], v[232:235], v[78:81]
	v_mfma_f32_16x16x32_bf16 v[118:121], v[160:163], v[212:215], v[118:121]
	v_mfma_f32_16x16x32_bf16 v[126:129], v[168:171], v[212:215], v[126:129]
	v_mfma_f32_16x16x32_bf16 v[106:109], v[160:163], v[220:223], v[106:109]
	v_mfma_f32_16x16x32_bf16 v[110:113], v[168:171], v[220:223], v[110:113]
	v_mfma_f32_16x16x32_bf16 v[90:93], v[160:163], v[228:231], v[90:93]
	v_mfma_f32_16x16x32_bf16 v[94:97], v[168:171], v[228:231], v[94:97]
	v_mfma_f32_16x16x32_bf16 v[74:77], v[160:163], v[236:239], v[74:77]
	v_mfma_f32_16x16x32_bf16 v[78:81], v[168:171], v[236:239], v[78:81]
	v_mfma_f32_16x16x32_bf16 v[114:117], v[172:175], v[208:211], v[114:117]
	v_mfma_f32_16x16x32_bf16 v[122:125], v[200:203], v[208:211], v[122:125]
	v_mfma_f32_16x16x32_bf16 v[98:101], v[172:175], v[216:219], v[98:101]
	v_mfma_f32_16x16x32_bf16 v[102:105], v[200:203], v[216:219], v[102:105]
	v_mfma_f32_16x16x32_bf16 v[82:85], v[172:175], v[224:227], v[82:85]
	v_mfma_f32_16x16x32_bf16 v[86:89], v[200:203], v[224:227], v[86:89]
	v_mfma_f32_16x16x32_bf16 v[66:69], v[172:175], v[232:235], v[66:69]
	v_mfma_f32_16x16x32_bf16 v[70:73], v[200:203], v[232:235], v[70:73]
	v_mfma_f32_16x16x32_bf16 v[114:117], v[176:179], v[212:215], v[114:117]
	v_mfma_f32_16x16x32_bf16 v[122:125], v[204:207], v[212:215], v[122:125]
	v_mfma_f32_16x16x32_bf16 v[98:101], v[176:179], v[220:223], v[98:101]
	v_mfma_f32_16x16x32_bf16 v[102:105], v[204:207], v[220:223], v[102:105]
	v_mfma_f32_16x16x32_bf16 v[82:85], v[176:179], v[228:231], v[82:85]
	v_mfma_f32_16x16x32_bf16 v[86:89], v[204:207], v[228:231], v[86:89]
	v_mfma_f32_16x16x32_bf16 v[66:69], v[176:179], v[236:239], v[66:69]
	v_mfma_f32_16x16x32_bf16 v[70:73], v[204:207], v[236:239], v[70:73]
	s_barrier
; #define PG8_STAGE(bufoff, gbase, voff) do { _Pragma("unroll") for (int _i = 0; _i < 2; ++_i) \
;         __builtin_amdgcn_global_load_lds((const unsigned*)((const char*)(gbase) + (voff)[_i]), (LAS unsigned*)(lds + (bufoff) + ldsw + _i * 8192), 16, 0, 0); } while (0)
; #define PG8_LDA(dst, b, h) do { _Pragma("unroll") for (int m = 0; m < 4; ++m) _Pragma("unroll") for (int k = 0; k < 2; ++k) dst[m][k] = *(const LAS bf16x8*)(lds + PG8_SA(b, h) + aoff + m * 2048 + k * 1024); } while (0)
; #define PG8_MMA(ai, bj, At, Bt) do { __builtin_amdgcn_s_setprio(1); _Pragma("unroll") for (int m = 0; m < 4; ++m) _Pragma("unroll") for (int n = 0; n < 2; ++n) _Pragma("unroll") for (int k = 0; k < 2; ++k) \
;         acc[ai][bj][m][n] = __builtin_amdgcn_mfma_f32_16x16x32_bf16(Bt[n][k], At[m][k], acc[ai][bj][m][n], 0, 0, 0); __builtin_amdgcn_s_setprio(0); } while (0)
; #define PG8_WAIT_V(n) asm volatile("s_waitcnt vmcnt(" #n ")" ::: "memory")
; #define PG8_WAIT_L(n) asm volatile("s_waitcnt lgkmcnt(" #n ")" ::: "memory")
; #define PG8_BAR __builtin_amdgcn_s_barrier()
; #define PG8_SCHED __builtin_amdgcn_sched_barrier(0)
; template <class Epi, bool ALIGN_EPI>
; __device__ __forceinline__ void gemm_phase(LAS unsigned char* lds, const Gemm g, const StaticOrder& S, const Epi& E) {
;     ...
;             PG8_LDA(At, 1, 1); PG8_STAGE(PG8_SB(1, 0), b3, voffB); PG8_STAGE(PG8_SB(1, 1), b3 + hsB, voffB); PG8_STAGE(PG8_SA(1, 0), a3, voffA);
;             PG8_WAIT_V(8); PG8_WAIT_L(0); PG8_BAR; PG8_MMA(1, 0, At, B0); PG8_MMA(1, 1, At, B1); PG8_BAR; PG8_SCHED;
;         }
	s_add_i32 s14, s44, s16
	v_lshl_add_u64 v[180:181], v[180:181], 0, s[96:97]
	s_mov_b32 m0, s14
	s_nop 0
	global_load_lds_dwordx4 v[180:181], off
	s_add_i32 m0, s14, 0x2000
	s_add_u32 s12, s12, 0x40080
	v_lshl_add_u64 v[180:181], v[240:241], 0, s[96:97]
	s_addc_u32 s13, s13, 0
	s_add_i32 s14, s45, s16
	global_load_lds_dwordx4 v[180:181], off
	v_lshl_add_u64 v[180:181], s[12:13], 0, v[136:137]
	s_mov_b32 m0, s14
	s_nop 0
	global_load_lds_dwordx4 v[180:181], off
	v_lshl_add_u64 v[180:181], s[12:13], 0, v[140:141]
	s_add_i32 m0, s14, 0x2000
	s_nop 0
	global_load_lds_dwordx4 v[180:181], off
	v_lshl_add_u64 v[180:181], v[242:243], 0, s[96:97]
	s_mov_b32 m0, s23
	s_nop 0
	global_load_lds_dwordx4 v[180:181], off
	v_lshl_add_u64 v[180:181], v[244:245], 0, s[96:97]
	s_mov_b32 m0, s24
	s_nop 0
	global_load_lds_dwordx4 v[180:181], off
	ds_read_b128 v[208:211], v196 offset:49152
	ds_read_b128 v[212:215], v196 offset:50176
	ds_read_b128 v[216:219], v196 offset:51200
	ds_read_b128 v[220:223], v196 offset:52224
	ds_read_b128 v[224:227], v196 offset:53248
	ds_read_b128 v[228:231], v196 offset:54272
	ds_read_b128 v[232:235], v196 offset:55296
	ds_read_b128 v[236:239], v196 offset:56320
	s_waitcnt vmcnt(8)
	s_waitcnt lgkmcnt(0)
	s_barrier
	s_waitcnt lgkmcnt(0)
	v_mfma_f32_16x16x32_bf16 v[58:61], v[130:133], v[208:211], v[58:61]
	v_mfma_f32_16x16x32_bf16 v[62:65], v[164:167], v[208:211], v[62:65]
	v_mfma_f32_16x16x32_bf16 v[42:45], v[130:133], v[216:219], v[42:45]
	v_mfma_f32_16x16x32_bf16 v[46:49], v[164:167], v[216:219], v[46:49]
	v_mfma_f32_16x16x32_bf16 v[26:29], v[130:133], v[224:227], v[26:29]
	v_mfma_f32_16x16x32_bf16 v[30:33], v[164:167], v[224:227], v[30:33]
	v_mfma_f32_16x16x32_bf16 v[10:13], v[130:133], v[232:235], v[10:13]
	v_mfma_f32_16x16x32_bf16 v[14:17], v[164:167], v[232:235], v[14:17]
	v_mfma_f32_16x16x32_bf16 v[58:61], v[160:163], v[212:215], v[58:61]
	v_mfma_f32_16x16x32_bf16 v[62:65], v[168:171], v[212:215], v[62:65]
	v_mfma_f32_16x16x32_bf16 v[42:45], v[160:163], v[220:223], v[42:45]
	v_mfma_f32_16x16x32_bf16 v[46:49], v[168:171], v[220:223], v[46:49]
	v_mfma_f32_16x16x32_bf16 v[26:29], v[160:163], v[228:231], v[26:29]
	v_mfma_f32_16x16x32_bf16 v[30:33], v[168:171], v[228:231], v[30:33]
	v_mfma_f32_16x16x32_bf16 v[10:13], v[160:163], v[236:239], v[10:13]
	v_mfma_f32_16x16x32_bf16 v[14:17], v[168:171], v[236:239], v[14:17]
	v_mfma_f32_16x16x32_bf16 v[50:53], v[172:175], v[208:211], v[50:53]
	v_mfma_f32_16x16x32_bf16 v[54:57], v[200:203], v[208:211], v[54:57]
	v_mfma_f32_16x16x32_bf16 v[34:37], v[172:175], v[216:219], v[34:37]
	v_mfma_f32_16x16x32_bf16 v[38:41], v[200:203], v[216:219], v[38:41]
	v_mfma_f32_16x16x32_bf16 v[18:21], v[172:175], v[224:227], v[18:21]
	v_mfma_f32_16x16x32_bf16 v[22:25], v[200:203], v[224:227], v[22:25]
	v_mfma_f32_16x16x32_bf16 v[2:5], v[172:175], v[232:235], v[2:5]
	v_mfma_f32_16x16x32_bf16 v[6:9], v[200:203], v[232:235], v[6:9]
	v_mfma_f32_16x16x32_bf16 v[50:53], v[176:179], v[212:215], v[50:53]
	v_mfma_f32_16x16x32_bf16 v[54:57], v[204:207], v[212:215], v[54:57]
	v_mfma_f32_16x16x32_bf16 v[34:37], v[176:179], v[220:223], v[34:37]
	v_mfma_f32_16x16x32_bf16 v[38:41], v[204:207], v[220:223], v[38:41]
	v_mfma_f32_16x16x32_bf16 v[18:21], v[176:179], v[228:231], v[18:21]
	v_mfma_f32_16x16x32_bf16 v[22:25], v[204:207], v[228:231], v[22:25]
	v_mfma_f32_16x16x32_bf16 v[2:5], v[176:179], v[236:239], v[2:5]
	v_mfma_f32_16x16x32_bf16 v[6:9], v[204:207], v[236:239], v[6:9]
	s_barrier
	s_add_i32 s43, s43, 2
	s_add_u32 s8, s8, 0x100
	s_addc_u32 s9, s9, 0
	s_add_u32 s41, s41, 0x100
	s_addc_u32 s42, s42, 0
	s_cmp_gt_u32 s43, 13
	s_cbranch_scc0 .LBB0_419
	s_and_b64 vcc, exec, s[86:87]
	s_cbranch_vccz .LBB0_422
	s_barrier

; #define PG8_STAGE(bufoff, gbase, voff) do { _Pragma("unroll") for (int _i = 0; _i < 2; ++_i) \
;         __builtin_amdgcn_global_load_lds((const unsigned*)((const char*)(gbase) + (voff)[_i]), (LAS unsigned*)(lds + (bufoff) + ldsw + _i * 8192), 16, 0, 0); } while (0)
; #define PG8_LDA(dst, b, h) do { _Pragma("unroll") for (int m = 0; m < 4; ++m) _Pragma("unroll") for (int k = 0; k < 2; ++k) dst[m][k] = *(const LAS bf16x8*)(lds + PG8_SA(b, h) + aoff + m * 2048 + k * 1024); } while (0)
; #define PG8_LDB(dst, b, h) do { _Pragma("unroll") for (int n = 0; n < 2; ++n) _Pragma("unroll") for (int k = 0; k < 2; ++k) dst[n][k] = *(const LAS bf16x8*)(lds + PG8_SB(b, h) + boff + n * 2048 + k * 1024); } while (0)
; #define PG8_MMA(ai, bj, At, Bt) do { __builtin_amdgcn_s_setprio(1); _Pragma("unroll") for (int m = 0; m < 4; ++m) _Pragma("unroll") for (int n = 0; n < 2; ++n) _Pragma("unroll") for (int k = 0; k < 2; ++k) \
;         acc[ai][bj][m][n] = __builtin_amdgcn_mfma_f32_16x16x32_bf16(Bt[n][k], At[m][k], acc[ai][bj][m][n], 0, 0, 0); __builtin_amdgcn_s_setprio(0); } while (0)
; #define PG8_WAIT_V(n) asm volatile("s_waitcnt vmcnt(" #n ")" ::: "memory")
; #define PG8_WAIT_L(n) asm volatile("s_waitcnt lgkmcnt(" #n ")" ::: "memory")
; #define PG8_BAR __builtin_amdgcn_s_barrier()
; #define PG8_SCHED __builtin_amdgcn_sched_barrier(0)
; template <class Epi, bool ALIGN_EPI>
; __device__ __forceinline__ void gemm_phase(LAS unsigned char* lds, const Gemm g, const StaticOrder& S, const Epi& E) {
;     ...
;         for (int t = 0; t < nt; t += 2) {
;             const bool last = (t == nt - 2);
;             const char* a1 = cA + (size_t)(t + 1) * kstepA;
;             const char* a2 = last ? nA : cA + (size_t)(t + 2) * kstepA; const char* b2 = last ? nB : cB + (size_t)(t + 2) * kstep;
;             const char* a3 = a2 + kstepA; const char* b3 = b2 + kstep;
;             PG8_LDB(B0, 0, 0); PG8_LDB(B1, 0, 1); PG8_SCHED; PG8_LDA(At, 0, 0); PG8_STAGE(PG8_SA(1, 1), a1 + hsA, voffA);
;             PG8_WAIT_V(8); PG8_WAIT_L(0); PG8_BAR; PG8_MMA(0, 0, At, B0); PG8_MMA(0, 1, At, B1); PG8_BAR; PG8_SCHED;
;             PG8_LDA(At, 0, 1); PG8_STAGE(PG8_SB(0, 0), b2, voffB); PG8_STAGE(PG8_SB(0, 1), b2 + hsB, voffB); PG8_STAGE(PG8_SA(0, 0), a2, voffA);
.LBB0_670:
	s_add_i32 s55, s28, 2
	s_add_u32 s29, s26, 0xfffe0080
	s_addc_u32 s30, s27, -1
	s_cmp_eq_u32 s46, s28
	s_cselect_b32 s28, s52, s53
	s_cselect_b32 s31, s17, s30
	s_cselect_b32 s30, s19, s29
	s_cselect_b32 s29, s51, s54
	v_lshl_add_u64 v[212:213], s[26:27], 0, v[140:141]
	s_add_i32 m0, s38, 0xc000
	s_nop 0
	global_load_lds_dwordx4 v[212:213], off
	v_lshl_add_u64 v[212:213], s[26:27], 0, v[142:143]
	s_add_i32 m0, s38, 0xe000
	s_nop 0
	global_load_lds_dwordx4 v[212:213], off
	ds_read_b128 v[148:151], v145
	ds_read_b128 v[152:155], v145 offset:1024
	ds_read_b128 v[156:159], v145 offset:2048
	ds_read_b128 v[160:163], v145 offset:3072
	ds_read_b128 v[164:167], v146
	ds_read_b128 v[168:171], v146 offset:1024
	ds_read_b128 v[172:175], v146 offset:2048
	ds_read_b128 v[176:179], v146 offset:3072
	ds_read_b128 v[180:183], v147
	ds_read_b128 v[184:187], v147 offset:1024
	ds_read_b128 v[188:191], v147 offset:2048
	ds_read_b128 v[192:195], v147 offset:3072
	ds_read_b128 v[196:199], v147 offset:4096
	ds_read_b128 v[200:203], v147 offset:5120
	ds_read_b128 v[204:207], v147 offset:6144
	ds_read_b128 v[208:211], v147 offset:7168
	s_waitcnt vmcnt(8)
	s_waitcnt lgkmcnt(0)
	s_barrier
	s_waitcnt lgkmcnt(0)
	v_mfma_f32_16x16x32_bf16 v[126:129], v[148:151], v[180:183], v[126:129]
	v_mfma_f32_16x16x32_bf16 v[122:125], v[156:159], v[180:183], v[122:125]
	v_mfma_f32_16x16x32_bf16 v[110:113], v[148:151], v[188:191], v[110:113]
	v_mfma_f32_16x16x32_bf16 v[106:109], v[156:159], v[188:191], v[106:109]
	v_mfma_f32_16x16x32_bf16 v[94:97], v[148:151], v[196:199], v[94:97]
	v_mfma_f32_16x16x32_bf16 v[90:93], v[156:159], v[196:199], v[90:93]
	v_mfma_f32_16x16x32_bf16 v[78:81], v[148:151], v[204:207], v[78:81]
	v_mfma_f32_16x16x32_bf16 v[74:77], v[156:159], v[204:207], v[74:77]
	v_mfma_f32_16x16x32_bf16 v[126:129], v[152:155], v[184:187], v[126:129]
	v_mfma_f32_16x16x32_bf16 v[122:125], v[160:163], v[184:187], v[122:125]
	v_mfma_f32_16x16x32_bf16 v[110:113], v[152:155], v[192:195], v[110:113]
	v_mfma_f32_16x16x32_bf16 v[106:109], v[160:163], v[192:195], v[106:109]
	v_mfma_f32_16x16x32_bf16 v[94:97], v[152:155], v[200:203], v[94:97]
	v_mfma_f32_16x16x32_bf16 v[90:93], v[160:163], v[200:203], v[90:93]
	v_mfma_f32_16x16x32_bf16 v[78:81], v[152:155], v[208:211], v[78:81]
	v_mfma_f32_16x16x32_bf16 v[74:77], v[160:163], v[208:211], v[74:77]
	v_mfma_f32_16x16x32_bf16 v[118:121], v[164:167], v[180:183], v[118:121]
	v_mfma_f32_16x16x32_bf16 v[114:117], v[172:175], v[180:183], v[114:117]
	v_mfma_f32_16x16x32_bf16 v[102:105], v[164:167], v[188:191], v[102:105]
	v_mfma_f32_16x16x32_bf16 v[98:101], v[172:175], v[188:191], v[98:101]
	v_mfma_f32_16x16x32_bf16 v[86:89], v[164:167], v[196:199], v[86:89]
	v_mfma_f32_16x16x32_bf16 v[82:85], v[172:175], v[196:199], v[82:85]
	v_mfma_f32_16x16x32_bf16 v[70:73], v[164:167], v[204:207], v[70:73]
	v_mfma_f32_16x16x32_bf16 v[66:69], v[172:175], v[204:207], v[66:69]
	v_mfma_f32_16x16x32_bf16 v[118:121], v[168:171], v[184:187], v[118:121]
	v_mfma_f32_16x16x32_bf16 v[114:117], v[176:179], v[184:187], v[114:117]
	v_mfma_f32_16x16x32_bf16 v[102:105], v[168:171], v[192:195], v[102:105]
	v_mfma_f32_16x16x32_bf16 v[98:101], v[176:179], v[192:195], v[98:101]
	v_mfma_f32_16x16x32_bf16 v[86:89], v[168:171], v[200:203], v[86:89]
	v_mfma_f32_16x16x32_bf16 v[82:85], v[176:179], v[200:203], v[82:85]
	v_mfma_f32_16x16x32_bf16 v[70:73], v[168:171], v[208:211], v[70:73]
	v_mfma_f32_16x16x32_bf16 v[66:69], v[176:179], v[208:211], v[66:69]
	s_barrier
	s_add_i32 s56, s48, s36
	v_lshl_add_u64 v[212:213], s[28:29], 0, v[134:135]
	s_mov_b32 m0, s56
	s_nop 0
	global_load_lds_dwordx4 v[212:213], off
	s_add_i32 m0, s56, 0x2000
	s_add_u32 s56, s28, 0x10000
	v_lshl_add_u64 v[214:215], s[28:29], 0, v[130:131]
	s_addc_u32 s57, s29, 0
	s_add_i32 s58, s49, s36
	global_load_lds_dwordx4 v[214:215], off
	v_lshl_add_u64 v[216:217], s[56:57], 0, v[134:135]
	s_mov_b32 m0, s58
	v_lshl_add_u64 v[218:219], s[30:31], 0, v[132:133]
	global_load_lds_dwordx4 v[216:217], off
	v_lshl_add_u64 v[216:217], s[56:57], 0, v[130:131]
	s_add_i32 m0, s58, 0x2000
	s_nop 0
	global_load_lds_dwordx4 v[216:217], off
	v_lshl_add_u64 v[216:217], s[30:31], 0, v[136:137]
	s_mov_b32 m0, s38
	s_nop 0
	global_load_lds_dwordx4 v[216:217], off
	s_mov_b32 m0, s39
	s_nop 0
	global_load_lds_dwordx4 v[218:219], off
	ds_read_b128 v[180:183], v147 offset:16384
	ds_read_b128 v[184:187], v147 offset:17408
	ds_read_b128 v[188:191], v147 offset:18432
	ds_read_b128 v[192:195], v147 offset:19456
	ds_read_b128 v[196:199], v147 offset:20480
	ds_read_b128 v[200:203], v147 offset:21504
	ds_read_b128 v[204:207], v147 offset:22528
	ds_read_b128 v[208:211], v147 offset:23552
	s_waitcnt vmcnt(8)
	s_waitcnt lgkmcnt(0)
	s_barrier
; #define PG8_STAGE(bufoff, gbase, voff) do { _Pragma("unroll") for (int _i = 0; _i < 2; ++_i) \
;         __builtin_amdgcn_global_load_lds((const unsigned*)((const char*)(gbase) + (voff)[_i]), (LAS unsigned*)(lds + (bufoff) + ldsw + _i * 8192), 16, 0, 0); } while (0)
; #define PG8_LDA(dst, b, h) do { _Pragma("unroll") for (int m = 0; m < 4; ++m) _Pragma("unroll") for (int k = 0; k < 2; ++k) dst[m][k] = *(const LAS bf16x8*)(lds + PG8_SA(b, h) + aoff + m * 2048 + k * 1024); } while (0)
; #define PG8_LDB(dst, b, h) do { _Pragma("unroll") for (int n = 0; n < 2; ++n) _Pragma("unroll") for (int k = 0; k < 2; ++k) dst[n][k] = *(const LAS bf16x8*)(lds + PG8_SB(b, h) + boff + n * 2048 + k * 1024); } while (0)
; #define PG8_MMA(ai, bj, At, Bt) do { __builtin_amdgcn_s_setprio(1); _Pragma("unroll") for (int m = 0; m < 4; ++m) _Pragma("unroll") for (int n = 0; n < 2; ++n) _Pragma("unroll") for (int k = 0; k < 2; ++k) \
;         acc[ai][bj][m][n] = __builtin_amdgcn_mfma_f32_16x16x32_bf16(Bt[n][k], At[m][k], acc[ai][bj][m][n], 0, 0, 0); __builtin_amdgcn_s_setprio(0); } while (0)
; #define PG8_WAIT_V(n) asm volatile("s_waitcnt vmcnt(" #n ")" ::: "memory")
; #define PG8_WAIT_L(n) asm volatile("s_waitcnt lgkmcnt(" #n ")" ::: "memory")
; #define PG8_BAR __builtin_amdgcn_s_barrier()
; #define PG8_SCHED __builtin_amdgcn_sched_barrier(0)
; template <class Epi, bool ALIGN_EPI>
; __device__ __forceinline__ void gemm_phase(LAS unsigned char* lds, const Gemm g, const StaticOrder& S, const Epi& E) {
;     ...
;             PG8_WAIT_V(8); PG8_WAIT_L(0); PG8_BAR; PG8_MMA(1, 0, At, B0); PG8_MMA(1, 1, At, B1); PG8_BAR; PG8_SCHED;
;             PG8_LDB(B0, 1, 0); PG8_LDB(B1, 1, 1); PG8_SCHED; PG8_LDA(At, 1, 0); PG8_STAGE(PG8_SA(0, 1), a2 + hsA, voffA);
;             PG8_WAIT_V(8); PG8_WAIT_L(0); PG8_BAR; PG8_MMA(0, 0, At, B0); PG8_MMA(0, 1, At, B1); PG8_BAR; PG8_SCHED;
	s_waitcnt lgkmcnt(0)
	v_mfma_f32_16x16x32_bf16 v[62:65], v[148:151], v[180:183], v[62:65]
	v_mfma_f32_16x16x32_bf16 v[58:61], v[156:159], v[180:183], v[58:61]
	v_mfma_f32_16x16x32_bf16 v[46:49], v[148:151], v[188:191], v[46:49]
	v_mfma_f32_16x16x32_bf16 v[42:45], v[156:159], v[188:191], v[42:45]
	v_mfma_f32_16x16x32_bf16 v[30:33], v[148:151], v[196:199], v[30:33]
	v_mfma_f32_16x16x32_bf16 v[26:29], v[156:159], v[196:199], v[26:29]
	v_mfma_f32_16x16x32_bf16 v[14:17], v[148:151], v[204:207], v[14:17]
	v_mfma_f32_16x16x32_bf16 v[10:13], v[156:159], v[204:207], v[10:13]
	v_mfma_f32_16x16x32_bf16 v[62:65], v[152:155], v[184:187], v[62:65]
	v_mfma_f32_16x16x32_bf16 v[58:61], v[160:163], v[184:187], v[58:61]
	v_mfma_f32_16x16x32_bf16 v[46:49], v[152:155], v[192:195], v[46:49]
	v_mfma_f32_16x16x32_bf16 v[42:45], v[160:163], v[192:195], v[42:45]
	v_mfma_f32_16x16x32_bf16 v[30:33], v[152:155], v[200:203], v[30:33]
	v_mfma_f32_16x16x32_bf16 v[26:29], v[160:163], v[200:203], v[26:29]
	v_mfma_f32_16x16x32_bf16 v[14:17], v[152:155], v[208:211], v[14:17]
	v_mfma_f32_16x16x32_bf16 v[10:13], v[160:163], v[208:211], v[10:13]
	v_mfma_f32_16x16x32_bf16 v[54:57], v[164:167], v[180:183], v[54:57]
	v_mfma_f32_16x16x32_bf16 v[50:53], v[172:175], v[180:183], v[50:53]
	v_mfma_f32_16x16x32_bf16 v[38:41], v[164:167], v[188:191], v[38:41]
	v_mfma_f32_16x16x32_bf16 v[34:37], v[172:175], v[188:191], v[34:37]
	v_mfma_f32_16x16x32_bf16 v[22:25], v[164:167], v[196:199], v[22:25]
	v_mfma_f32_16x16x32_bf16 v[18:21], v[172:175], v[196:199], v[18:21]
	v_mfma_f32_16x16x32_bf16 v[6:9], v[164:167], v[204:207], v[6:9]
	v_mfma_f32_16x16x32_bf16 v[2:5], v[172:175], v[204:207], v[2:5]
	v_mfma_f32_16x16x32_bf16 v[54:57], v[168:171], v[184:187], v[54:57]
	v_mfma_f32_16x16x32_bf16 v[50:53], v[176:179], v[184:187], v[50:53]
	v_mfma_f32_16x16x32_bf16 v[38:41], v[168:171], v[192:195], v[38:41]
	v_mfma_f32_16x16x32_bf16 v[34:37], v[176:179], v[192:195], v[34:37]
	v_mfma_f32_16x16x32_bf16 v[22:25], v[168:171], v[200:203], v[22:25]
	v_mfma_f32_16x16x32_bf16 v[18:21], v[176:179], v[200:203], v[18:21]
	v_mfma_f32_16x16x32_bf16 v[6:9], v[168:171], v[208:211], v[6:9]
	v_mfma_f32_16x16x32_bf16 v[2:5], v[176:179], v[208:211], v[2:5]
	s_barrier
	s_add_i32 s56, 0, 0x18000
	s_add_i32 s57, 0, 0x1c000
	s_add_u32 s30, s30, 0x20000
	s_addc_u32 s31, s31, 0
	s_mov_b32 m0, s40
	v_lshl_add_u64 v[220:221], s[30:31], 0, v[136:137]
	global_load_lds_dwordx4 v[220:221], off
	v_lshl_add_u64 v[220:221], s[30:31], 0, v[132:133]
	s_mov_b32 m0, s41
	s_nop 0
	global_load_lds_dwordx4 v[220:221], off
	v_add_u32_e32 v160, s56, v144
	v_add_u32_e32 v176, s57, v144
	ds_read_b128 v[148:151], v160
	ds_read_b128 v[152:155], v160 offset:1024
	ds_read_b128 v[156:159], v160 offset:2048
	ds_read_b128 v[160:163], v160 offset:3072
	ds_read_b128 v[164:167], v176
	ds_read_b128 v[168:171], v176 offset:1024
	ds_read_b128 v[172:175], v176 offset:2048
	ds_read_b128 v[176:179], v176 offset:3072
	ds_read_b128 v[180:183], v147 offset:32768
	ds_read_b128 v[184:187], v147 offset:33792
	ds_read_b128 v[188:191], v147 offset:34816
	ds_read_b128 v[192:195], v147 offset:35840
	ds_read_b128 v[196:199], v147 offset:36864
	ds_read_b128 v[200:203], v147 offset:37888
	ds_read_b128 v[204:207], v147 offset:38912
	ds_read_b128 v[208:211], v147 offset:39936
	s_waitcnt vmcnt(8)
	s_waitcnt lgkmcnt(0)
	s_barrier
	s_waitcnt lgkmcnt(0)
	v_mfma_f32_16x16x32_bf16 v[126:129], v[148:151], v[180:183], v[126:129]
	v_mfma_f32_16x16x32_bf16 v[122:125], v[156:159], v[180:183], v[122:125]
	v_mfma_f32_16x16x32_bf16 v[110:113], v[148:151], v[188:191], v[110:113]
	v_mfma_f32_16x16x32_bf16 v[106:109], v[156:159], v[188:191], v[106:109]
	v_mfma_f32_16x16x32_bf16 v[94:97], v[148:151], v[196:199], v[94:97]
	v_mfma_f32_16x16x32_bf16 v[90:93], v[156:159], v[196:199], v[90:93]
	v_mfma_f32_16x16x32_bf16 v[78:81], v[148:151], v[204:207], v[78:81]
	v_mfma_f32_16x16x32_bf16 v[74:77], v[156:159], v[204:207], v[74:77]
	v_mfma_f32_16x16x32_bf16 v[126:129], v[152:155], v[184:187], v[126:129]
	v_mfma_f32_16x16x32_bf16 v[122:125], v[160:163], v[184:187], v[122:125]
	v_mfma_f32_16x16x32_bf16 v[110:113], v[152:155], v[192:195], v[110:113]
	v_mfma_f32_16x16x32_bf16 v[106:109], v[160:163], v[192:195], v[106:109]
	v_mfma_f32_16x16x32_bf16 v[94:97], v[152:155], v[200:203], v[94:97]
	v_mfma_f32_16x16x32_bf16 v[90:93], v[160:163], v[200:203], v[90:93]
	v_mfma_f32_16x16x32_bf16 v[78:81], v[152:155], v[208:211], v[78:81]
	v_mfma_f32_16x16x32_bf16 v[74:77], v[160:163], v[208:211], v[74:77]
	v_mfma_f32_16x16x32_bf16 v[118:121], v[164:167], v[180:183], v[118:121]
	v_mfma_f32_16x16x32_bf16 v[114:117], v[172:175], v[180:183], v[114:117]
	v_mfma_f32_16x16x32_bf16 v[102:105], v[164:167], v[188:191], v[102:105]
	v_mfma_f32_16x16x32_bf16 v[98:101], v[172:175], v[188:191], v[98:101]
	v_mfma_f32_16x16x32_bf16 v[86:89], v[164:167], v[196:199], v[86:89]
	v_mfma_f32_16x16x32_bf16 v[82:85], v[172:175], v[196:199], v[82:85]
	v_mfma_f32_16x16x32_bf16 v[70:73], v[164:167], v[204:207], v[70:73]
	v_mfma_f32_16x16x32_bf16 v[66:69], v[172:175], v[204:207], v[66:69]
	v_mfma_f32_16x16x32_bf16 v[118:121], v[168:171], v[184:187], v[118:121]
	v_mfma_f32_16x16x32_bf16 v[114:117], v[176:179], v[184:187], v[114:117]
	v_mfma_f32_16x16x32_bf16 v[102:105], v[168:171], v[192:195], v[102:105]
	v_mfma_f32_16x16x32_bf16 v[98:101], v[176:179], v[192:195], v[98:101]
	v_mfma_f32_16x16x32_bf16 v[86:89], v[168:171], v[200:203], v[86:89]
	v_mfma_f32_16x16x32_bf16 v[82:85], v[176:179], v[200:203], v[82:85]
	v_mfma_f32_16x16x32_bf16 v[70:73], v[168:171], v[208:211], v[70:73]
	v_mfma_f32_16x16x32_bf16 v[66:69], v[176:179], v[208:211], v[66:69]
	s_barrier
; #define PG8_STAGE(bufoff, gbase, voff) do { _Pragma("unroll") for (int _i = 0; _i < 2; ++_i) \
;         __builtin_amdgcn_global_load_lds((const unsigned*)((const char*)(gbase) + (voff)[_i]), (LAS unsigned*)(lds + (bufoff) + ldsw + _i * 8192), 16, 0, 0); } while (0)
; #define PG8_LDA(dst, b, h) do { _Pragma("unroll") for (int m = 0; m < 4; ++m) _Pragma("unroll") for (int k = 0; k < 2; ++k) dst[m][k] = *(const LAS bf16x8*)(lds + PG8_SA(b, h) + aoff + m * 2048 + k * 1024); } while (0)
; #define PG8_MMA(ai, bj, At, Bt) do { __builtin_amdgcn_s_setprio(1); _Pragma("unroll") for (int m = 0; m < 4; ++m) _Pragma("unroll") for (int n = 0; n < 2; ++n) _Pragma("unroll") for (int k = 0; k < 2; ++k) \
;         acc[ai][bj][m][n] = __builtin_amdgcn_mfma_f32_16x16x32_bf16(Bt[n][k], At[m][k], acc[ai][bj][m][n], 0, 0, 0); __builtin_amdgcn_s_setprio(0); } while (0)
; #define PG8_WAIT_V(n) asm volatile("s_waitcnt vmcnt(" #n ")" ::: "memory")
; #define PG8_WAIT_L(n) asm volatile("s_waitcnt lgkmcnt(" #n ")" ::: "memory")
; #define PG8_BAR __builtin_amdgcn_s_barrier()
; #define PG8_SCHED __builtin_amdgcn_sched_barrier(0)
; template <class Epi, bool ALIGN_EPI>
; __device__ __forceinline__ void gemm_phase(LAS unsigned char* lds, const Gemm g, const StaticOrder& S, const Epi& E) {
;     ...
;             PG8_LDA(At, 1, 1); PG8_STAGE(PG8_SB(1, 0), b3, voffB); PG8_STAGE(PG8_SB(1, 1), b3 + hsB, voffB); PG8_STAGE(PG8_SA(1, 0), a3, voffA);
;             PG8_WAIT_V(8); PG8_WAIT_L(0); PG8_BAR; PG8_MMA(1, 0, At, B0); PG8_MMA(1, 1, At, B1); PG8_BAR; PG8_SCHED;
;         }
	s_add_i32 s30, s56, s36
	v_lshl_add_u64 v[212:213], v[212:213], 0, s[8:9]
	s_mov_b32 m0, s30
	s_nop 0
	global_load_lds_dwordx4 v[212:213], off
	s_add_i32 m0, s30, 0x2000
	s_add_u32 s28, s28, 0x10080
	v_lshl_add_u64 v[212:213], v[214:215], 0, s[8:9]
	s_addc_u32 s29, s29, 0
	s_add_i32 s30, s57, s36
	global_load_lds_dwordx4 v[212:213], off
	v_lshl_add_u64 v[212:213], s[28:29], 0, v[134:135]
	s_mov_b32 m0, s30
	s_nop 0
	global_load_lds_dwordx4 v[212:213], off
	v_lshl_add_u64 v[212:213], s[28:29], 0, v[130:131]
	s_add_i32 m0, s30, 0x2000
	s_nop 0
	global_load_lds_dwordx4 v[212:213], off
	v_lshl_add_u64 v[212:213], v[216:217], 0, s[8:9]
	s_mov_b32 m0, s44
	s_nop 0
	global_load_lds_dwordx4 v[212:213], off
	v_lshl_add_u64 v[212:213], v[218:219], 0, s[8:9]
	s_mov_b32 m0, s45
	s_nop 0
	global_load_lds_dwordx4 v[212:213], off
	ds_read_b128 v[180:183], v147 offset:49152
	ds_read_b128 v[184:187], v147 offset:50176
	ds_read_b128 v[188:191], v147 offset:51200
	ds_read_b128 v[192:195], v147 offset:52224
	ds_read_b128 v[196:199], v147 offset:53248
	ds_read_b128 v[200:203], v147 offset:54272
	ds_read_b128 v[204:207], v147 offset:55296
	ds_read_b128 v[208:211], v147 offset:56320
	s_waitcnt vmcnt(8)
	s_waitcnt lgkmcnt(0)
	s_barrier
	s_waitcnt lgkmcnt(0)
	v_mfma_f32_16x16x32_bf16 v[62:65], v[148:151], v[180:183], v[62:65]
	v_mfma_f32_16x16x32_bf16 v[58:61], v[156:159], v[180:183], v[58:61]
	v_mfma_f32_16x16x32_bf16 v[46:49], v[148:151], v[188:191], v[46:49]
	v_mfma_f32_16x16x32_bf16 v[42:45], v[156:159], v[188:191], v[42:45]
	v_mfma_f32_16x16x32_bf16 v[30:33], v[148:151], v[196:199], v[30:33]
	v_mfma_f32_16x16x32_bf16 v[26:29], v[156:159], v[196:199], v[26:29]
	v_mfma_f32_16x16x32_bf16 v[14:17], v[148:151], v[204:207], v[14:17]
	v_mfma_f32_16x16x32_bf16 v[10:13], v[156:159], v[204:207], v[10:13]
	v_mfma_f32_16x16x32_bf16 v[62:65], v[152:155], v[184:187], v[62:65]
	v_mfma_f32_16x16x32_bf16 v[58:61], v[160:163], v[184:187], v[58:61]
	v_mfma_f32_16x16x32_bf16 v[46:49], v[152:155], v[192:195], v[46:49]
	v_mfma_f32_16x16x32_bf16 v[42:45], v[160:163], v[192:195], v[42:45]
	v_mfma_f32_16x16x32_bf16 v[30:33], v[152:155], v[200:203], v[30:33]
	v_mfma_f32_16x16x32_bf16 v[26:29], v[160:163], v[200:203], v[26:29]
	v_mfma_f32_16x16x32_bf16 v[14:17], v[152:155], v[208:211], v[14:17]
	v_mfma_f32_16x16x32_bf16 v[10:13], v[160:163], v[208:211], v[10:13]
	v_mfma_f32_16x16x32_bf16 v[54:57], v[164:167], v[180:183], v[54:57]
	v_mfma_f32_16x16x32_bf16 v[50:53], v[172:175], v[180:183], v[50:53]
	v_mfma_f32_16x16x32_bf16 v[38:41], v[164:167], v[188:191], v[38:41]
	v_mfma_f32_16x16x32_bf16 v[34:37], v[172:175], v[188:191], v[34:37]
	v_mfma_f32_16x16x32_bf16 v[22:25], v[164:167], v[196:199], v[22:25]
	v_mfma_f32_16x16x32_bf16 v[18:21], v[172:175], v[196:199], v[18:21]
	v_mfma_f32_16x16x32_bf16 v[6:9], v[164:167], v[204:207], v[6:9]
	v_mfma_f32_16x16x32_bf16 v[2:5], v[172:175], v[204:207], v[2:5]
	v_mfma_f32_16x16x32_bf16 v[54:57], v[168:171], v[184:187], v[54:57]
	v_mfma_f32_16x16x32_bf16 v[50:53], v[176:179], v[184:187], v[50:53]
	v_mfma_f32_16x16x32_bf16 v[38:41], v[168:171], v[192:195], v[38:41]
	v_mfma_f32_16x16x32_bf16 v[34:37], v[176:179], v[192:195], v[34:37]
	v_mfma_f32_16x16x32_bf16 v[22:25], v[168:171], v[200:203], v[22:25]
	v_mfma_f32_16x16x32_bf16 v[18:21], v[176:179], v[200:203], v[18:21]
	v_mfma_f32_16x16x32_bf16 v[6:9], v[168:171], v[208:211], v[6:9]
	v_mfma_f32_16x16x32_bf16 v[2:5], v[176:179], v[208:211], v[2:5]
	s_barrier
	s_add_u32 s26, s26, 0x100
	s_addc_u32 s27, s27, 0
	s_add_u32 s53, s53, 0x100
	s_addc_u32 s54, s54, 0
	s_cmp_ge_i32 s55, s43
	s_mov_b32 s28, s55
	s_cbranch_scc0 .LBB0_670

; #define PG8_STAGE(bufoff, gbase, voff) do { _Pragma("unroll") for (int _i = 0; _i < 2; ++_i) \
;         __builtin_amdgcn_global_load_lds((const unsigned*)((const char*)(gbase) + (voff)[_i]), (LAS unsigned*)(lds + (bufoff) + ldsw + _i * 8192), 16, 0, 0); } while (0)
; #define PG8_LDA(dst, b, h) do { _Pragma("unroll") for (int m = 0; m < 4; ++m) _Pragma("unroll") for (int k = 0; k < 2; ++k) dst[m][k] = *(const LAS bf16x8*)(lds + PG8_SA(b, h) + aoff + m * 2048 + k * 1024); } while (0)
; #define PG8_LDB(dst, b, h) do { _Pragma("unroll") for (int n = 0; n < 2; ++n) _Pragma("unroll") for (int k = 0; k < 2; ++k) dst[n][k] = *(const LAS bf16x8*)(lds + PG8_SB(b, h) + boff + n * 2048 + k * 1024); } while (0)
; #define PG8_MMA(ai, bj, At, Bt) do { __builtin_amdgcn_s_setprio(1); _Pragma("unroll") for (int m = 0; m < 4; ++m) _Pragma("unroll") for (int n = 0; n < 2; ++n) _Pragma("unroll") for (int k = 0; k < 2; ++k) \
;         acc[ai][bj][m][n] = __builtin_amdgcn_mfma_f32_16x16x32_bf16(Bt[n][k], At[m][k], acc[ai][bj][m][n], 0, 0, 0); __builtin_amdgcn_s_setprio(0); } while (0)
; #define PG8_WAIT_V(n) asm volatile("s_waitcnt vmcnt(" #n ")" ::: "memory")
; #define PG8_WAIT_L(n) asm volatile("s_waitcnt lgkmcnt(" #n ")" ::: "memory")
; #define PG8_BAR __builtin_amdgcn_s_barrier()
; #define PG8_SCHED __builtin_amdgcn_sched_barrier(0)
; template <class Epi, bool ALIGN_EPI>
; __device__ __forceinline__ void gemm_phase(LAS unsigned char* lds, const Gemm g, const StaticOrder& S, const Epi& E) {
;     ...
;         for (int t = 0; t < nt; t += 2) {
;             const bool last = (t == nt - 2);
;             const char* a1 = cA + (size_t)(t + 1) * kstepA;
;             const char* a2 = last ? nA : cA + (size_t)(t + 2) * kstepA; const char* b2 = last ? nB : cB + (size_t)(t + 2) * kstep;
;             const char* a3 = a2 + kstepA; const char* b3 = b2 + kstep;
;             PG8_LDB(B0, 0, 0); PG8_LDB(B1, 0, 1); PG8_SCHED; PG8_LDA(At, 0, 0); PG8_STAGE(PG8_SA(1, 1), a1 + hsA, voffA);
;             PG8_WAIT_V(8); PG8_WAIT_L(0); PG8_BAR; PG8_MMA(0, 0, At, B0); PG8_MMA(0, 1, At, B1); PG8_BAR; PG8_SCHED;
;             PG8_LDA(At, 0, 1); PG8_STAGE(PG8_SB(0, 0), b2, voffB); PG8_STAGE(PG8_SB(0, 1), b2 + hsB, voffB); PG8_STAGE(PG8_SA(0, 0), a2, voffA);
.LBB0_948:
	s_add_u32 s26, s24, 0xfffe0080
	s_addc_u32 s27, s25, -1
	s_cmp_eq_u32 s21, 4
	s_cselect_b32 s29, s5, s27
	s_cselect_b32 s28, s4, s26
	s_cselect_b32 s27, s23, s19
	s_cselect_b32 s26, s22, s17
	v_lshl_add_u64 v[218:219], s[24:25], 0, v[140:141]
	s_add_i32 m0, s30, 0xc000
	s_nop 0
	global_load_lds_dwordx4 v[218:219], off
	v_lshl_add_u64 v[218:219], s[24:25], 0, v[142:143]
	s_add_i32 m0, s30, 0xe000
	s_nop 0
	global_load_lds_dwordx4 v[218:219], off
	ds_read_b128 v[154:157], v151
	ds_read_b128 v[158:161], v151 offset:1024
	ds_read_b128 v[162:165], v151 offset:2048
	ds_read_b128 v[166:169], v151 offset:3072
	ds_read_b128 v[170:173], v152
	ds_read_b128 v[174:177], v152 offset:1024
	ds_read_b128 v[178:181], v152 offset:2048
	ds_read_b128 v[182:185], v152 offset:3072
	ds_read_b128 v[186:189], v153
	ds_read_b128 v[190:193], v153 offset:1024
	ds_read_b128 v[194:197], v153 offset:2048
	ds_read_b128 v[198:201], v153 offset:3072
	ds_read_b128 v[202:205], v153 offset:4096
	ds_read_b128 v[206:209], v153 offset:5120
	ds_read_b128 v[210:213], v153 offset:6144
	ds_read_b128 v[214:217], v153 offset:7168
	s_waitcnt vmcnt(8)
	s_waitcnt lgkmcnt(0)
	s_barrier
	s_waitcnt lgkmcnt(0)
	v_mfma_f32_16x16x32_bf16 v[126:129], v[154:157], v[186:189], v[126:129]
	v_mfma_f32_16x16x32_bf16 v[122:125], v[162:165], v[186:189], v[122:125]
	v_mfma_f32_16x16x32_bf16 v[110:113], v[154:157], v[194:197], v[110:113]
	v_mfma_f32_16x16x32_bf16 v[106:109], v[162:165], v[194:197], v[106:109]
	v_mfma_f32_16x16x32_bf16 v[94:97], v[154:157], v[202:205], v[94:97]
	v_mfma_f32_16x16x32_bf16 v[90:93], v[162:165], v[202:205], v[90:93]
	v_mfma_f32_16x16x32_bf16 v[78:81], v[154:157], v[210:213], v[78:81]
	v_mfma_f32_16x16x32_bf16 v[74:77], v[162:165], v[210:213], v[74:77]
	v_mfma_f32_16x16x32_bf16 v[126:129], v[158:161], v[190:193], v[126:129]
	v_mfma_f32_16x16x32_bf16 v[122:125], v[166:169], v[190:193], v[122:125]
	v_mfma_f32_16x16x32_bf16 v[110:113], v[158:161], v[198:201], v[110:113]
	v_mfma_f32_16x16x32_bf16 v[106:109], v[166:169], v[198:201], v[106:109]
	v_mfma_f32_16x16x32_bf16 v[94:97], v[158:161], v[206:209], v[94:97]
	v_mfma_f32_16x16x32_bf16 v[90:93], v[166:169], v[206:209], v[90:93]
	v_mfma_f32_16x16x32_bf16 v[78:81], v[158:161], v[214:217], v[78:81]
	v_mfma_f32_16x16x32_bf16 v[74:77], v[166:169], v[214:217], v[74:77]
	v_mfma_f32_16x16x32_bf16 v[118:121], v[170:173], v[186:189], v[118:121]
	v_mfma_f32_16x16x32_bf16 v[114:117], v[178:181], v[186:189], v[114:117]
	v_mfma_f32_16x16x32_bf16 v[102:105], v[170:173], v[194:197], v[102:105]
	v_mfma_f32_16x16x32_bf16 v[98:101], v[178:181], v[194:197], v[98:101]
	v_mfma_f32_16x16x32_bf16 v[86:89], v[170:173], v[202:205], v[86:89]
	v_mfma_f32_16x16x32_bf16 v[82:85], v[178:181], v[202:205], v[82:85]
	v_mfma_f32_16x16x32_bf16 v[70:73], v[170:173], v[210:213], v[70:73]
	v_mfma_f32_16x16x32_bf16 v[66:69], v[178:181], v[210:213], v[66:69]
	v_mfma_f32_16x16x32_bf16 v[118:121], v[174:177], v[190:193], v[118:121]
	v_mfma_f32_16x16x32_bf16 v[114:117], v[182:185], v[190:193], v[114:117]
	v_mfma_f32_16x16x32_bf16 v[102:105], v[174:177], v[198:201], v[102:105]
	v_mfma_f32_16x16x32_bf16 v[98:101], v[182:185], v[198:201], v[98:101]
	v_mfma_f32_16x16x32_bf16 v[86:89], v[174:177], v[206:209], v[86:89]
	v_mfma_f32_16x16x32_bf16 v[82:85], v[182:185], v[206:209], v[82:85]
	v_mfma_f32_16x16x32_bf16 v[70:73], v[174:177], v[214:217], v[70:73]
	v_mfma_f32_16x16x32_bf16 v[66:69], v[182:185], v[214:217], v[66:69]
	s_barrier
	s_add_i32 s42, s39, s15
	v_lshl_add_u64 v[218:219], s[26:27], 0, v[134:135]
	s_mov_b32 m0, s42
	s_nop 0
	global_load_lds_dwordx4 v[218:219], off
	s_add_i32 m0, s42, 0x2000
	s_add_u32 s42, s26, 0x20000
	v_lshl_add_u64 v[220:221], s[26:27], 0, v[130:131]
	s_addc_u32 s43, s27, 0
	s_add_i32 s44, s40, s15
	global_load_lds_dwordx4 v[220:221], off
	v_lshl_add_u64 v[222:223], s[42:43], 0, v[134:135]
	s_mov_b32 m0, s44
	v_lshl_add_u64 v[224:225], s[28:29], 0, v[132:133]
	global_load_lds_dwordx4 v[222:223], off
	v_lshl_add_u64 v[222:223], s[42:43], 0, v[130:131]
	s_add_i32 m0, s44, 0x2000
	s_nop 0
	global_load_lds_dwordx4 v[222:223], off
	v_lshl_add_u64 v[222:223], s[28:29], 0, v[136:137]
	s_mov_b32 m0, s30
	s_nop 0
	global_load_lds_dwordx4 v[222:223], off
	s_mov_b32 m0, s31
	s_nop 0
	global_load_lds_dwordx4 v[224:225], off
	ds_read_b128 v[186:189], v153 offset:16384
	ds_read_b128 v[190:193], v153 offset:17408
	ds_read_b128 v[194:197], v153 offset:18432
	ds_read_b128 v[198:201], v153 offset:19456
	ds_read_b128 v[202:205], v153 offset:20480
	ds_read_b128 v[206:209], v153 offset:21504
	ds_read_b128 v[210:213], v153 offset:22528
	ds_read_b128 v[214:217], v153 offset:23552
	s_waitcnt vmcnt(8)
	s_waitcnt lgkmcnt(0)
	s_barrier
; #define PG8_STAGE(bufoff, gbase, voff) do { _Pragma("unroll") for (int _i = 0; _i < 2; ++_i) \
;         __builtin_amdgcn_global_load_lds((const unsigned*)((const char*)(gbase) + (voff)[_i]), (LAS unsigned*)(lds + (bufoff) + ldsw + _i * 8192), 16, 0, 0); } while (0)
; #define PG8_LDA(dst, b, h) do { _Pragma("unroll") for (int m = 0; m < 4; ++m) _Pragma("unroll") for (int k = 0; k < 2; ++k) dst[m][k] = *(const LAS bf16x8*)(lds + PG8_SA(b, h) + aoff + m * 2048 + k * 1024); } while (0)
; #define PG8_LDB(dst, b, h) do { _Pragma("unroll") for (int n = 0; n < 2; ++n) _Pragma("unroll") for (int k = 0; k < 2; ++k) dst[n][k] = *(const LAS bf16x8*)(lds + PG8_SB(b, h) + boff + n * 2048 + k * 1024); } while (0)
; #define PG8_MMA(ai, bj, At, Bt) do { __builtin_amdgcn_s_setprio(1); _Pragma("unroll") for (int m = 0; m < 4; ++m) _Pragma("unroll") for (int n = 0; n < 2; ++n) _Pragma("unroll") for (int k = 0; k < 2; ++k) \
;         acc[ai][bj][m][n] = __builtin_amdgcn_mfma_f32_16x16x32_bf16(Bt[n][k], At[m][k], acc[ai][bj][m][n], 0, 0, 0); __builtin_amdgcn_s_setprio(0); } while (0)
; #define PG8_WAIT_V(n) asm volatile("s_waitcnt vmcnt(" #n ")" ::: "memory")
; #define PG8_WAIT_L(n) asm volatile("s_waitcnt lgkmcnt(" #n ")" ::: "memory")
; #define PG8_BAR __builtin_amdgcn_s_barrier()
; #define PG8_SCHED __builtin_amdgcn_sched_barrier(0)
; template <class Epi, bool ALIGN_EPI>
; __device__ __forceinline__ void gemm_phase(LAS unsigned char* lds, const Gemm g, const StaticOrder& S, const Epi& E) {
;     ...
;             PG8_WAIT_V(8); PG8_WAIT_L(0); PG8_BAR; PG8_MMA(1, 0, At, B0); PG8_MMA(1, 1, At, B1); PG8_BAR; PG8_SCHED;
;             PG8_LDB(B0, 1, 0); PG8_LDB(B1, 1, 1); PG8_SCHED; PG8_LDA(At, 1, 0); PG8_STAGE(PG8_SA(0, 1), a2 + hsA, voffA);
;             PG8_WAIT_V(8); PG8_WAIT_L(0); PG8_BAR; PG8_MMA(0, 0, At, B0); PG8_MMA(0, 1, At, B1); PG8_BAR; PG8_SCHED;
	s_waitcnt lgkmcnt(0)
	v_mfma_f32_16x16x32_bf16 v[62:65], v[154:157], v[186:189], v[62:65]
	v_mfma_f32_16x16x32_bf16 v[58:61], v[162:165], v[186:189], v[58:61]
	v_mfma_f32_16x16x32_bf16 v[46:49], v[154:157], v[194:197], v[46:49]
	v_mfma_f32_16x16x32_bf16 v[42:45], v[162:165], v[194:197], v[42:45]
	v_mfma_f32_16x16x32_bf16 v[30:33], v[154:157], v[202:205], v[30:33]
	v_mfma_f32_16x16x32_bf16 v[26:29], v[162:165], v[202:205], v[26:29]
	v_mfma_f32_16x16x32_bf16 v[14:17], v[154:157], v[210:213], v[14:17]
	v_mfma_f32_16x16x32_bf16 v[10:13], v[162:165], v[210:213], v[10:13]
	v_mfma_f32_16x16x32_bf16 v[62:65], v[158:161], v[190:193], v[62:65]
	v_mfma_f32_16x16x32_bf16 v[58:61], v[166:169], v[190:193], v[58:61]
	v_mfma_f32_16x16x32_bf16 v[46:49], v[158:161], v[198:201], v[46:49]
	v_mfma_f32_16x16x32_bf16 v[42:45], v[166:169], v[198:201], v[42:45]
	v_mfma_f32_16x16x32_bf16 v[30:33], v[158:161], v[206:209], v[30:33]
	v_mfma_f32_16x16x32_bf16 v[26:29], v[166:169], v[206:209], v[26:29]
	v_mfma_f32_16x16x32_bf16 v[14:17], v[158:161], v[214:217], v[14:17]
	v_mfma_f32_16x16x32_bf16 v[10:13], v[166:169], v[214:217], v[10:13]
	v_mfma_f32_16x16x32_bf16 v[54:57], v[170:173], v[186:189], v[54:57]
	v_mfma_f32_16x16x32_bf16 v[50:53], v[178:181], v[186:189], v[50:53]
	v_mfma_f32_16x16x32_bf16 v[38:41], v[170:173], v[194:197], v[38:41]
	v_mfma_f32_16x16x32_bf16 v[34:37], v[178:181], v[194:197], v[34:37]
	v_mfma_f32_16x16x32_bf16 v[22:25], v[170:173], v[202:205], v[22:25]
	v_mfma_f32_16x16x32_bf16 v[18:21], v[178:181], v[202:205], v[18:21]
	v_mfma_f32_16x16x32_bf16 v[6:9], v[170:173], v[210:213], v[6:9]
	v_mfma_f32_16x16x32_bf16 v[2:5], v[178:181], v[210:213], v[2:5]
	v_mfma_f32_16x16x32_bf16 v[54:57], v[174:177], v[190:193], v[54:57]
	v_mfma_f32_16x16x32_bf16 v[50:53], v[182:185], v[190:193], v[50:53]
	v_mfma_f32_16x16x32_bf16 v[38:41], v[174:177], v[198:201], v[38:41]
	v_mfma_f32_16x16x32_bf16 v[34:37], v[182:185], v[198:201], v[34:37]
	v_mfma_f32_16x16x32_bf16 v[22:25], v[174:177], v[206:209], v[22:25]
	v_mfma_f32_16x16x32_bf16 v[18:21], v[182:185], v[206:209], v[18:21]
	v_mfma_f32_16x16x32_bf16 v[6:9], v[174:177], v[214:217], v[6:9]
	v_mfma_f32_16x16x32_bf16 v[2:5], v[182:185], v[214:217], v[2:5]
	s_barrier
	s_add_i32 s42, 0, 0x18000
	s_add_i32 s43, 0, 0x1c000
	s_add_u32 s28, s28, 0x20000
	s_addc_u32 s29, s29, 0
	s_mov_b32 m0, s33
	v_lshl_add_u64 v[226:227], s[28:29], 0, v[136:137]
	global_load_lds_dwordx4 v[226:227], off
	v_lshl_add_u64 v[226:227], s[28:29], 0, v[132:133]
	s_mov_b32 m0, s34
	s_nop 0
	global_load_lds_dwordx4 v[226:227], off
	v_add_u32_e32 v166, s42, v1
	v_add_u32_e32 v182, s43, v1
	ds_read_b128 v[154:157], v166
	ds_read_b128 v[158:161], v166 offset:1024
	ds_read_b128 v[162:165], v166 offset:2048
	ds_read_b128 v[166:169], v166 offset:3072
	ds_read_b128 v[170:173], v182
	ds_read_b128 v[174:177], v182 offset:1024
	ds_read_b128 v[178:181], v182 offset:2048
	ds_read_b128 v[182:185], v182 offset:3072
	ds_read_b128 v[186:189], v153 offset:32768
	ds_read_b128 v[190:193], v153 offset:33792
	ds_read_b128 v[194:197], v153 offset:34816
	ds_read_b128 v[198:201], v153 offset:35840
	ds_read_b128 v[202:205], v153 offset:36864
	ds_read_b128 v[206:209], v153 offset:37888
	ds_read_b128 v[210:213], v153 offset:38912
	ds_read_b128 v[214:217], v153 offset:39936
	s_waitcnt vmcnt(8)
	s_waitcnt lgkmcnt(0)
	s_barrier
	s_waitcnt lgkmcnt(0)
	v_mfma_f32_16x16x32_bf16 v[126:129], v[154:157], v[186:189], v[126:129]
	v_mfma_f32_16x16x32_bf16 v[122:125], v[162:165], v[186:189], v[122:125]
	v_mfma_f32_16x16x32_bf16 v[110:113], v[154:157], v[194:197], v[110:113]
	v_mfma_f32_16x16x32_bf16 v[106:109], v[162:165], v[194:197], v[106:109]
	v_mfma_f32_16x16x32_bf16 v[94:97], v[154:157], v[202:205], v[94:97]
	v_mfma_f32_16x16x32_bf16 v[90:93], v[162:165], v[202:205], v[90:93]
	v_mfma_f32_16x16x32_bf16 v[78:81], v[154:157], v[210:213], v[78:81]
	v_mfma_f32_16x16x32_bf16 v[74:77], v[162:165], v[210:213], v[74:77]
	v_mfma_f32_16x16x32_bf16 v[126:129], v[158:161], v[190:193], v[126:129]
	v_mfma_f32_16x16x32_bf16 v[122:125], v[166:169], v[190:193], v[122:125]
	v_mfma_f32_16x16x32_bf16 v[110:113], v[158:161], v[198:201], v[110:113]
	v_mfma_f32_16x16x32_bf16 v[106:109], v[166:169], v[198:201], v[106:109]
	v_mfma_f32_16x16x32_bf16 v[94:97], v[158:161], v[206:209], v[94:97]
	v_mfma_f32_16x16x32_bf16 v[90:93], v[166:169], v[206:209], v[90:93]
	v_mfma_f32_16x16x32_bf16 v[78:81], v[158:161], v[214:217], v[78:81]
	v_mfma_f32_16x16x32_bf16 v[74:77], v[166:169], v[214:217], v[74:77]
	v_mfma_f32_16x16x32_bf16 v[118:121], v[170:173], v[186:189], v[118:121]
	v_mfma_f32_16x16x32_bf16 v[114:117], v[178:181], v[186:189], v[114:117]
	v_mfma_f32_16x16x32_bf16 v[102:105], v[170:173], v[194:197], v[102:105]
	v_mfma_f32_16x16x32_bf16 v[98:101], v[178:181], v[194:197], v[98:101]
	v_mfma_f32_16x16x32_bf16 v[86:89], v[170:173], v[202:205], v[86:89]
	v_mfma_f32_16x16x32_bf16 v[82:85], v[178:181], v[202:205], v[82:85]
	v_mfma_f32_16x16x32_bf16 v[70:73], v[170:173], v[210:213], v[70:73]
	v_mfma_f32_16x16x32_bf16 v[66:69], v[178:181], v[210:213], v[66:69]
	v_mfma_f32_16x16x32_bf16 v[118:121], v[174:177], v[190:193], v[118:121]
	v_mfma_f32_16x16x32_bf16 v[114:117], v[182:185], v[190:193], v[114:117]
	v_mfma_f32_16x16x32_bf16 v[102:105], v[174:177], v[198:201], v[102:105]
	v_mfma_f32_16x16x32_bf16 v[98:101], v[182:185], v[198:201], v[98:101]
	v_mfma_f32_16x16x32_bf16 v[86:89], v[174:177], v[206:209], v[86:89]
	v_mfma_f32_16x16x32_bf16 v[82:85], v[182:185], v[206:209], v[82:85]
	v_mfma_f32_16x16x32_bf16 v[70:73], v[174:177], v[214:217], v[70:73]
	v_mfma_f32_16x16x32_bf16 v[66:69], v[182:185], v[214:217], v[66:69]
	s_barrier
; #define PG8_STAGE(bufoff, gbase, voff) do { _Pragma("unroll") for (int _i = 0; _i < 2; ++_i) \
;         __builtin_amdgcn_global_load_lds((const unsigned*)((const char*)(gbase) + (voff)[_i]), (LAS unsigned*)(lds + (bufoff) + ldsw + _i * 8192), 16, 0, 0); } while (0)
; #define PG8_LDA(dst, b, h) do { _Pragma("unroll") for (int m = 0; m < 4; ++m) _Pragma("unroll") for (int k = 0; k < 2; ++k) dst[m][k] = *(const LAS bf16x8*)(lds + PG8_SA(b, h) + aoff + m * 2048 + k * 1024); } while (0)
; #define PG8_MMA(ai, bj, At, Bt) do { __builtin_amdgcn_s_setprio(1); _Pragma("unroll") for (int m = 0; m < 4; ++m) _Pragma("unroll") for (int n = 0; n < 2; ++n) _Pragma("unroll") for (int k = 0; k < 2; ++k) \
;         acc[ai][bj][m][n] = __builtin_amdgcn_mfma_f32_16x16x32_bf16(Bt[n][k], At[m][k], acc[ai][bj][m][n], 0, 0, 0); __builtin_amdgcn_s_setprio(0); } while (0)
; #define PG8_WAIT_V(n) asm volatile("s_waitcnt vmcnt(" #n ")" ::: "memory")
; #define PG8_WAIT_L(n) asm volatile("s_waitcnt lgkmcnt(" #n ")" ::: "memory")
; #define PG8_BAR __builtin_amdgcn_s_barrier()
; #define PG8_SCHED __builtin_amdgcn_sched_barrier(0)
; template <class Epi, bool ALIGN_EPI>
; __device__ __forceinline__ void gemm_phase(LAS unsigned char* lds, const Gemm g, const StaticOrder& S, const Epi& E) {
;     ...
;             PG8_LDA(At, 1, 1); PG8_STAGE(PG8_SB(1, 0), b3, voffB); PG8_STAGE(PG8_SB(1, 1), b3 + hsB, voffB); PG8_STAGE(PG8_SA(1, 0), a3, voffA);
;             PG8_WAIT_V(8); PG8_WAIT_L(0); PG8_BAR; PG8_MMA(1, 0, At, B0); PG8_MMA(1, 1, At, B1); PG8_BAR; PG8_SCHED;
;         }
	s_add_i32 s28, s42, s15
	v_lshl_add_u64 v[218:219], v[218:219], 0, s[8:9]
	s_mov_b32 m0, s28
	s_nop 0
	global_load_lds_dwordx4 v[218:219], off
	s_add_i32 m0, s28, 0x2000
	s_add_u32 s26, s26, 0x20080
	v_lshl_add_u64 v[218:219], v[220:221], 0, s[8:9]
	s_addc_u32 s27, s27, 0
	s_add_i32 s28, s43, s15
	global_load_lds_dwordx4 v[218:219], off
	v_lshl_add_u64 v[218:219], s[26:27], 0, v[134:135]
	s_mov_b32 m0, s28
	s_nop 0
	global_load_lds_dwordx4 v[218:219], off
	v_lshl_add_u64 v[218:219], s[26:27], 0, v[130:131]
	s_add_i32 m0, s28, 0x2000
	s_nop 0
	global_load_lds_dwordx4 v[218:219], off
	v_lshl_add_u64 v[218:219], v[222:223], 0, s[8:9]
	s_mov_b32 m0, s36
	s_nop 0
	global_load_lds_dwordx4 v[218:219], off
	v_lshl_add_u64 v[218:219], v[224:225], 0, s[8:9]
	s_mov_b32 m0, s37
	s_nop 0
	global_load_lds_dwordx4 v[218:219], off
	ds_read_b128 v[186:189], v153 offset:49152
	ds_read_b128 v[190:193], v153 offset:50176
	ds_read_b128 v[194:197], v153 offset:51200
	ds_read_b128 v[198:201], v153 offset:52224
	ds_read_b128 v[202:205], v153 offset:53248
	ds_read_b128 v[206:209], v153 offset:54272
	ds_read_b128 v[210:213], v153 offset:55296
	ds_read_b128 v[214:217], v153 offset:56320
	s_waitcnt vmcnt(8)
	s_waitcnt lgkmcnt(0)
	s_barrier
	s_waitcnt lgkmcnt(0)
	v_mfma_f32_16x16x32_bf16 v[62:65], v[154:157], v[186:189], v[62:65]
	v_mfma_f32_16x16x32_bf16 v[58:61], v[162:165], v[186:189], v[58:61]
	v_mfma_f32_16x16x32_bf16 v[46:49], v[154:157], v[194:197], v[46:49]
	v_mfma_f32_16x16x32_bf16 v[42:45], v[162:165], v[194:197], v[42:45]
	v_mfma_f32_16x16x32_bf16 v[30:33], v[154:157], v[202:205], v[30:33]
	v_mfma_f32_16x16x32_bf16 v[26:29], v[162:165], v[202:205], v[26:29]
	v_mfma_f32_16x16x32_bf16 v[14:17], v[154:157], v[210:213], v[14:17]
	v_mfma_f32_16x16x32_bf16 v[10:13], v[162:165], v[210:213], v[10:13]
	v_mfma_f32_16x16x32_bf16 v[62:65], v[158:161], v[190:193], v[62:65]
	v_mfma_f32_16x16x32_bf16 v[58:61], v[166:169], v[190:193], v[58:61]
	v_mfma_f32_16x16x32_bf16 v[46:49], v[158:161], v[198:201], v[46:49]
	v_mfma_f32_16x16x32_bf16 v[42:45], v[166:169], v[198:201], v[42:45]
	v_mfma_f32_16x16x32_bf16 v[30:33], v[158:161], v[206:209], v[30:33]
	v_mfma_f32_16x16x32_bf16 v[26:29], v[166:169], v[206:209], v[26:29]
	v_mfma_f32_16x16x32_bf16 v[14:17], v[158:161], v[214:217], v[14:17]
	v_mfma_f32_16x16x32_bf16 v[10:13], v[166:169], v[214:217], v[10:13]
	v_mfma_f32_16x16x32_bf16 v[54:57], v[170:173], v[186:189], v[54:57]
	v_mfma_f32_16x16x32_bf16 v[50:53], v[178:181], v[186:189], v[50:53]
	v_mfma_f32_16x16x32_bf16 v[38:41], v[170:173], v[194:197], v[38:41]
	v_mfma_f32_16x16x32_bf16 v[34:37], v[178:181], v[194:197], v[34:37]
	v_mfma_f32_16x16x32_bf16 v[22:25], v[170:173], v[202:205], v[22:25]
	v_mfma_f32_16x16x32_bf16 v[18:21], v[178:181], v[202:205], v[18:21]
	v_mfma_f32_16x16x32_bf16 v[6:9], v[170:173], v[210:213], v[6:9]
	v_mfma_f32_16x16x32_bf16 v[2:5], v[178:181], v[210:213], v[2:5]
	v_mfma_f32_16x16x32_bf16 v[54:57], v[174:177], v[190:193], v[54:57]
	v_mfma_f32_16x16x32_bf16 v[50:53], v[182:185], v[190:193], v[50:53]
	v_mfma_f32_16x16x32_bf16 v[38:41], v[174:177], v[198:201], v[38:41]
	v_mfma_f32_16x16x32_bf16 v[34:37], v[182:185], v[198:201], v[34:37]
	v_mfma_f32_16x16x32_bf16 v[22:25], v[174:177], v[206:209], v[22:25]
	v_mfma_f32_16x16x32_bf16 v[18:21], v[182:185], v[206:209], v[18:21]
	v_mfma_f32_16x16x32_bf16 v[6:9], v[174:177], v[214:217], v[6:9]
	v_mfma_f32_16x16x32_bf16 v[2:5], v[182:185], v[214:217], v[2:5]
	s_barrier
	s_add_i32 s21, s21, 2
	s_add_u32 s24, s24, 0x100
	s_addc_u32 s25, s25, 0
	s_add_u32 s17, s17, 0x100
	s_addc_u32 s19, s19, 0
	s_cmp_gt_u32 s21, 5
	s_cbranch_scc0 .LBB0_948
	s_and_b64 vcc, exec, s[10:11]
	s_cbranch_vccz .LBB0_951
	s_barrier

; #define PG8_STAGE(bufoff, gbase, voff) do { _Pragma("unroll") for (int _i = 0; _i < 2; ++_i) \
;         __builtin_amdgcn_global_load_lds((const unsigned*)((const char*)(gbase) + (voff)[_i]), (LAS unsigned*)(lds + (bufoff) + ldsw + _i * 8192), 16, 0, 0); } while (0)
; #define PG8_LDA(dst, b, h) do { _Pragma("unroll") for (int m = 0; m < 4; ++m) _Pragma("unroll") for (int k = 0; k < 2; ++k) dst[m][k] = *(const LAS bf16x8*)(lds + PG8_SA(b, h) + aoff + m * 2048 + k * 1024); } while (0)
; #define PG8_LDB(dst, b, h) do { _Pragma("unroll") for (int n = 0; n < 2; ++n) _Pragma("unroll") for (int k = 0; k < 2; ++k) dst[n][k] = *(const LAS bf16x8*)(lds + PG8_SB(b, h) + boff + n * 2048 + k * 1024); } while (0)
; #define PG8_MMA(ai, bj, At, Bt) do { __builtin_amdgcn_s_setprio(1); _Pragma("unroll") for (int m = 0; m < 4; ++m) _Pragma("unroll") for (int n = 0; n < 2; ++n) _Pragma("unroll") for (int k = 0; k < 2; ++k) \
;         acc[ai][bj][m][n] = __builtin_amdgcn_mfma_f32_16x16x32_bf16(Bt[n][k], At[m][k], acc[ai][bj][m][n], 0, 0, 0); __builtin_amdgcn_s_setprio(0); } while (0)
; #define PG8_WAIT_V(n) asm volatile("s_waitcnt vmcnt(" #n ")" ::: "memory")
; #define PG8_WAIT_L(n) asm volatile("s_waitcnt lgkmcnt(" #n ")" ::: "memory")
; #define PG8_BAR __builtin_amdgcn_s_barrier()
; #define PG8_SCHED __builtin_amdgcn_sched_barrier(0)
; template <class Epi, bool ALIGN_EPI>
; __device__ __forceinline__ void gemm_phase(LAS unsigned char* lds, const Gemm g, const StaticOrder& S, const Epi& E) {
;     ...
;         for (int t = 0; t < nt; t += 2) {
;             const bool last = (t == nt - 2);
;             const char* a1 = cA + (size_t)(t + 1) * kstepA;
;             const char* a2 = last ? nA : cA + (size_t)(t + 2) * kstepA; const char* b2 = last ? nB : cB + (size_t)(t + 2) * kstep;
;             const char* a3 = a2 + kstepA; const char* b3 = b2 + kstep;
;             PG8_LDB(B0, 0, 0); PG8_LDB(B1, 0, 1); PG8_SCHED; PG8_LDA(At, 0, 0); PG8_STAGE(PG8_SA(1, 1), a1 + hsA, voffA);
;             PG8_WAIT_V(8); PG8_WAIT_L(0); PG8_BAR; PG8_MMA(0, 0, At, B0); PG8_MMA(0, 1, At, B1); PG8_BAR; PG8_SCHED;
;             PG8_LDA(At, 0, 1); PG8_STAGE(PG8_SB(0, 0), b2, voffB); PG8_STAGE(PG8_SB(0, 1), b2 + hsB, voffB); PG8_STAGE(PG8_SA(0, 0), a2, voffA);
.LBB0_1027:
	s_add_u32 s30, s26, 0xfffe0080
	s_addc_u32 s31, s27, -1
	s_cmp_eq_u32 s51, 4
	s_cselect_b32 s35, s9, s31
	s_cselect_b32 s34, s47, s30
	s_cselect_b32 s31, s21, s50
	s_cselect_b32 s30, s48, s49
	v_lshl_add_u64 v[194:195], s[26:27], 0, v[206:207]
	s_add_i32 m0, s25, 0xc000
	s_nop 0
	global_load_lds_dwordx4 v[194:195], off
	v_lshl_add_u64 v[194:195], s[26:27], 0, v[208:209]
	s_add_i32 m0, s25, 0xe000
	s_nop 0
	global_load_lds_dwordx4 v[194:195], off
	ds_read_b128 v[74:77], v232
	ds_read_b128 v[82:85], v232 offset:1024
	ds_read_b128 v[90:93], v232 offset:2048
	ds_read_b128 v[98:101], v232 offset:3072
	ds_read_b128 v[106:109], v233
	ds_read_b128 v[114:117], v233 offset:1024
	ds_read_b128 v[130:133], v233 offset:2048
	ds_read_b128 v[138:141], v233 offset:3072
	ds_read_b128 v[154:157], v234
	ds_read_b128 v[166:169], v234 offset:1024
	ds_read_b128 v[170:173], v234 offset:2048
	ds_read_b128 v[174:177], v234 offset:3072
	ds_read_b128 v[178:181], v234 offset:4096
	ds_read_b128 v[182:185], v234 offset:5120
	ds_read_b128 v[186:189], v234 offset:6144
	ds_read_b128 v[190:193], v234 offset:7168
	s_waitcnt vmcnt(8)
	s_waitcnt lgkmcnt(0)
	s_barrier
	s_waitcnt lgkmcnt(0)
	v_mfma_f32_16x16x32_bf16 v[162:165], v[74:77], v[154:157], v[162:165]
	v_mfma_f32_16x16x32_bf16 v[158:161], v[90:93], v[154:157], v[158:161]
	v_mfma_f32_16x16x32_bf16 v[142:145], v[74:77], v[170:173], v[142:145]
	v_mfma_f32_16x16x32_bf16 v[134:137], v[90:93], v[170:173], v[134:137]
	v_mfma_f32_16x16x32_bf16 v[118:121], v[74:77], v[178:181], v[118:121]
	v_mfma_f32_16x16x32_bf16 v[110:113], v[90:93], v[178:181], v[110:113]
	v_mfma_f32_16x16x32_bf16 v[86:89], v[74:77], v[186:189], v[86:89]
	v_mfma_f32_16x16x32_bf16 v[78:81], v[90:93], v[186:189], v[78:81]
	v_mfma_f32_16x16x32_bf16 v[162:165], v[82:85], v[166:169], v[162:165]
	v_mfma_f32_16x16x32_bf16 v[158:161], v[98:101], v[166:169], v[158:161]
	v_mfma_f32_16x16x32_bf16 v[142:145], v[82:85], v[174:177], v[142:145]
	v_mfma_f32_16x16x32_bf16 v[134:137], v[98:101], v[174:177], v[134:137]
	v_mfma_f32_16x16x32_bf16 v[118:121], v[82:85], v[182:185], v[118:121]
	v_mfma_f32_16x16x32_bf16 v[110:113], v[98:101], v[182:185], v[110:113]
	v_mfma_f32_16x16x32_bf16 v[86:89], v[82:85], v[190:193], v[86:89]
	v_mfma_f32_16x16x32_bf16 v[78:81], v[98:101], v[190:193], v[78:81]
	v_mfma_f32_16x16x32_bf16 v[150:153], v[106:109], v[154:157], v[150:153]
	v_mfma_f32_16x16x32_bf16 v[146:149], v[130:133], v[154:157], v[146:149]
	v_mfma_f32_16x16x32_bf16 v[126:129], v[106:109], v[170:173], v[126:129]
	v_mfma_f32_16x16x32_bf16 v[122:125], v[130:133], v[170:173], v[122:125]
	v_mfma_f32_16x16x32_bf16 v[102:105], v[106:109], v[178:181], v[102:105]
	v_mfma_f32_16x16x32_bf16 v[94:97], v[130:133], v[178:181], v[94:97]
	v_mfma_f32_16x16x32_bf16 v[70:73], v[106:109], v[186:189], v[70:73]
	v_mfma_f32_16x16x32_bf16 v[66:69], v[130:133], v[186:189], v[66:69]
	v_mfma_f32_16x16x32_bf16 v[150:153], v[114:117], v[166:169], v[150:153]
	v_mfma_f32_16x16x32_bf16 v[146:149], v[138:141], v[166:169], v[146:149]
	v_mfma_f32_16x16x32_bf16 v[126:129], v[114:117], v[174:177], v[126:129]
	v_mfma_f32_16x16x32_bf16 v[122:125], v[138:141], v[174:177], v[122:125]
	v_mfma_f32_16x16x32_bf16 v[102:105], v[114:117], v[182:185], v[102:105]
	v_mfma_f32_16x16x32_bf16 v[94:97], v[138:141], v[182:185], v[94:97]
	v_mfma_f32_16x16x32_bf16 v[70:73], v[114:117], v[190:193], v[70:73]
	v_mfma_f32_16x16x32_bf16 v[66:69], v[138:141], v[190:193], v[66:69]
	s_barrier
	s_add_i32 s52, s44, s33
	v_lshl_add_u64 v[194:195], s[30:31], 0, v[200:201]
	s_mov_b32 m0, s52
	s_nop 0
	global_load_lds_dwordx4 v[194:195], off
	s_add_i32 m0, s52, 0x2000
	s_add_u32 s52, s30, 0x20000
	v_lshl_add_u64 v[196:197], s[30:31], 0, v[204:205]
	s_addc_u32 s53, s31, 0
	s_add_i32 s54, s45, s33
	global_load_lds_dwordx4 v[196:197], off
	v_lshl_add_u64 v[214:215], s[52:53], 0, v[200:201]
	s_mov_b32 m0, s54
	v_lshl_add_u64 v[216:217], s[34:35], 0, v[202:203]
	global_load_lds_dwordx4 v[214:215], off
	v_lshl_add_u64 v[214:215], s[52:53], 0, v[204:205]
	s_add_i32 m0, s54, 0x2000
	s_nop 0
	global_load_lds_dwordx4 v[214:215], off
	v_lshl_add_u64 v[214:215], s[34:35], 0, v[198:199]
	s_mov_b32 m0, s25
	s_nop 0
	global_load_lds_dwordx4 v[214:215], off
	s_mov_b32 m0, s36
	s_nop 0
	global_load_lds_dwordx4 v[216:217], off
	ds_read_b128 v[154:157], v234 offset:16384
	ds_read_b128 v[166:169], v234 offset:17408
	ds_read_b128 v[170:173], v234 offset:18432
	ds_read_b128 v[174:177], v234 offset:19456
	ds_read_b128 v[178:181], v234 offset:20480
	ds_read_b128 v[182:185], v234 offset:21504
	ds_read_b128 v[186:189], v234 offset:22528
	ds_read_b128 v[190:193], v234 offset:23552
	s_waitcnt vmcnt(8)
	s_waitcnt lgkmcnt(0)
	s_barrier
; #define PG8_STAGE(bufoff, gbase, voff) do { _Pragma("unroll") for (int _i = 0; _i < 2; ++_i) \
;         __builtin_amdgcn_global_load_lds((const unsigned*)((const char*)(gbase) + (voff)[_i]), (LAS unsigned*)(lds + (bufoff) + ldsw + _i * 8192), 16, 0, 0); } while (0)
; #define PG8_LDA(dst, b, h) do { _Pragma("unroll") for (int m = 0; m < 4; ++m) _Pragma("unroll") for (int k = 0; k < 2; ++k) dst[m][k] = *(const LAS bf16x8*)(lds + PG8_SA(b, h) + aoff + m * 2048 + k * 1024); } while (0)
; #define PG8_LDB(dst, b, h) do { _Pragma("unroll") for (int n = 0; n < 2; ++n) _Pragma("unroll") for (int k = 0; k < 2; ++k) dst[n][k] = *(const LAS bf16x8*)(lds + PG8_SB(b, h) + boff + n * 2048 + k * 1024); } while (0)
; #define PG8_MMA(ai, bj, At, Bt) do { __builtin_amdgcn_s_setprio(1); _Pragma("unroll") for (int m = 0; m < 4; ++m) _Pragma("unroll") for (int n = 0; n < 2; ++n) _Pragma("unroll") for (int k = 0; k < 2; ++k) \
;         acc[ai][bj][m][n] = __builtin_amdgcn_mfma_f32_16x16x32_bf16(Bt[n][k], At[m][k], acc[ai][bj][m][n], 0, 0, 0); __builtin_amdgcn_s_setprio(0); } while (0)
; #define PG8_WAIT_V(n) asm volatile("s_waitcnt vmcnt(" #n ")" ::: "memory")
; #define PG8_WAIT_L(n) asm volatile("s_waitcnt lgkmcnt(" #n ")" ::: "memory")
; #define PG8_BAR __builtin_amdgcn_s_barrier()
; #define PG8_SCHED __builtin_amdgcn_sched_barrier(0)
; template <class Epi, bool ALIGN_EPI>
; __device__ __forceinline__ void gemm_phase(LAS unsigned char* lds, const Gemm g, const StaticOrder& S, const Epi& E) {
;     ...
;             PG8_WAIT_V(8); PG8_WAIT_L(0); PG8_BAR; PG8_MMA(1, 0, At, B0); PG8_MMA(1, 1, At, B1); PG8_BAR; PG8_SCHED;
;             PG8_LDB(B0, 1, 0); PG8_LDB(B1, 1, 1); PG8_SCHED; PG8_LDA(At, 1, 0); PG8_STAGE(PG8_SA(0, 1), a2 + hsA, voffA);
;             PG8_WAIT_V(8); PG8_WAIT_L(0); PG8_BAR; PG8_MMA(0, 0, At, B0); PG8_MMA(0, 1, At, B1); PG8_BAR; PG8_SCHED;
	s_waitcnt lgkmcnt(0)
	v_mfma_f32_16x16x32_bf16 v[62:65], v[74:77], v[154:157], v[62:65]
	v_mfma_f32_16x16x32_bf16 v[58:61], v[90:93], v[154:157], v[58:61]
	v_mfma_f32_16x16x32_bf16 v[46:49], v[74:77], v[170:173], v[46:49]
	v_mfma_f32_16x16x32_bf16 v[42:45], v[90:93], v[170:173], v[42:45]
	v_mfma_f32_16x16x32_bf16 v[30:33], v[74:77], v[178:181], v[30:33]
	v_mfma_f32_16x16x32_bf16 v[26:29], v[90:93], v[178:181], v[26:29]
	v_mfma_f32_16x16x32_bf16 v[14:17], v[74:77], v[186:189], v[14:17]
	v_mfma_f32_16x16x32_bf16 v[10:13], v[90:93], v[186:189], v[10:13]
	v_mfma_f32_16x16x32_bf16 v[62:65], v[82:85], v[166:169], v[62:65]
	v_mfma_f32_16x16x32_bf16 v[58:61], v[98:101], v[166:169], v[58:61]
	v_mfma_f32_16x16x32_bf16 v[46:49], v[82:85], v[174:177], v[46:49]
	v_mfma_f32_16x16x32_bf16 v[42:45], v[98:101], v[174:177], v[42:45]
	v_mfma_f32_16x16x32_bf16 v[30:33], v[82:85], v[182:185], v[30:33]
	v_mfma_f32_16x16x32_bf16 v[26:29], v[98:101], v[182:185], v[26:29]
	v_mfma_f32_16x16x32_bf16 v[14:17], v[82:85], v[190:193], v[14:17]
	v_mfma_f32_16x16x32_bf16 v[10:13], v[98:101], v[190:193], v[10:13]
	v_mfma_f32_16x16x32_bf16 v[54:57], v[106:109], v[154:157], v[54:57]
	v_mfma_f32_16x16x32_bf16 v[50:53], v[130:133], v[154:157], v[50:53]
	v_mfma_f32_16x16x32_bf16 v[38:41], v[106:109], v[170:173], v[38:41]
	v_mfma_f32_16x16x32_bf16 v[34:37], v[130:133], v[170:173], v[34:37]
	v_mfma_f32_16x16x32_bf16 v[22:25], v[106:109], v[178:181], v[22:25]
	v_mfma_f32_16x16x32_bf16 v[18:21], v[130:133], v[178:181], v[18:21]
	v_mfma_f32_16x16x32_bf16 v[6:9], v[106:109], v[186:189], v[6:9]
	v_mfma_f32_16x16x32_bf16 v[2:5], v[130:133], v[186:189], v[2:5]
	v_mfma_f32_16x16x32_bf16 v[54:57], v[114:117], v[166:169], v[54:57]
	v_mfma_f32_16x16x32_bf16 v[50:53], v[138:141], v[166:169], v[50:53]
	v_mfma_f32_16x16x32_bf16 v[38:41], v[114:117], v[174:177], v[38:41]
	v_mfma_f32_16x16x32_bf16 v[34:37], v[138:141], v[174:177], v[34:37]
	v_mfma_f32_16x16x32_bf16 v[22:25], v[114:117], v[182:185], v[22:25]
	v_mfma_f32_16x16x32_bf16 v[18:21], v[138:141], v[182:185], v[18:21]
	v_mfma_f32_16x16x32_bf16 v[6:9], v[114:117], v[190:193], v[6:9]
	v_mfma_f32_16x16x32_bf16 v[2:5], v[138:141], v[190:193], v[2:5]
	s_barrier
	s_add_i32 s52, 0, 0x18000
	s_add_i32 s53, 0, 0x1c000
	s_add_u32 s34, s34, 0x20000
	s_addc_u32 s35, s35, 0
	s_mov_b32 m0, s37
	v_lshl_add_u64 v[218:219], s[34:35], 0, v[198:199]
	global_load_lds_dwordx4 v[218:219], off
	v_lshl_add_u64 v[218:219], s[34:35], 0, v[202:203]
	s_mov_b32 m0, s38
	s_nop 0
	global_load_lds_dwordx4 v[218:219], off
	v_add_u32_e32 v98, s52, v230
	v_add_u32_e32 v138, s53, v230
	ds_read_b128 v[74:77], v98
	ds_read_b128 v[82:85], v98 offset:1024
	ds_read_b128 v[90:93], v98 offset:2048
	ds_read_b128 v[98:101], v98 offset:3072
	ds_read_b128 v[106:109], v138
	ds_read_b128 v[114:117], v138 offset:1024
	ds_read_b128 v[130:133], v138 offset:2048
	ds_read_b128 v[138:141], v138 offset:3072
	ds_read_b128 v[154:157], v234 offset:32768
	ds_read_b128 v[166:169], v234 offset:33792
	ds_read_b128 v[170:173], v234 offset:34816
	ds_read_b128 v[174:177], v234 offset:35840
	ds_read_b128 v[178:181], v234 offset:36864
	ds_read_b128 v[182:185], v234 offset:37888
	ds_read_b128 v[186:189], v234 offset:38912
	ds_read_b128 v[190:193], v234 offset:39936
	s_waitcnt vmcnt(8)
	s_waitcnt lgkmcnt(0)
	s_barrier
	s_waitcnt lgkmcnt(0)
	v_mfma_f32_16x16x32_bf16 v[162:165], v[74:77], v[154:157], v[162:165]
	v_mfma_f32_16x16x32_bf16 v[158:161], v[90:93], v[154:157], v[158:161]
	v_mfma_f32_16x16x32_bf16 v[142:145], v[74:77], v[170:173], v[142:145]
	v_mfma_f32_16x16x32_bf16 v[134:137], v[90:93], v[170:173], v[134:137]
	v_mfma_f32_16x16x32_bf16 v[118:121], v[74:77], v[178:181], v[118:121]
	v_mfma_f32_16x16x32_bf16 v[110:113], v[90:93], v[178:181], v[110:113]
	v_mfma_f32_16x16x32_bf16 v[86:89], v[74:77], v[186:189], v[86:89]
	v_mfma_f32_16x16x32_bf16 v[78:81], v[90:93], v[186:189], v[78:81]
	v_mfma_f32_16x16x32_bf16 v[162:165], v[82:85], v[166:169], v[162:165]
	v_mfma_f32_16x16x32_bf16 v[158:161], v[98:101], v[166:169], v[158:161]
	v_mfma_f32_16x16x32_bf16 v[142:145], v[82:85], v[174:177], v[142:145]
	v_mfma_f32_16x16x32_bf16 v[134:137], v[98:101], v[174:177], v[134:137]
	v_mfma_f32_16x16x32_bf16 v[118:121], v[82:85], v[182:185], v[118:121]
	v_mfma_f32_16x16x32_bf16 v[110:113], v[98:101], v[182:185], v[110:113]
	v_mfma_f32_16x16x32_bf16 v[86:89], v[82:85], v[190:193], v[86:89]
	v_mfma_f32_16x16x32_bf16 v[78:81], v[98:101], v[190:193], v[78:81]
	v_mfma_f32_16x16x32_bf16 v[150:153], v[106:109], v[154:157], v[150:153]
	v_mfma_f32_16x16x32_bf16 v[146:149], v[130:133], v[154:157], v[146:149]
	v_mfma_f32_16x16x32_bf16 v[126:129], v[106:109], v[170:173], v[126:129]
	v_mfma_f32_16x16x32_bf16 v[122:125], v[130:133], v[170:173], v[122:125]
	v_mfma_f32_16x16x32_bf16 v[102:105], v[106:109], v[178:181], v[102:105]
	v_mfma_f32_16x16x32_bf16 v[94:97], v[130:133], v[178:181], v[94:97]
	v_mfma_f32_16x16x32_bf16 v[70:73], v[106:109], v[186:189], v[70:73]
	v_mfma_f32_16x16x32_bf16 v[66:69], v[130:133], v[186:189], v[66:69]
	v_mfma_f32_16x16x32_bf16 v[150:153], v[114:117], v[166:169], v[150:153]
	v_mfma_f32_16x16x32_bf16 v[146:149], v[138:141], v[166:169], v[146:149]
	v_mfma_f32_16x16x32_bf16 v[126:129], v[114:117], v[174:177], v[126:129]
	v_mfma_f32_16x16x32_bf16 v[122:125], v[138:141], v[174:177], v[122:125]
	v_mfma_f32_16x16x32_bf16 v[102:105], v[114:117], v[182:185], v[102:105]
	v_mfma_f32_16x16x32_bf16 v[94:97], v[138:141], v[182:185], v[94:97]
	v_mfma_f32_16x16x32_bf16 v[70:73], v[114:117], v[190:193], v[70:73]
	v_mfma_f32_16x16x32_bf16 v[66:69], v[138:141], v[190:193], v[66:69]
	s_barrier
; #define PG8_STAGE(bufoff, gbase, voff) do { _Pragma("unroll") for (int _i = 0; _i < 2; ++_i) \
;         __builtin_amdgcn_global_load_lds((const unsigned*)((const char*)(gbase) + (voff)[_i]), (LAS unsigned*)(lds + (bufoff) + ldsw + _i * 8192), 16, 0, 0); } while (0)
; #define PG8_LDA(dst, b, h) do { _Pragma("unroll") for (int m = 0; m < 4; ++m) _Pragma("unroll") for (int k = 0; k < 2; ++k) dst[m][k] = *(const LAS bf16x8*)(lds + PG8_SA(b, h) + aoff + m * 2048 + k * 1024); } while (0)
; #define PG8_MMA(ai, bj, At, Bt) do { __builtin_amdgcn_s_setprio(1); _Pragma("unroll") for (int m = 0; m < 4; ++m) _Pragma("unroll") for (int n = 0; n < 2; ++n) _Pragma("unroll") for (int k = 0; k < 2; ++k) \
;         acc[ai][bj][m][n] = __builtin_amdgcn_mfma_f32_16x16x32_bf16(Bt[n][k], At[m][k], acc[ai][bj][m][n], 0, 0, 0); __builtin_amdgcn_s_setprio(0); } while (0)
; #define PG8_WAIT_V(n) asm volatile("s_waitcnt vmcnt(" #n ")" ::: "memory")
; #define PG8_WAIT_L(n) asm volatile("s_waitcnt lgkmcnt(" #n ")" ::: "memory")
; #define PG8_BAR __builtin_amdgcn_s_barrier()
; #define PG8_SCHED __builtin_amdgcn_sched_barrier(0)
; template <class Epi, bool ALIGN_EPI>
; __device__ __forceinline__ void gemm_phase(LAS unsigned char* lds, const Gemm g, const StaticOrder& S, const Epi& E) {
;     ...
;             PG8_LDA(At, 1, 1); PG8_STAGE(PG8_SB(1, 0), b3, voffB); PG8_STAGE(PG8_SB(1, 1), b3 + hsB, voffB); PG8_STAGE(PG8_SA(1, 0), a3, voffA);
;             PG8_WAIT_V(8); PG8_WAIT_L(0); PG8_BAR; PG8_MMA(1, 0, At, B0); PG8_MMA(1, 1, At, B1); PG8_BAR; PG8_SCHED;
;         }
	s_add_i32 s34, s52, s33
	v_lshl_add_u64 v[194:195], v[194:195], 0, s[12:13]
	s_mov_b32 m0, s34
	s_nop 0
	global_load_lds_dwordx4 v[194:195], off
	s_add_i32 m0, s34, 0x2000
	s_add_u32 s30, s30, 0x20080
	v_lshl_add_u64 v[194:195], v[196:197], 0, s[12:13]
	s_addc_u32 s31, s31, 0
	s_add_i32 s34, s53, s33
	global_load_lds_dwordx4 v[194:195], off
	v_lshl_add_u64 v[194:195], s[30:31], 0, v[200:201]
	s_mov_b32 m0, s34
	s_nop 0
	global_load_lds_dwordx4 v[194:195], off
	v_lshl_add_u64 v[194:195], s[30:31], 0, v[204:205]
	s_add_i32 m0, s34, 0x2000
	s_nop 0
	global_load_lds_dwordx4 v[194:195], off
	v_lshl_add_u64 v[194:195], v[214:215], 0, s[12:13]
	s_mov_b32 m0, s40
	s_nop 0
	global_load_lds_dwordx4 v[194:195], off
	v_lshl_add_u64 v[194:195], v[216:217], 0, s[12:13]
	s_mov_b32 m0, s41
	s_nop 0
	global_load_lds_dwordx4 v[194:195], off
	ds_read_b128 v[154:157], v234 offset:49152
	ds_read_b128 v[166:169], v234 offset:50176
	ds_read_b128 v[170:173], v234 offset:51200
	ds_read_b128 v[174:177], v234 offset:52224
	ds_read_b128 v[178:181], v234 offset:53248
	ds_read_b128 v[182:185], v234 offset:54272
	ds_read_b128 v[186:189], v234 offset:55296
	ds_read_b128 v[190:193], v234 offset:56320
	s_waitcnt vmcnt(8)
	s_waitcnt lgkmcnt(0)
	s_barrier
	s_waitcnt lgkmcnt(0)
	v_mfma_f32_16x16x32_bf16 v[62:65], v[74:77], v[154:157], v[62:65]
	v_mfma_f32_16x16x32_bf16 v[58:61], v[90:93], v[154:157], v[58:61]
	v_mfma_f32_16x16x32_bf16 v[46:49], v[74:77], v[170:173], v[46:49]
	v_mfma_f32_16x16x32_bf16 v[42:45], v[90:93], v[170:173], v[42:45]
	v_mfma_f32_16x16x32_bf16 v[30:33], v[74:77], v[178:181], v[30:33]
	v_mfma_f32_16x16x32_bf16 v[26:29], v[90:93], v[178:181], v[26:29]
	v_mfma_f32_16x16x32_bf16 v[14:17], v[74:77], v[186:189], v[14:17]
	v_mfma_f32_16x16x32_bf16 v[10:13], v[90:93], v[186:189], v[10:13]
	v_mfma_f32_16x16x32_bf16 v[62:65], v[82:85], v[166:169], v[62:65]
	v_mfma_f32_16x16x32_bf16 v[58:61], v[98:101], v[166:169], v[58:61]
	v_mfma_f32_16x16x32_bf16 v[46:49], v[82:85], v[174:177], v[46:49]
	v_mfma_f32_16x16x32_bf16 v[42:45], v[98:101], v[174:177], v[42:45]
	v_mfma_f32_16x16x32_bf16 v[30:33], v[82:85], v[182:185], v[30:33]
	v_mfma_f32_16x16x32_bf16 v[26:29], v[98:101], v[182:185], v[26:29]
	v_mfma_f32_16x16x32_bf16 v[14:17], v[82:85], v[190:193], v[14:17]
	v_mfma_f32_16x16x32_bf16 v[10:13], v[98:101], v[190:193], v[10:13]
	v_mfma_f32_16x16x32_bf16 v[54:57], v[106:109], v[154:157], v[54:57]
	v_mfma_f32_16x16x32_bf16 v[50:53], v[130:133], v[154:157], v[50:53]
	v_mfma_f32_16x16x32_bf16 v[38:41], v[106:109], v[170:173], v[38:41]
	v_mfma_f32_16x16x32_bf16 v[34:37], v[130:133], v[170:173], v[34:37]
	v_mfma_f32_16x16x32_bf16 v[22:25], v[106:109], v[178:181], v[22:25]
	v_mfma_f32_16x16x32_bf16 v[18:21], v[130:133], v[178:181], v[18:21]
	v_mfma_f32_16x16x32_bf16 v[6:9], v[106:109], v[186:189], v[6:9]
	v_mfma_f32_16x16x32_bf16 v[2:5], v[130:133], v[186:189], v[2:5]
	v_mfma_f32_16x16x32_bf16 v[54:57], v[114:117], v[166:169], v[54:57]
	v_mfma_f32_16x16x32_bf16 v[50:53], v[138:141], v[166:169], v[50:53]
	v_mfma_f32_16x16x32_bf16 v[38:41], v[114:117], v[174:177], v[38:41]
	v_mfma_f32_16x16x32_bf16 v[34:37], v[138:141], v[174:177], v[34:37]
	v_mfma_f32_16x16x32_bf16 v[22:25], v[114:117], v[182:185], v[22:25]
	v_mfma_f32_16x16x32_bf16 v[18:21], v[138:141], v[182:185], v[18:21]
	v_mfma_f32_16x16x32_bf16 v[6:9], v[114:117], v[190:193], v[6:9]
	v_mfma_f32_16x16x32_bf16 v[2:5], v[138:141], v[190:193], v[2:5]
	s_barrier
	s_add_i32 s51, s51, 2
	s_add_u32 s26, s26, 0x100
	s_addc_u32 s27, s27, 0
	s_add_u32 s49, s49, 0x100
	s_addc_u32 s50, s50, 0
	s_cmp_gt_u32 s51, 5
	s_cbranch_scc0 .LBB0_1027
	s_and_b64 vcc, exec, s[14:15]
	s_cbranch_vccz .LBB0_1030
	s_barrier

; #define PG8_STAGE(bufoff, gbase, voff) do { _Pragma("unroll") for (int _i = 0; _i < 2; ++_i) \
;         __builtin_amdgcn_global_load_lds((const unsigned*)((const char*)(gbase) + (voff)[_i]), (LAS unsigned*)(lds + (bufoff) + ldsw + _i * 8192), 16, 0, 0); } while (0)
; #define PG8_LDA(dst, b, h) do { _Pragma("unroll") for (int m = 0; m < 4; ++m) _Pragma("unroll") for (int k = 0; k < 2; ++k) dst[m][k] = *(const LAS bf16x8*)(lds + PG8_SA(b, h) + aoff + m * 2048 + k * 1024); } while (0)
; #define PG8_LDB(dst, b, h) do { _Pragma("unroll") for (int n = 0; n < 2; ++n) _Pragma("unroll") for (int k = 0; k < 2; ++k) dst[n][k] = *(const LAS bf16x8*)(lds + PG8_SB(b, h) + boff + n * 2048 + k * 1024); } while (0)
; #define PG8_MMA(ai, bj, At, Bt) do { __builtin_amdgcn_s_setprio(1); _Pragma("unroll") for (int m = 0; m < 4; ++m) _Pragma("unroll") for (int n = 0; n < 2; ++n) _Pragma("unroll") for (int k = 0; k < 2; ++k) \
;         acc[ai][bj][m][n] = __builtin_amdgcn_mfma_f32_16x16x32_bf16(Bt[n][k], At[m][k], acc[ai][bj][m][n], 0, 0, 0); __builtin_amdgcn_s_setprio(0); } while (0)
; #define PG8_WAIT_V(n) asm volatile("s_waitcnt vmcnt(" #n ")" ::: "memory")
; #define PG8_WAIT_L(n) asm volatile("s_waitcnt lgkmcnt(" #n ")" ::: "memory")
; #define PG8_BAR __builtin_amdgcn_s_barrier()
; #define PG8_SCHED __builtin_amdgcn_sched_barrier(0)
; template <class Epi, bool ALIGN_EPI>
; __device__ __forceinline__ void gemm_phase(LAS unsigned char* lds, const Gemm g, const StaticOrder& S, const Epi& E) {
;     ...
;         for (int t = 0; t < nt; t += 2) {
;             const bool last = (t == nt - 2);
;             const char* a1 = cA + (size_t)(t + 1) * kstepA;
;             const char* a2 = last ? nA : cA + (size_t)(t + 2) * kstepA; const char* b2 = last ? nB : cB + (size_t)(t + 2) * kstep;
;             const char* a3 = a2 + kstepA; const char* b3 = b2 + kstep;
;             PG8_LDB(B0, 0, 0); PG8_LDB(B1, 0, 1); PG8_SCHED; PG8_LDA(At, 0, 0); PG8_STAGE(PG8_SA(1, 1), a1 + hsA, voffA);
;             PG8_WAIT_V(8); PG8_WAIT_L(0); PG8_BAR; PG8_MMA(0, 0, At, B0); PG8_MMA(0, 1, At, B1); PG8_BAR; PG8_SCHED;
;             PG8_LDA(At, 0, 1); PG8_STAGE(PG8_SB(0, 0), b2, voffB); PG8_STAGE(PG8_SB(0, 1), b2 + hsB, voffB); PG8_STAGE(PG8_SA(0, 0), a2, voffA);
.LBB0_1106:
	s_add_u32 s36, s34, 0xfffe0080
	s_addc_u32 s37, s35, -1
	s_cmp_eq_u32 s55, 4
	s_cselect_b32 s39, s23, s37
	s_cselect_b32 s38, s51, s36
	s_cselect_b32 s37, s25, s54
	s_cselect_b32 s36, s52, s53
	v_lshl_add_u64 v[216:217], s[34:35], 0, v[138:139]
	s_add_i32 m0, s31, 0xc000
	s_nop 0
	global_load_lds_dwordx4 v[216:217], off
	v_lshl_add_u64 v[216:217], s[34:35], 0, v[140:141]
	s_add_i32 m0, s31, 0xe000
	s_nop 0
	global_load_lds_dwordx4 v[216:217], off
	ds_read_b128 v[146:149], v160
	ds_read_b128 v[150:153], v160 offset:1024
	ds_read_b128 v[154:157], v160 offset:2048
	ds_read_b128 v[164:167], v160 offset:3072
	ds_read_b128 v[168:171], v161
	ds_read_b128 v[172:175], v161 offset:1024
	ds_read_b128 v[176:179], v161 offset:2048
	ds_read_b128 v[180:183], v161 offset:3072
	ds_read_b128 v[184:187], v162
	ds_read_b128 v[188:191], v162 offset:1024
	ds_read_b128 v[192:195], v162 offset:2048
	ds_read_b128 v[196:199], v162 offset:3072
	ds_read_b128 v[200:203], v162 offset:4096
	ds_read_b128 v[204:207], v162 offset:5120
	ds_read_b128 v[208:211], v162 offset:6144
	ds_read_b128 v[212:215], v162 offset:7168
	s_waitcnt vmcnt(8)
	s_waitcnt lgkmcnt(0)
	s_barrier
	s_waitcnt lgkmcnt(0)
	v_mfma_f32_16x16x32_bf16 v[126:129], v[146:149], v[184:187], v[126:129]
	v_mfma_f32_16x16x32_bf16 v[122:125], v[154:157], v[184:187], v[122:125]
	v_mfma_f32_16x16x32_bf16 v[118:121], v[146:149], v[192:195], v[118:121]
	v_mfma_f32_16x16x32_bf16 v[106:109], v[154:157], v[192:195], v[106:109]
	v_mfma_f32_16x16x32_bf16 v[94:97], v[146:149], v[200:203], v[94:97]
	v_mfma_f32_16x16x32_bf16 v[90:93], v[154:157], v[200:203], v[90:93]
	v_mfma_f32_16x16x32_bf16 v[78:81], v[146:149], v[208:211], v[78:81]
	v_mfma_f32_16x16x32_bf16 v[74:77], v[154:157], v[208:211], v[74:77]
	v_mfma_f32_16x16x32_bf16 v[126:129], v[150:153], v[188:191], v[126:129]
	v_mfma_f32_16x16x32_bf16 v[122:125], v[164:167], v[188:191], v[122:125]
	v_mfma_f32_16x16x32_bf16 v[118:121], v[150:153], v[196:199], v[118:121]
	v_mfma_f32_16x16x32_bf16 v[106:109], v[164:167], v[196:199], v[106:109]
	v_mfma_f32_16x16x32_bf16 v[94:97], v[150:153], v[204:207], v[94:97]
	v_mfma_f32_16x16x32_bf16 v[90:93], v[164:167], v[204:207], v[90:93]
	v_mfma_f32_16x16x32_bf16 v[78:81], v[150:153], v[212:215], v[78:81]
	v_mfma_f32_16x16x32_bf16 v[74:77], v[164:167], v[212:215], v[74:77]
	v_mfma_f32_16x16x32_bf16 v[114:117], v[168:171], v[184:187], v[114:117]
	v_mfma_f32_16x16x32_bf16 v[110:113], v[176:179], v[184:187], v[110:113]
	v_mfma_f32_16x16x32_bf16 v[102:105], v[168:171], v[192:195], v[102:105]
	v_mfma_f32_16x16x32_bf16 v[98:101], v[176:179], v[192:195], v[98:101]
	v_mfma_f32_16x16x32_bf16 v[86:89], v[168:171], v[200:203], v[86:89]
	v_mfma_f32_16x16x32_bf16 v[82:85], v[176:179], v[200:203], v[82:85]
	v_mfma_f32_16x16x32_bf16 v[70:73], v[168:171], v[208:211], v[70:73]
	v_mfma_f32_16x16x32_bf16 v[66:69], v[176:179], v[208:211], v[66:69]
	v_mfma_f32_16x16x32_bf16 v[114:117], v[172:175], v[188:191], v[114:117]
	v_mfma_f32_16x16x32_bf16 v[110:113], v[180:183], v[188:191], v[110:113]
	v_mfma_f32_16x16x32_bf16 v[102:105], v[172:175], v[196:199], v[102:105]
	v_mfma_f32_16x16x32_bf16 v[98:101], v[180:183], v[196:199], v[98:101]
	v_mfma_f32_16x16x32_bf16 v[86:89], v[172:175], v[204:207], v[86:89]
	v_mfma_f32_16x16x32_bf16 v[82:85], v[180:183], v[204:207], v[82:85]
	v_mfma_f32_16x16x32_bf16 v[70:73], v[172:175], v[212:215], v[70:73]
	v_mfma_f32_16x16x32_bf16 v[66:69], v[180:183], v[212:215], v[66:69]
	s_barrier
	s_add_i32 s56, s48, s33
	v_lshl_add_u64 v[216:217], s[36:37], 0, v[132:133]
	s_mov_b32 m0, s56
	s_nop 0
	global_load_lds_dwordx4 v[216:217], off
	s_add_i32 m0, s56, 0x2000
	s_add_u32 s56, s36, 0x20000
	v_lshl_add_u64 v[218:219], s[36:37], 0, v[136:137]
	s_addc_u32 s57, s37, 0
	s_add_i32 s58, s49, s33
	global_load_lds_dwordx4 v[218:219], off
	v_lshl_add_u64 v[220:221], s[56:57], 0, v[132:133]
	s_mov_b32 m0, s58
	v_lshl_add_u64 v[222:223], s[38:39], 0, v[134:135]
	global_load_lds_dwordx4 v[220:221], off
	v_lshl_add_u64 v[220:221], s[56:57], 0, v[136:137]
	s_add_i32 m0, s58, 0x2000
	s_nop 0
	global_load_lds_dwordx4 v[220:221], off
	v_lshl_add_u64 v[220:221], s[38:39], 0, v[130:131]
	s_mov_b32 m0, s31
	s_nop 0
	global_load_lds_dwordx4 v[220:221], off
	s_mov_b32 m0, s40
	s_nop 0
	global_load_lds_dwordx4 v[222:223], off
	ds_read_b128 v[184:187], v162 offset:16384
	ds_read_b128 v[188:191], v162 offset:17408
	ds_read_b128 v[192:195], v162 offset:18432
	ds_read_b128 v[196:199], v162 offset:19456
	ds_read_b128 v[200:203], v162 offset:20480
	ds_read_b128 v[204:207], v162 offset:21504
	ds_read_b128 v[208:211], v162 offset:22528
	ds_read_b128 v[212:215], v162 offset:23552
	s_waitcnt vmcnt(8)
	s_waitcnt lgkmcnt(0)
	s_barrier
; #define PG8_STAGE(bufoff, gbase, voff) do { _Pragma("unroll") for (int _i = 0; _i < 2; ++_i) \
;         __builtin_amdgcn_global_load_lds((const unsigned*)((const char*)(gbase) + (voff)[_i]), (LAS unsigned*)(lds + (bufoff) + ldsw + _i * 8192), 16, 0, 0); } while (0)
; #define PG8_LDA(dst, b, h) do { _Pragma("unroll") for (int m = 0; m < 4; ++m) _Pragma("unroll") for (int k = 0; k < 2; ++k) dst[m][k] = *(const LAS bf16x8*)(lds + PG8_SA(b, h) + aoff + m * 2048 + k * 1024); } while (0)
; #define PG8_LDB(dst, b, h) do { _Pragma("unroll") for (int n = 0; n < 2; ++n) _Pragma("unroll") for (int k = 0; k < 2; ++k) dst[n][k] = *(const LAS bf16x8*)(lds + PG8_SB(b, h) + boff + n * 2048 + k * 1024); } while (0)
; #define PG8_MMA(ai, bj, At, Bt) do { __builtin_amdgcn_s_setprio(1); _Pragma("unroll") for (int m = 0; m < 4; ++m) _Pragma("unroll") for (int n = 0; n < 2; ++n) _Pragma("unroll") for (int k = 0; k < 2; ++k) \
;         acc[ai][bj][m][n] = __builtin_amdgcn_mfma_f32_16x16x32_bf16(Bt[n][k], At[m][k], acc[ai][bj][m][n], 0, 0, 0); __builtin_amdgcn_s_setprio(0); } while (0)
; #define PG8_WAIT_V(n) asm volatile("s_waitcnt vmcnt(" #n ")" ::: "memory")
; #define PG8_WAIT_L(n) asm volatile("s_waitcnt lgkmcnt(" #n ")" ::: "memory")
; #define PG8_BAR __builtin_amdgcn_s_barrier()
; #define PG8_SCHED __builtin_amdgcn_sched_barrier(0)
; template <class Epi, bool ALIGN_EPI>
; __device__ __forceinline__ void gemm_phase(LAS unsigned char* lds, const Gemm g, const StaticOrder& S, const Epi& E) {
;     ...
;             PG8_WAIT_V(8); PG8_WAIT_L(0); PG8_BAR; PG8_MMA(1, 0, At, B0); PG8_MMA(1, 1, At, B1); PG8_BAR; PG8_SCHED;
;             PG8_LDB(B0, 1, 0); PG8_LDB(B1, 1, 1); PG8_SCHED; PG8_LDA(At, 1, 0); PG8_STAGE(PG8_SA(0, 1), a2 + hsA, voffA);
;             PG8_WAIT_V(8); PG8_WAIT_L(0); PG8_BAR; PG8_MMA(0, 0, At, B0); PG8_MMA(0, 1, At, B1); PG8_BAR; PG8_SCHED;
	s_waitcnt lgkmcnt(0)
	v_mfma_f32_16x16x32_bf16 v[62:65], v[146:149], v[184:187], v[62:65]
	v_mfma_f32_16x16x32_bf16 v[58:61], v[154:157], v[184:187], v[58:61]
	v_mfma_f32_16x16x32_bf16 v[46:49], v[146:149], v[192:195], v[46:49]
	v_mfma_f32_16x16x32_bf16 v[42:45], v[154:157], v[192:195], v[42:45]
	v_mfma_f32_16x16x32_bf16 v[30:33], v[146:149], v[200:203], v[30:33]
	v_mfma_f32_16x16x32_bf16 v[26:29], v[154:157], v[200:203], v[26:29]
	v_mfma_f32_16x16x32_bf16 v[14:17], v[146:149], v[208:211], v[14:17]
	v_mfma_f32_16x16x32_bf16 v[10:13], v[154:157], v[208:211], v[10:13]
	v_mfma_f32_16x16x32_bf16 v[62:65], v[150:153], v[188:191], v[62:65]
	v_mfma_f32_16x16x32_bf16 v[58:61], v[164:167], v[188:191], v[58:61]
	v_mfma_f32_16x16x32_bf16 v[46:49], v[150:153], v[196:199], v[46:49]
	v_mfma_f32_16x16x32_bf16 v[42:45], v[164:167], v[196:199], v[42:45]
	v_mfma_f32_16x16x32_bf16 v[30:33], v[150:153], v[204:207], v[30:33]
	v_mfma_f32_16x16x32_bf16 v[26:29], v[164:167], v[204:207], v[26:29]
	v_mfma_f32_16x16x32_bf16 v[14:17], v[150:153], v[212:215], v[14:17]
	v_mfma_f32_16x16x32_bf16 v[10:13], v[164:167], v[212:215], v[10:13]
	v_mfma_f32_16x16x32_bf16 v[54:57], v[168:171], v[184:187], v[54:57]
	v_mfma_f32_16x16x32_bf16 v[50:53], v[176:179], v[184:187], v[50:53]
	v_mfma_f32_16x16x32_bf16 v[38:41], v[168:171], v[192:195], v[38:41]
	v_mfma_f32_16x16x32_bf16 v[34:37], v[176:179], v[192:195], v[34:37]
	v_mfma_f32_16x16x32_bf16 v[22:25], v[168:171], v[200:203], v[22:25]
	v_mfma_f32_16x16x32_bf16 v[18:21], v[176:179], v[200:203], v[18:21]
	v_mfma_f32_16x16x32_bf16 v[6:9], v[168:171], v[208:211], v[6:9]
	v_mfma_f32_16x16x32_bf16 v[2:5], v[176:179], v[208:211], v[2:5]
	v_mfma_f32_16x16x32_bf16 v[54:57], v[172:175], v[188:191], v[54:57]
	v_mfma_f32_16x16x32_bf16 v[50:53], v[180:183], v[188:191], v[50:53]
	v_mfma_f32_16x16x32_bf16 v[38:41], v[172:175], v[196:199], v[38:41]
	v_mfma_f32_16x16x32_bf16 v[34:37], v[180:183], v[196:199], v[34:37]
	v_mfma_f32_16x16x32_bf16 v[22:25], v[172:175], v[204:207], v[22:25]
	v_mfma_f32_16x16x32_bf16 v[18:21], v[180:183], v[204:207], v[18:21]
	v_mfma_f32_16x16x32_bf16 v[6:9], v[172:175], v[212:215], v[6:9]
	v_mfma_f32_16x16x32_bf16 v[2:5], v[180:183], v[212:215], v[2:5]
	s_barrier
	s_add_i32 s56, 0, 0x18000
	s_add_i32 s57, 0, 0x1c000
	s_add_u32 s38, s38, 0x20000
	s_addc_u32 s39, s39, 0
	s_mov_b32 m0, s41
	v_lshl_add_u64 v[224:225], s[38:39], 0, v[130:131]
	global_load_lds_dwordx4 v[224:225], off
	v_lshl_add_u64 v[224:225], s[38:39], 0, v[134:135]
	s_mov_b32 m0, s42
	s_nop 0
	global_load_lds_dwordx4 v[224:225], off
	v_add_u32_e32 v163, s56, v158
	ds_read_b128 v[146:149], v163
	ds_read_b128 v[150:153], v163 offset:1024
	ds_read_b128 v[154:157], v163 offset:2048
	ds_read_b128 v[164:167], v163 offset:3072
	v_add_u32_e32 v163, s57, v158
	ds_read_b128 v[168:171], v163
	ds_read_b128 v[172:175], v163 offset:1024
	ds_read_b128 v[176:179], v163 offset:2048
	ds_read_b128 v[180:183], v163 offset:3072
	ds_read_b128 v[184:187], v162 offset:32768
	ds_read_b128 v[188:191], v162 offset:33792
	ds_read_b128 v[192:195], v162 offset:34816
	ds_read_b128 v[196:199], v162 offset:35840
	ds_read_b128 v[200:203], v162 offset:36864
	ds_read_b128 v[204:207], v162 offset:37888
	ds_read_b128 v[208:211], v162 offset:38912
	ds_read_b128 v[212:215], v162 offset:39936
	s_waitcnt vmcnt(8)
	s_waitcnt lgkmcnt(0)
	s_barrier
	s_waitcnt lgkmcnt(0)
	v_mfma_f32_16x16x32_bf16 v[126:129], v[146:149], v[184:187], v[126:129]
	v_mfma_f32_16x16x32_bf16 v[122:125], v[154:157], v[184:187], v[122:125]
	v_mfma_f32_16x16x32_bf16 v[118:121], v[146:149], v[192:195], v[118:121]
	v_mfma_f32_16x16x32_bf16 v[106:109], v[154:157], v[192:195], v[106:109]
	v_mfma_f32_16x16x32_bf16 v[94:97], v[146:149], v[200:203], v[94:97]
	v_mfma_f32_16x16x32_bf16 v[90:93], v[154:157], v[200:203], v[90:93]
	v_mfma_f32_16x16x32_bf16 v[78:81], v[146:149], v[208:211], v[78:81]
	v_mfma_f32_16x16x32_bf16 v[74:77], v[154:157], v[208:211], v[74:77]
	v_mfma_f32_16x16x32_bf16 v[126:129], v[150:153], v[188:191], v[126:129]
	v_mfma_f32_16x16x32_bf16 v[122:125], v[164:167], v[188:191], v[122:125]
	v_mfma_f32_16x16x32_bf16 v[118:121], v[150:153], v[196:199], v[118:121]
	v_mfma_f32_16x16x32_bf16 v[106:109], v[164:167], v[196:199], v[106:109]
	v_mfma_f32_16x16x32_bf16 v[94:97], v[150:153], v[204:207], v[94:97]
	v_mfma_f32_16x16x32_bf16 v[90:93], v[164:167], v[204:207], v[90:93]
	v_mfma_f32_16x16x32_bf16 v[78:81], v[150:153], v[212:215], v[78:81]
	v_mfma_f32_16x16x32_bf16 v[74:77], v[164:167], v[212:215], v[74:77]
	v_mfma_f32_16x16x32_bf16 v[114:117], v[168:171], v[184:187], v[114:117]
	v_mfma_f32_16x16x32_bf16 v[110:113], v[176:179], v[184:187], v[110:113]
	v_mfma_f32_16x16x32_bf16 v[102:105], v[168:171], v[192:195], v[102:105]
	v_mfma_f32_16x16x32_bf16 v[98:101], v[176:179], v[192:195], v[98:101]
	v_mfma_f32_16x16x32_bf16 v[86:89], v[168:171], v[200:203], v[86:89]
	v_mfma_f32_16x16x32_bf16 v[82:85], v[176:179], v[200:203], v[82:85]
	v_mfma_f32_16x16x32_bf16 v[70:73], v[168:171], v[208:211], v[70:73]
	v_mfma_f32_16x16x32_bf16 v[66:69], v[176:179], v[208:211], v[66:69]
	v_mfma_f32_16x16x32_bf16 v[114:117], v[172:175], v[188:191], v[114:117]
	v_mfma_f32_16x16x32_bf16 v[110:113], v[180:183], v[188:191], v[110:113]
	v_mfma_f32_16x16x32_bf16 v[102:105], v[172:175], v[196:199], v[102:105]
	v_mfma_f32_16x16x32_bf16 v[98:101], v[180:183], v[196:199], v[98:101]
	v_mfma_f32_16x16x32_bf16 v[86:89], v[172:175], v[204:207], v[86:89]
	v_mfma_f32_16x16x32_bf16 v[82:85], v[180:183], v[204:207], v[82:85]
	v_mfma_f32_16x16x32_bf16 v[70:73], v[172:175], v[212:215], v[70:73]
	v_mfma_f32_16x16x32_bf16 v[66:69], v[180:183], v[212:215], v[66:69]
	s_barrier
; #define PG8_STAGE(bufoff, gbase, voff) do { _Pragma("unroll") for (int _i = 0; _i < 2; ++_i) \
;         __builtin_amdgcn_global_load_lds((const unsigned*)((const char*)(gbase) + (voff)[_i]), (LAS unsigned*)(lds + (bufoff) + ldsw + _i * 8192), 16, 0, 0); } while (0)
; #define PG8_LDA(dst, b, h) do { _Pragma("unroll") for (int m = 0; m < 4; ++m) _Pragma("unroll") for (int k = 0; k < 2; ++k) dst[m][k] = *(const LAS bf16x8*)(lds + PG8_SA(b, h) + aoff + m * 2048 + k * 1024); } while (0)
; #define PG8_MMA(ai, bj, At, Bt) do { __builtin_amdgcn_s_setprio(1); _Pragma("unroll") for (int m = 0; m < 4; ++m) _Pragma("unroll") for (int n = 0; n < 2; ++n) _Pragma("unroll") for (int k = 0; k < 2; ++k) \
;         acc[ai][bj][m][n] = __builtin_amdgcn_mfma_f32_16x16x32_bf16(Bt[n][k], At[m][k], acc[ai][bj][m][n], 0, 0, 0); __builtin_amdgcn_s_setprio(0); } while (0)
; #define PG8_WAIT_V(n) asm volatile("s_waitcnt vmcnt(" #n ")" ::: "memory")
; #define PG8_WAIT_L(n) asm volatile("s_waitcnt lgkmcnt(" #n ")" ::: "memory")
; #define PG8_BAR __builtin_amdgcn_s_barrier()
; #define PG8_SCHED __builtin_amdgcn_sched_barrier(0)
; template <class Epi, bool ALIGN_EPI>
; __device__ __forceinline__ void gemm_phase(LAS unsigned char* lds, const Gemm g, const StaticOrder& S, const Epi& E) {
;     ...
;             PG8_LDA(At, 1, 1); PG8_STAGE(PG8_SB(1, 0), b3, voffB); PG8_STAGE(PG8_SB(1, 1), b3 + hsB, voffB); PG8_STAGE(PG8_SA(1, 0), a3, voffA);
;             PG8_WAIT_V(8); PG8_WAIT_L(0); PG8_BAR; PG8_MMA(1, 0, At, B0); PG8_MMA(1, 1, At, B1); PG8_BAR; PG8_SCHED;
;         }
	s_add_i32 s38, s56, s33
	v_lshl_add_u64 v[216:217], v[216:217], 0, s[10:11]
	s_mov_b32 m0, s38
	s_nop 0
	global_load_lds_dwordx4 v[216:217], off
	s_add_i32 m0, s38, 0x2000
	s_add_u32 s36, s36, 0x20080
	v_lshl_add_u64 v[216:217], v[218:219], 0, s[10:11]
	s_addc_u32 s37, s37, 0
	s_add_i32 s38, s57, s33
	global_load_lds_dwordx4 v[216:217], off
	v_lshl_add_u64 v[216:217], s[36:37], 0, v[132:133]
	s_mov_b32 m0, s38
	s_nop 0
	global_load_lds_dwordx4 v[216:217], off
	v_lshl_add_u64 v[216:217], s[36:37], 0, v[136:137]
	s_add_i32 m0, s38, 0x2000
	s_nop 0
	global_load_lds_dwordx4 v[216:217], off
	v_lshl_add_u64 v[216:217], v[220:221], 0, s[10:11]
	s_mov_b32 m0, s44
	s_nop 0
	global_load_lds_dwordx4 v[216:217], off
	v_lshl_add_u64 v[216:217], v[222:223], 0, s[10:11]
	s_mov_b32 m0, s45
	s_nop 0
	global_load_lds_dwordx4 v[216:217], off
	ds_read_b128 v[184:187], v162 offset:49152
	ds_read_b128 v[188:191], v162 offset:50176
	ds_read_b128 v[192:195], v162 offset:51200
	ds_read_b128 v[196:199], v162 offset:52224
	ds_read_b128 v[200:203], v162 offset:53248
	ds_read_b128 v[204:207], v162 offset:54272
	ds_read_b128 v[208:211], v162 offset:55296
	ds_read_b128 v[212:215], v162 offset:56320
	s_waitcnt vmcnt(8)
	s_waitcnt lgkmcnt(0)
	s_barrier
	s_waitcnt lgkmcnt(0)
	v_mfma_f32_16x16x32_bf16 v[62:65], v[146:149], v[184:187], v[62:65]
	v_mfma_f32_16x16x32_bf16 v[58:61], v[154:157], v[184:187], v[58:61]
	v_mfma_f32_16x16x32_bf16 v[46:49], v[146:149], v[192:195], v[46:49]
	v_mfma_f32_16x16x32_bf16 v[42:45], v[154:157], v[192:195], v[42:45]
	v_mfma_f32_16x16x32_bf16 v[30:33], v[146:149], v[200:203], v[30:33]
	v_mfma_f32_16x16x32_bf16 v[26:29], v[154:157], v[200:203], v[26:29]
	v_mfma_f32_16x16x32_bf16 v[14:17], v[146:149], v[208:211], v[14:17]
	v_mfma_f32_16x16x32_bf16 v[10:13], v[154:157], v[208:211], v[10:13]
	v_mfma_f32_16x16x32_bf16 v[62:65], v[150:153], v[188:191], v[62:65]
	v_mfma_f32_16x16x32_bf16 v[58:61], v[164:167], v[188:191], v[58:61]
	v_mfma_f32_16x16x32_bf16 v[46:49], v[150:153], v[196:199], v[46:49]
	v_mfma_f32_16x16x32_bf16 v[42:45], v[164:167], v[196:199], v[42:45]
	v_mfma_f32_16x16x32_bf16 v[30:33], v[150:153], v[204:207], v[30:33]
	v_mfma_f32_16x16x32_bf16 v[26:29], v[164:167], v[204:207], v[26:29]
	v_mfma_f32_16x16x32_bf16 v[14:17], v[150:153], v[212:215], v[14:17]
	v_mfma_f32_16x16x32_bf16 v[10:13], v[164:167], v[212:215], v[10:13]
	v_mfma_f32_16x16x32_bf16 v[54:57], v[168:171], v[184:187], v[54:57]
	v_mfma_f32_16x16x32_bf16 v[50:53], v[176:179], v[184:187], v[50:53]
	v_mfma_f32_16x16x32_bf16 v[38:41], v[168:171], v[192:195], v[38:41]
	v_mfma_f32_16x16x32_bf16 v[34:37], v[176:179], v[192:195], v[34:37]
	v_mfma_f32_16x16x32_bf16 v[22:25], v[168:171], v[200:203], v[22:25]
	v_mfma_f32_16x16x32_bf16 v[18:21], v[176:179], v[200:203], v[18:21]
	v_mfma_f32_16x16x32_bf16 v[6:9], v[168:171], v[208:211], v[6:9]
	v_mfma_f32_16x16x32_bf16 v[2:5], v[176:179], v[208:211], v[2:5]
	v_mfma_f32_16x16x32_bf16 v[54:57], v[172:175], v[188:191], v[54:57]
	v_mfma_f32_16x16x32_bf16 v[50:53], v[180:183], v[188:191], v[50:53]
	v_mfma_f32_16x16x32_bf16 v[38:41], v[172:175], v[196:199], v[38:41]
	v_mfma_f32_16x16x32_bf16 v[34:37], v[180:183], v[196:199], v[34:37]
	v_mfma_f32_16x16x32_bf16 v[22:25], v[172:175], v[204:207], v[22:25]
	v_mfma_f32_16x16x32_bf16 v[18:21], v[180:183], v[204:207], v[18:21]
	v_mfma_f32_16x16x32_bf16 v[6:9], v[172:175], v[212:215], v[6:9]
	v_mfma_f32_16x16x32_bf16 v[2:5], v[180:183], v[212:215], v[2:5]
	s_barrier
	s_add_i32 s55, s55, 2
	s_add_u32 s34, s34, 0x100
	s_addc_u32 s35, s35, 0
	s_add_u32 s53, s53, 0x100
	s_addc_u32 s54, s54, 0
	s_cmp_gt_u32 s55, 5
	s_cbranch_scc0 .LBB0_1106
	v_readlane_b32 s52, v251, 40
	s_and_b64 vcc, exec, s[12:13]
	v_readlane_b32 s66, v251, 54
	v_readlane_b32 s67, v251, 55
	v_readlane_b32 s53, v251, 41
	v_readlane_b32 s54, v251, 42
	v_readlane_b32 s55, v251, 43
	v_readlane_b32 s56, v251, 44
	v_readlane_b32 s57, v251, 45
	v_readlane_b32 s58, v251, 46
	v_readlane_b32 s59, v251, 47
	v_readlane_b32 s60, v251, 48
	v_readlane_b32 s61, v251, 49
	v_readlane_b32 s62, v251, 50
	v_readlane_b32 s63, v251, 51
	v_readlane_b32 s64, v251, 52
	v_readlane_b32 s65, v251, 53
	s_cbranch_vccz .LBB0_1109
	s_barrier

; #define PG8_STAGE(bufoff, gbase, voff) do { _Pragma("unroll") for (int _i = 0; _i < 2; ++_i) \
;         __builtin_amdgcn_global_load_lds((const unsigned*)((const char*)(gbase) + (voff)[_i]), (LAS unsigned*)(lds + (bufoff) + ldsw + _i * 8192), 16, 0, 0); } while (0)
; #define PG8_LDA(dst, b, h) do { _Pragma("unroll") for (int m = 0; m < 4; ++m) _Pragma("unroll") for (int k = 0; k < 2; ++k) dst[m][k] = *(const LAS bf16x8*)(lds + PG8_SA(b, h) + aoff + m * 2048 + k * 1024); } while (0)
; #define PG8_LDB(dst, b, h) do { _Pragma("unroll") for (int n = 0; n < 2; ++n) _Pragma("unroll") for (int k = 0; k < 2; ++k) dst[n][k] = *(const LAS bf16x8*)(lds + PG8_SB(b, h) + boff + n * 2048 + k * 1024); } while (0)
; #define PG8_MMA(ai, bj, At, Bt) do { __builtin_amdgcn_s_setprio(1); _Pragma("unroll") for (int m = 0; m < 4; ++m) _Pragma("unroll") for (int n = 0; n < 2; ++n) _Pragma("unroll") for (int k = 0; k < 2; ++k) \
;         acc[ai][bj][m][n] = __builtin_amdgcn_mfma_f32_16x16x32_bf16(Bt[n][k], At[m][k], acc[ai][bj][m][n], 0, 0, 0); __builtin_amdgcn_s_setprio(0); } while (0)
; #define PG8_WAIT_V(n) asm volatile("s_waitcnt vmcnt(" #n ")" ::: "memory")
; #define PG8_WAIT_L(n) asm volatile("s_waitcnt lgkmcnt(" #n ")" ::: "memory")
; #define PG8_BAR __builtin_amdgcn_s_barrier()
; #define PG8_SCHED __builtin_amdgcn_sched_barrier(0)
; template <class Epi, bool ALIGN_EPI>
; __device__ __forceinline__ void gemm_phase(LAS unsigned char* lds, const Gemm g, const StaticOrder& S, const Epi& E) {
;     ...
;         for (int t = 0; t < nt; t += 2) {
;             const bool last = (t == nt - 2);
;             const char* a1 = cA + (size_t)(t + 1) * kstepA;
;             const char* a2 = last ? nA : cA + (size_t)(t + 2) * kstepA; const char* b2 = last ? nB : cB + (size_t)(t + 2) * kstep;
;             const char* a3 = a2 + kstepA; const char* b3 = b2 + kstep;
;             PG8_LDB(B0, 0, 0); PG8_LDB(B1, 0, 1); PG8_SCHED; PG8_LDA(At, 0, 0); PG8_STAGE(PG8_SA(1, 1), a1 + hsA, voffA);
;             PG8_WAIT_V(8); PG8_WAIT_L(0); PG8_BAR; PG8_MMA(0, 0, At, B0); PG8_MMA(0, 1, At, B1); PG8_BAR; PG8_SCHED;
;             PG8_LDA(At, 0, 1); PG8_STAGE(PG8_SB(0, 0), b2, voffB); PG8_STAGE(PG8_SB(0, 1), b2 + hsB, voffB); PG8_STAGE(PG8_SA(0, 0), a2, voffA);
.LBB0_1131:
	s_add_u32 s38, s36, 0xfffe0080
	s_addc_u32 s39, s37, -1
	s_cmp_eq_u32 s57, 4
	s_cselect_b32 s41, s25, s39
	s_cselect_b32 s40, s53, s38
	s_cselect_b32 s39, s27, s56
	s_cselect_b32 s38, s54, s55
	v_lshl_add_u64 v[216:217], s[36:37], 0, v[154:155]
	s_add_i32 m0, s35, 0xc000
	s_nop 0
	global_load_lds_dwordx4 v[216:217], off
	v_lshl_add_u64 v[216:217], s[36:37], 0, v[156:157]
	s_add_i32 m0, s35, 0xe000
	s_nop 0
	global_load_lds_dwordx4 v[216:217], off
	ds_read_b128 v[130:133], v184
	ds_read_b128 v[134:137], v184 offset:1024
	ds_read_b128 v[138:141], v184 offset:2048
	ds_read_b128 v[142:145], v184 offset:3072
	ds_read_b128 v[162:165], v185
	ds_read_b128 v[166:169], v185 offset:1024
	ds_read_b128 v[170:173], v185 offset:2048
	ds_read_b128 v[174:177], v185 offset:3072
	ds_read_b128 v[178:181], v186
	ds_read_b128 v[188:191], v186 offset:1024
	ds_read_b128 v[192:195], v186 offset:2048
	ds_read_b128 v[196:199], v186 offset:3072
	ds_read_b128 v[200:203], v186 offset:4096
	ds_read_b128 v[204:207], v186 offset:5120
	ds_read_b128 v[208:211], v186 offset:6144
	ds_read_b128 v[212:215], v186 offset:7168
	s_waitcnt vmcnt(8)
	s_waitcnt lgkmcnt(0)
	s_barrier
	s_waitcnt lgkmcnt(0)
	v_mfma_f32_16x16x32_bf16 v[126:129], v[130:133], v[178:181], v[126:129]
	v_mfma_f32_16x16x32_bf16 v[122:125], v[138:141], v[178:181], v[122:125]
	v_mfma_f32_16x16x32_bf16 v[110:113], v[130:133], v[192:195], v[110:113]
	v_mfma_f32_16x16x32_bf16 v[106:109], v[138:141], v[192:195], v[106:109]
	v_mfma_f32_16x16x32_bf16 v[94:97], v[130:133], v[200:203], v[94:97]
	v_mfma_f32_16x16x32_bf16 v[90:93], v[138:141], v[200:203], v[90:93]
	v_mfma_f32_16x16x32_bf16 v[78:81], v[130:133], v[208:211], v[78:81]
	v_mfma_f32_16x16x32_bf16 v[74:77], v[138:141], v[208:211], v[74:77]
	v_mfma_f32_16x16x32_bf16 v[126:129], v[134:137], v[188:191], v[126:129]
	v_mfma_f32_16x16x32_bf16 v[122:125], v[142:145], v[188:191], v[122:125]
	v_mfma_f32_16x16x32_bf16 v[110:113], v[134:137], v[196:199], v[110:113]
	v_mfma_f32_16x16x32_bf16 v[106:109], v[142:145], v[196:199], v[106:109]
	v_mfma_f32_16x16x32_bf16 v[94:97], v[134:137], v[204:207], v[94:97]
	v_mfma_f32_16x16x32_bf16 v[90:93], v[142:145], v[204:207], v[90:93]
	v_mfma_f32_16x16x32_bf16 v[78:81], v[134:137], v[212:215], v[78:81]
	v_mfma_f32_16x16x32_bf16 v[74:77], v[142:145], v[212:215], v[74:77]
	v_mfma_f32_16x16x32_bf16 v[118:121], v[162:165], v[178:181], v[118:121]
	v_mfma_f32_16x16x32_bf16 v[114:117], v[170:173], v[178:181], v[114:117]
	v_mfma_f32_16x16x32_bf16 v[102:105], v[162:165], v[192:195], v[102:105]
	v_mfma_f32_16x16x32_bf16 v[98:101], v[170:173], v[192:195], v[98:101]
	v_mfma_f32_16x16x32_bf16 v[86:89], v[162:165], v[200:203], v[86:89]
	v_mfma_f32_16x16x32_bf16 v[82:85], v[170:173], v[200:203], v[82:85]
	v_mfma_f32_16x16x32_bf16 v[70:73], v[162:165], v[208:211], v[70:73]
	v_mfma_f32_16x16x32_bf16 v[66:69], v[170:173], v[208:211], v[66:69]
	v_mfma_f32_16x16x32_bf16 v[118:121], v[166:169], v[188:191], v[118:121]
	v_mfma_f32_16x16x32_bf16 v[114:117], v[174:177], v[188:191], v[114:117]
	v_mfma_f32_16x16x32_bf16 v[102:105], v[166:169], v[196:199], v[102:105]
	v_mfma_f32_16x16x32_bf16 v[98:101], v[174:177], v[196:199], v[98:101]
	v_mfma_f32_16x16x32_bf16 v[86:89], v[166:169], v[204:207], v[86:89]
	v_mfma_f32_16x16x32_bf16 v[82:85], v[174:177], v[204:207], v[82:85]
	v_mfma_f32_16x16x32_bf16 v[70:73], v[166:169], v[212:215], v[70:73]
	v_mfma_f32_16x16x32_bf16 v[66:69], v[174:177], v[212:215], v[66:69]
	s_barrier
	s_add_i32 s58, s50, s33
	v_lshl_add_u64 v[216:217], s[38:39], 0, v[148:149]
	s_mov_b32 m0, s58
	s_nop 0
	global_load_lds_dwordx4 v[216:217], off
	s_add_i32 m0, s58, 0x2000
	s_add_u32 s58, s38, 0x20000
	v_lshl_add_u64 v[218:219], s[38:39], 0, v[152:153]
	s_addc_u32 s59, s39, 0
	s_add_i32 s60, s51, s33
	global_load_lds_dwordx4 v[218:219], off
	v_lshl_add_u64 v[220:221], s[58:59], 0, v[148:149]
	s_mov_b32 m0, s60
	v_lshl_add_u64 v[222:223], s[40:41], 0, v[150:151]
	global_load_lds_dwordx4 v[220:221], off
	v_lshl_add_u64 v[220:221], s[58:59], 0, v[152:153]
	s_add_i32 m0, s60, 0x2000
	s_nop 0
	global_load_lds_dwordx4 v[220:221], off
	v_lshl_add_u64 v[220:221], s[40:41], 0, v[146:147]
	s_mov_b32 m0, s35
	s_nop 0
	global_load_lds_dwordx4 v[220:221], off
	s_mov_b32 m0, s42
	s_nop 0
	global_load_lds_dwordx4 v[222:223], off
	ds_read_b128 v[178:181], v186 offset:16384
	ds_read_b128 v[188:191], v186 offset:17408
	ds_read_b128 v[192:195], v186 offset:18432
	ds_read_b128 v[196:199], v186 offset:19456
	ds_read_b128 v[200:203], v186 offset:20480
	ds_read_b128 v[204:207], v186 offset:21504
	ds_read_b128 v[208:211], v186 offset:22528
	ds_read_b128 v[212:215], v186 offset:23552
	s_waitcnt vmcnt(8)
	s_waitcnt lgkmcnt(0)
	s_barrier
; #define PG8_STAGE(bufoff, gbase, voff) do { _Pragma("unroll") for (int _i = 0; _i < 2; ++_i) \
;         __builtin_amdgcn_global_load_lds((const unsigned*)((const char*)(gbase) + (voff)[_i]), (LAS unsigned*)(lds + (bufoff) + ldsw + _i * 8192), 16, 0, 0); } while (0)
; #define PG8_LDA(dst, b, h) do { _Pragma("unroll") for (int m = 0; m < 4; ++m) _Pragma("unroll") for (int k = 0; k < 2; ++k) dst[m][k] = *(const LAS bf16x8*)(lds + PG8_SA(b, h) + aoff + m * 2048 + k * 1024); } while (0)
; #define PG8_LDB(dst, b, h) do { _Pragma("unroll") for (int n = 0; n < 2; ++n) _Pragma("unroll") for (int k = 0; k < 2; ++k) dst[n][k] = *(const LAS bf16x8*)(lds + PG8_SB(b, h) + boff + n * 2048 + k * 1024); } while (0)
; #define PG8_MMA(ai, bj, At, Bt) do { __builtin_amdgcn_s_setprio(1); _Pragma("unroll") for (int m = 0; m < 4; ++m) _Pragma("unroll") for (int n = 0; n < 2; ++n) _Pragma("unroll") for (int k = 0; k < 2; ++k) \
;         acc[ai][bj][m][n] = __builtin_amdgcn_mfma_f32_16x16x32_bf16(Bt[n][k], At[m][k], acc[ai][bj][m][n], 0, 0, 0); __builtin_amdgcn_s_setprio(0); } while (0)
; #define PG8_WAIT_V(n) asm volatile("s_waitcnt vmcnt(" #n ")" ::: "memory")
; #define PG8_WAIT_L(n) asm volatile("s_waitcnt lgkmcnt(" #n ")" ::: "memory")
; #define PG8_BAR __builtin_amdgcn_s_barrier()
; #define PG8_SCHED __builtin_amdgcn_sched_barrier(0)
; template <class Epi, bool ALIGN_EPI>
; __device__ __forceinline__ void gemm_phase(LAS unsigned char* lds, const Gemm g, const StaticOrder& S, const Epi& E) {
;     ...
;             PG8_WAIT_V(8); PG8_WAIT_L(0); PG8_BAR; PG8_MMA(1, 0, At, B0); PG8_MMA(1, 1, At, B1); PG8_BAR; PG8_SCHED;
;             PG8_LDB(B0, 1, 0); PG8_LDB(B1, 1, 1); PG8_SCHED; PG8_LDA(At, 1, 0); PG8_STAGE(PG8_SA(0, 1), a2 + hsA, voffA);
;             PG8_WAIT_V(8); PG8_WAIT_L(0); PG8_BAR; PG8_MMA(0, 0, At, B0); PG8_MMA(0, 1, At, B1); PG8_BAR; PG8_SCHED;
	s_waitcnt lgkmcnt(0)
	v_mfma_f32_16x16x32_bf16 v[62:65], v[130:133], v[178:181], v[62:65]
	v_mfma_f32_16x16x32_bf16 v[58:61], v[138:141], v[178:181], v[58:61]
	v_mfma_f32_16x16x32_bf16 v[46:49], v[130:133], v[192:195], v[46:49]
	v_mfma_f32_16x16x32_bf16 v[42:45], v[138:141], v[192:195], v[42:45]
	v_mfma_f32_16x16x32_bf16 v[30:33], v[130:133], v[200:203], v[30:33]
	v_mfma_f32_16x16x32_bf16 v[26:29], v[138:141], v[200:203], v[26:29]
	v_mfma_f32_16x16x32_bf16 v[14:17], v[130:133], v[208:211], v[14:17]
	v_mfma_f32_16x16x32_bf16 v[10:13], v[138:141], v[208:211], v[10:13]
	v_mfma_f32_16x16x32_bf16 v[62:65], v[134:137], v[188:191], v[62:65]
	v_mfma_f32_16x16x32_bf16 v[58:61], v[142:145], v[188:191], v[58:61]
	v_mfma_f32_16x16x32_bf16 v[46:49], v[134:137], v[196:199], v[46:49]
	v_mfma_f32_16x16x32_bf16 v[42:45], v[142:145], v[196:199], v[42:45]
	v_mfma_f32_16x16x32_bf16 v[30:33], v[134:137], v[204:207], v[30:33]
	v_mfma_f32_16x16x32_bf16 v[26:29], v[142:145], v[204:207], v[26:29]
	v_mfma_f32_16x16x32_bf16 v[14:17], v[134:137], v[212:215], v[14:17]
	v_mfma_f32_16x16x32_bf16 v[10:13], v[142:145], v[212:215], v[10:13]
	v_mfma_f32_16x16x32_bf16 v[54:57], v[162:165], v[178:181], v[54:57]
	v_mfma_f32_16x16x32_bf16 v[50:53], v[170:173], v[178:181], v[50:53]
	v_mfma_f32_16x16x32_bf16 v[38:41], v[162:165], v[192:195], v[38:41]
	v_mfma_f32_16x16x32_bf16 v[34:37], v[170:173], v[192:195], v[34:37]
	v_mfma_f32_16x16x32_bf16 v[22:25], v[162:165], v[200:203], v[22:25]
	v_mfma_f32_16x16x32_bf16 v[18:21], v[170:173], v[200:203], v[18:21]
	v_mfma_f32_16x16x32_bf16 v[6:9], v[162:165], v[208:211], v[6:9]
	v_mfma_f32_16x16x32_bf16 v[2:5], v[170:173], v[208:211], v[2:5]
	v_mfma_f32_16x16x32_bf16 v[54:57], v[166:169], v[188:191], v[54:57]
	v_mfma_f32_16x16x32_bf16 v[50:53], v[174:177], v[188:191], v[50:53]
	v_mfma_f32_16x16x32_bf16 v[38:41], v[166:169], v[196:199], v[38:41]
	v_mfma_f32_16x16x32_bf16 v[34:37], v[174:177], v[196:199], v[34:37]
	v_mfma_f32_16x16x32_bf16 v[22:25], v[166:169], v[204:207], v[22:25]
	v_mfma_f32_16x16x32_bf16 v[18:21], v[174:177], v[204:207], v[18:21]
	v_mfma_f32_16x16x32_bf16 v[6:9], v[166:169], v[212:215], v[6:9]
	v_mfma_f32_16x16x32_bf16 v[2:5], v[174:177], v[212:215], v[2:5]
	s_barrier
	s_add_i32 s58, 0, 0x18000
	s_add_i32 s59, 0, 0x1c000
	s_add_u32 s40, s40, 0x20000
	s_addc_u32 s41, s41, 0
	s_mov_b32 m0, s43
	v_lshl_add_u64 v[224:225], s[40:41], 0, v[146:147]
	global_load_lds_dwordx4 v[224:225], off
	v_lshl_add_u64 v[224:225], s[40:41], 0, v[150:151]
	s_mov_b32 m0, s44
	s_nop 0
	global_load_lds_dwordx4 v[224:225], off
	v_add_u32_e32 v142, s58, v182
	v_add_u32_e32 v174, s59, v182
	ds_read_b128 v[130:133], v142
	ds_read_b128 v[134:137], v142 offset:1024
	ds_read_b128 v[138:141], v142 offset:2048
	ds_read_b128 v[142:145], v142 offset:3072
	ds_read_b128 v[162:165], v174
	ds_read_b128 v[166:169], v174 offset:1024
	ds_read_b128 v[170:173], v174 offset:2048
	ds_read_b128 v[174:177], v174 offset:3072
	ds_read_b128 v[178:181], v186 offset:32768
	ds_read_b128 v[188:191], v186 offset:33792
	ds_read_b128 v[192:195], v186 offset:34816
	ds_read_b128 v[196:199], v186 offset:35840
	ds_read_b128 v[200:203], v186 offset:36864
	ds_read_b128 v[204:207], v186 offset:37888
	ds_read_b128 v[208:211], v186 offset:38912
	ds_read_b128 v[212:215], v186 offset:39936
	s_waitcnt vmcnt(8)
	s_waitcnt lgkmcnt(0)
	s_barrier
	s_waitcnt lgkmcnt(0)
	v_mfma_f32_16x16x32_bf16 v[126:129], v[130:133], v[178:181], v[126:129]
	v_mfma_f32_16x16x32_bf16 v[122:125], v[138:141], v[178:181], v[122:125]
	v_mfma_f32_16x16x32_bf16 v[110:113], v[130:133], v[192:195], v[110:113]
	v_mfma_f32_16x16x32_bf16 v[106:109], v[138:141], v[192:195], v[106:109]
	v_mfma_f32_16x16x32_bf16 v[94:97], v[130:133], v[200:203], v[94:97]
	v_mfma_f32_16x16x32_bf16 v[90:93], v[138:141], v[200:203], v[90:93]
	v_mfma_f32_16x16x32_bf16 v[78:81], v[130:133], v[208:211], v[78:81]
	v_mfma_f32_16x16x32_bf16 v[74:77], v[138:141], v[208:211], v[74:77]
	v_mfma_f32_16x16x32_bf16 v[126:129], v[134:137], v[188:191], v[126:129]
	v_mfma_f32_16x16x32_bf16 v[122:125], v[142:145], v[188:191], v[122:125]
	v_mfma_f32_16x16x32_bf16 v[110:113], v[134:137], v[196:199], v[110:113]
	v_mfma_f32_16x16x32_bf16 v[106:109], v[142:145], v[196:199], v[106:109]
	v_mfma_f32_16x16x32_bf16 v[94:97], v[134:137], v[204:207], v[94:97]
	v_mfma_f32_16x16x32_bf16 v[90:93], v[142:145], v[204:207], v[90:93]
	v_mfma_f32_16x16x32_bf16 v[78:81], v[134:137], v[212:215], v[78:81]
	v_mfma_f32_16x16x32_bf16 v[74:77], v[142:145], v[212:215], v[74:77]
	v_mfma_f32_16x16x32_bf16 v[118:121], v[162:165], v[178:181], v[118:121]
	v_mfma_f32_16x16x32_bf16 v[114:117], v[170:173], v[178:181], v[114:117]
	v_mfma_f32_16x16x32_bf16 v[102:105], v[162:165], v[192:195], v[102:105]
	v_mfma_f32_16x16x32_bf16 v[98:101], v[170:173], v[192:195], v[98:101]
	v_mfma_f32_16x16x32_bf16 v[86:89], v[162:165], v[200:203], v[86:89]
	v_mfma_f32_16x16x32_bf16 v[82:85], v[170:173], v[200:203], v[82:85]
	v_mfma_f32_16x16x32_bf16 v[70:73], v[162:165], v[208:211], v[70:73]
	v_mfma_f32_16x16x32_bf16 v[66:69], v[170:173], v[208:211], v[66:69]
	v_mfma_f32_16x16x32_bf16 v[118:121], v[166:169], v[188:191], v[118:121]
	v_mfma_f32_16x16x32_bf16 v[114:117], v[174:177], v[188:191], v[114:117]
	v_mfma_f32_16x16x32_bf16 v[102:105], v[166:169], v[196:199], v[102:105]
	v_mfma_f32_16x16x32_bf16 v[98:101], v[174:177], v[196:199], v[98:101]
	v_mfma_f32_16x16x32_bf16 v[86:89], v[166:169], v[204:207], v[86:89]
	v_mfma_f32_16x16x32_bf16 v[82:85], v[174:177], v[204:207], v[82:85]
	v_mfma_f32_16x16x32_bf16 v[70:73], v[166:169], v[212:215], v[70:73]
	v_mfma_f32_16x16x32_bf16 v[66:69], v[174:177], v[212:215], v[66:69]
	s_barrier
; #define PG8_STAGE(bufoff, gbase, voff) do { _Pragma("unroll") for (int _i = 0; _i < 2; ++_i) \
;         __builtin_amdgcn_global_load_lds((const unsigned*)((const char*)(gbase) + (voff)[_i]), (LAS unsigned*)(lds + (bufoff) + ldsw + _i * 8192), 16, 0, 0); } while (0)
; #define PG8_LDA(dst, b, h) do { _Pragma("unroll") for (int m = 0; m < 4; ++m) _Pragma("unroll") for (int k = 0; k < 2; ++k) dst[m][k] = *(const LAS bf16x8*)(lds + PG8_SA(b, h) + aoff + m * 2048 + k * 1024); } while (0)
; #define PG8_MMA(ai, bj, At, Bt) do { __builtin_amdgcn_s_setprio(1); _Pragma("unroll") for (int m = 0; m < 4; ++m) _Pragma("unroll") for (int n = 0; n < 2; ++n) _Pragma("unroll") for (int k = 0; k < 2; ++k) \
;         acc[ai][bj][m][n] = __builtin_amdgcn_mfma_f32_16x16x32_bf16(Bt[n][k], At[m][k], acc[ai][bj][m][n], 0, 0, 0); __builtin_amdgcn_s_setprio(0); } while (0)
; #define PG8_WAIT_V(n) asm volatile("s_waitcnt vmcnt(" #n ")" ::: "memory")
; #define PG8_WAIT_L(n) asm volatile("s_waitcnt lgkmcnt(" #n ")" ::: "memory")
; #define PG8_BAR __builtin_amdgcn_s_barrier()
; #define PG8_SCHED __builtin_amdgcn_sched_barrier(0)
; template <class Epi, bool ALIGN_EPI>
; __device__ __forceinline__ void gemm_phase(LAS unsigned char* lds, const Gemm g, const StaticOrder& S, const Epi& E) {
;     ...
;             PG8_LDA(At, 1, 1); PG8_STAGE(PG8_SB(1, 0), b3, voffB); PG8_STAGE(PG8_SB(1, 1), b3 + hsB, voffB); PG8_STAGE(PG8_SA(1, 0), a3, voffA);
;             PG8_WAIT_V(8); PG8_WAIT_L(0); PG8_BAR; PG8_MMA(1, 0, At, B0); PG8_MMA(1, 1, At, B1); PG8_BAR; PG8_SCHED;
;         }
	s_add_i32 s40, s58, s33
	v_lshl_add_u64 v[216:217], v[216:217], 0, s[8:9]
	s_mov_b32 m0, s40
	s_nop 0
	global_load_lds_dwordx4 v[216:217], off
	s_add_i32 m0, s40, 0x2000
	s_add_u32 s38, s38, 0x20080
	v_lshl_add_u64 v[216:217], v[218:219], 0, s[8:9]
	s_addc_u32 s39, s39, 0
	s_add_i32 s40, s59, s33
	global_load_lds_dwordx4 v[216:217], off
	v_lshl_add_u64 v[216:217], s[38:39], 0, v[148:149]
	s_mov_b32 m0, s40
	s_nop 0
	global_load_lds_dwordx4 v[216:217], off
	v_lshl_add_u64 v[216:217], s[38:39], 0, v[152:153]
	s_add_i32 m0, s40, 0x2000
	s_nop 0
	global_load_lds_dwordx4 v[216:217], off
	v_lshl_add_u64 v[216:217], v[220:221], 0, s[8:9]
	s_mov_b32 m0, s46
	s_nop 0
	global_load_lds_dwordx4 v[216:217], off
	v_lshl_add_u64 v[216:217], v[222:223], 0, s[8:9]
	s_mov_b32 m0, s47
	s_nop 0
	global_load_lds_dwordx4 v[216:217], off
	ds_read_b128 v[178:181], v186 offset:49152
	ds_read_b128 v[188:191], v186 offset:50176
	ds_read_b128 v[192:195], v186 offset:51200
	ds_read_b128 v[196:199], v186 offset:52224
	ds_read_b128 v[200:203], v186 offset:53248
	ds_read_b128 v[204:207], v186 offset:54272
	ds_read_b128 v[208:211], v186 offset:55296
	ds_read_b128 v[212:215], v186 offset:56320
	s_waitcnt vmcnt(8)
	s_waitcnt lgkmcnt(0)
	s_barrier
	s_waitcnt lgkmcnt(0)
	v_mfma_f32_16x16x32_bf16 v[62:65], v[130:133], v[178:181], v[62:65]
	v_mfma_f32_16x16x32_bf16 v[58:61], v[138:141], v[178:181], v[58:61]
	v_mfma_f32_16x16x32_bf16 v[46:49], v[130:133], v[192:195], v[46:49]
	v_mfma_f32_16x16x32_bf16 v[42:45], v[138:141], v[192:195], v[42:45]
	v_mfma_f32_16x16x32_bf16 v[30:33], v[130:133], v[200:203], v[30:33]
	v_mfma_f32_16x16x32_bf16 v[26:29], v[138:141], v[200:203], v[26:29]
	v_mfma_f32_16x16x32_bf16 v[14:17], v[130:133], v[208:211], v[14:17]
	v_mfma_f32_16x16x32_bf16 v[10:13], v[138:141], v[208:211], v[10:13]
	v_mfma_f32_16x16x32_bf16 v[62:65], v[134:137], v[188:191], v[62:65]
	v_mfma_f32_16x16x32_bf16 v[58:61], v[142:145], v[188:191], v[58:61]
	v_mfma_f32_16x16x32_bf16 v[46:49], v[134:137], v[196:199], v[46:49]
	v_mfma_f32_16x16x32_bf16 v[42:45], v[142:145], v[196:199], v[42:45]
	v_mfma_f32_16x16x32_bf16 v[30:33], v[134:137], v[204:207], v[30:33]
	v_mfma_f32_16x16x32_bf16 v[26:29], v[142:145], v[204:207], v[26:29]
	v_mfma_f32_16x16x32_bf16 v[14:17], v[134:137], v[212:215], v[14:17]
	v_mfma_f32_16x16x32_bf16 v[10:13], v[142:145], v[212:215], v[10:13]
	v_mfma_f32_16x16x32_bf16 v[54:57], v[162:165], v[178:181], v[54:57]
	v_mfma_f32_16x16x32_bf16 v[50:53], v[170:173], v[178:181], v[50:53]
	v_mfma_f32_16x16x32_bf16 v[38:41], v[162:165], v[192:195], v[38:41]
	v_mfma_f32_16x16x32_bf16 v[34:37], v[170:173], v[192:195], v[34:37]
	v_mfma_f32_16x16x32_bf16 v[22:25], v[162:165], v[200:203], v[22:25]
	v_mfma_f32_16x16x32_bf16 v[18:21], v[170:173], v[200:203], v[18:21]
	v_mfma_f32_16x16x32_bf16 v[6:9], v[162:165], v[208:211], v[6:9]
	v_mfma_f32_16x16x32_bf16 v[2:5], v[170:173], v[208:211], v[2:5]
	v_mfma_f32_16x16x32_bf16 v[54:57], v[166:169], v[188:191], v[54:57]
	v_mfma_f32_16x16x32_bf16 v[50:53], v[174:177], v[188:191], v[50:53]
	v_mfma_f32_16x16x32_bf16 v[38:41], v[166:169], v[196:199], v[38:41]
	v_mfma_f32_16x16x32_bf16 v[34:37], v[174:177], v[196:199], v[34:37]
	v_mfma_f32_16x16x32_bf16 v[22:25], v[166:169], v[204:207], v[22:25]
	v_mfma_f32_16x16x32_bf16 v[18:21], v[174:177], v[204:207], v[18:21]
	v_mfma_f32_16x16x32_bf16 v[6:9], v[166:169], v[212:215], v[6:9]
	v_mfma_f32_16x16x32_bf16 v[2:5], v[174:177], v[212:215], v[2:5]
	s_barrier
	s_add_i32 s57, s57, 2
	s_add_u32 s36, s36, 0x100
	s_addc_u32 s37, s37, 0
	s_add_u32 s55, s55, 0x100
	s_addc_u32 s56, s56, 0
	s_cmp_gt_u32 s57, 5
	s_cbranch_scc0 .LBB0_1131
	s_and_b64 vcc, exec, s[10:11]
	s_cbranch_vccz .LBB0_1134
	s_barrier

; #define PG8_STAGE(bufoff, gbase, voff) do { _Pragma("unroll") for (int _i = 0; _i < 2; ++_i) \
;         __builtin_amdgcn_global_load_lds((const unsigned*)((const char*)(gbase) + (voff)[_i]), (LAS unsigned*)(lds + (bufoff) + ldsw + _i * 8192), 16, 0, 0); } while (0)
; #define PG8_LDA(dst, b, h) do { _Pragma("unroll") for (int m = 0; m < 4; ++m) _Pragma("unroll") for (int k = 0; k < 2; ++k) dst[m][k] = *(const LAS bf16x8*)(lds + PG8_SA(b, h) + aoff + m * 2048 + k * 1024); } while (0)
; #define PG8_LDB(dst, b, h) do { _Pragma("unroll") for (int n = 0; n < 2; ++n) _Pragma("unroll") for (int k = 0; k < 2; ++k) dst[n][k] = *(const LAS bf16x8*)(lds + PG8_SB(b, h) + boff + n * 2048 + k * 1024); } while (0)
; #define PG8_MMA(ai, bj, At, Bt) do { __builtin_amdgcn_s_setprio(1); _Pragma("unroll") for (int m = 0; m < 4; ++m) _Pragma("unroll") for (int n = 0; n < 2; ++n) _Pragma("unroll") for (int k = 0; k < 2; ++k) \
;         acc[ai][bj][m][n] = __builtin_amdgcn_mfma_f32_16x16x32_bf16(Bt[n][k], At[m][k], acc[ai][bj][m][n], 0, 0, 0); __builtin_amdgcn_s_setprio(0); } while (0)
; #define PG8_WAIT_V(n) asm volatile("s_waitcnt vmcnt(" #n ")" ::: "memory")
; #define PG8_WAIT_L(n) asm volatile("s_waitcnt lgkmcnt(" #n ")" ::: "memory")
; #define PG8_BAR __builtin_amdgcn_s_barrier()
; #define PG8_SCHED __builtin_amdgcn_sched_barrier(0)
; template <class Epi, bool ALIGN_EPI>
; __device__ __forceinline__ void gemm_phase(LAS unsigned char* lds, const Gemm g, const StaticOrder& S, const Epi& E) {
;     ...
;         for (int t = 0; t < nt; t += 2) {
;             const bool last = (t == nt - 2);
;             const char* a1 = cA + (size_t)(t + 1) * kstepA;
;             const char* a2 = last ? nA : cA + (size_t)(t + 2) * kstepA; const char* b2 = last ? nB : cB + (size_t)(t + 2) * kstep;
;             const char* a3 = a2 + kstepA; const char* b3 = b2 + kstep;
;             PG8_LDB(B0, 0, 0); PG8_LDB(B1, 0, 1); PG8_SCHED; PG8_LDA(At, 0, 0); PG8_STAGE(PG8_SA(1, 1), a1 + hsA, voffA);
;             PG8_WAIT_V(8); PG8_WAIT_L(0); PG8_BAR; PG8_MMA(0, 0, At, B0); PG8_MMA(0, 1, At, B1); PG8_BAR; PG8_SCHED;
;             PG8_LDA(At, 0, 1); PG8_STAGE(PG8_SB(0, 0), b2, voffB); PG8_STAGE(PG8_SB(0, 1), b2 + hsB, voffB); PG8_STAGE(PG8_SA(0, 0), a2, voffA);
.LBB0_1212:
	s_add_u32 s26, s24, 0xfffc0080
	s_addc_u32 s27, s25, -1
	s_cmp_eq_u32 s46, 12
	s_cselect_b32 s29, s13, s27
	s_cselect_b32 s28, s21, s26
	s_cselect_b32 s27, s15, s45
	s_cselect_b32 s26, s43, s44
	v_lshl_add_u64 v[186:187], s[24:25], 0, v[162:163]
	s_add_i32 m0, s23, 0xc000
	s_nop 0
	global_load_lds_dwordx4 v[186:187], off
	v_lshl_add_u64 v[186:187], s[24:25], 0, v[164:165]
	s_add_i32 m0, s23, 0xe000
	s_nop 0
	global_load_lds_dwordx4 v[186:187], off
	ds_read_b128 v[130:133], v190
	ds_read_b128 v[134:137], v190 offset:1024
	ds_read_b128 v[138:141], v190 offset:2048
	ds_read_b128 v[142:145], v190 offset:3072
	ds_read_b128 v[146:149], v191
	ds_read_b128 v[150:153], v191 offset:1024
	ds_read_b128 v[170:173], v191 offset:2048
	ds_read_b128 v[174:177], v191 offset:3072
	ds_read_b128 v[178:181], v192
	ds_read_b128 v[182:185], v192 offset:1024
	ds_read_b128 v[194:197], v192 offset:2048
	ds_read_b128 v[198:201], v192 offset:3072
	ds_read_b128 v[202:205], v192 offset:4096
	ds_read_b128 v[206:209], v192 offset:5120
	ds_read_b128 v[210:213], v192 offset:6144
	ds_read_b128 v[214:217], v192 offset:7168
	s_waitcnt vmcnt(8)
	s_waitcnt lgkmcnt(0)
	s_barrier
	s_waitcnt lgkmcnt(0)
	v_mfma_f32_16x16x32_bf16 v[126:129], v[130:133], v[178:181], v[126:129]
	v_mfma_f32_16x16x32_bf16 v[122:125], v[138:141], v[178:181], v[122:125]
	v_mfma_f32_16x16x32_bf16 v[110:113], v[130:133], v[194:197], v[110:113]
	v_mfma_f32_16x16x32_bf16 v[106:109], v[138:141], v[194:197], v[106:109]
	v_mfma_f32_16x16x32_bf16 v[94:97], v[130:133], v[202:205], v[94:97]
	v_mfma_f32_16x16x32_bf16 v[90:93], v[138:141], v[202:205], v[90:93]
	v_mfma_f32_16x16x32_bf16 v[78:81], v[130:133], v[210:213], v[78:81]
	v_mfma_f32_16x16x32_bf16 v[74:77], v[138:141], v[210:213], v[74:77]
	v_mfma_f32_16x16x32_bf16 v[126:129], v[134:137], v[182:185], v[126:129]
	v_mfma_f32_16x16x32_bf16 v[122:125], v[142:145], v[182:185], v[122:125]
	v_mfma_f32_16x16x32_bf16 v[110:113], v[134:137], v[198:201], v[110:113]
	v_mfma_f32_16x16x32_bf16 v[106:109], v[142:145], v[198:201], v[106:109]
	v_mfma_f32_16x16x32_bf16 v[94:97], v[134:137], v[206:209], v[94:97]
	v_mfma_f32_16x16x32_bf16 v[90:93], v[142:145], v[206:209], v[90:93]
	v_mfma_f32_16x16x32_bf16 v[78:81], v[134:137], v[214:217], v[78:81]
	v_mfma_f32_16x16x32_bf16 v[74:77], v[142:145], v[214:217], v[74:77]
	v_mfma_f32_16x16x32_bf16 v[118:121], v[146:149], v[178:181], v[118:121]
	v_mfma_f32_16x16x32_bf16 v[114:117], v[170:173], v[178:181], v[114:117]
	v_mfma_f32_16x16x32_bf16 v[102:105], v[146:149], v[194:197], v[102:105]
	v_mfma_f32_16x16x32_bf16 v[98:101], v[170:173], v[194:197], v[98:101]
	v_mfma_f32_16x16x32_bf16 v[86:89], v[146:149], v[202:205], v[86:89]
	v_mfma_f32_16x16x32_bf16 v[82:85], v[170:173], v[202:205], v[82:85]
	v_mfma_f32_16x16x32_bf16 v[70:73], v[146:149], v[210:213], v[70:73]
	v_mfma_f32_16x16x32_bf16 v[66:69], v[170:173], v[210:213], v[66:69]
	v_mfma_f32_16x16x32_bf16 v[118:121], v[150:153], v[182:185], v[118:121]
	v_mfma_f32_16x16x32_bf16 v[114:117], v[174:177], v[182:185], v[114:117]
	v_mfma_f32_16x16x32_bf16 v[102:105], v[150:153], v[198:201], v[102:105]
	v_mfma_f32_16x16x32_bf16 v[98:101], v[174:177], v[198:201], v[98:101]
	v_mfma_f32_16x16x32_bf16 v[86:89], v[150:153], v[206:209], v[86:89]
	v_mfma_f32_16x16x32_bf16 v[82:85], v[174:177], v[206:209], v[82:85]
	v_mfma_f32_16x16x32_bf16 v[70:73], v[150:153], v[214:217], v[70:73]
	v_mfma_f32_16x16x32_bf16 v[66:69], v[174:177], v[214:217], v[66:69]
	s_barrier
	s_add_i32 s47, s41, s30
	v_lshl_add_u64 v[186:187], s[26:27], 0, v[156:157]
	s_mov_b32 m0, s47
	s_nop 0
	global_load_lds_dwordx4 v[186:187], off
	s_add_i32 m0, s47, 0x2000
	s_add_u32 s48, s26, 0x40000
	v_lshl_add_u64 v[218:219], s[26:27], 0, v[160:161]
	s_addc_u32 s49, s27, 0
	s_add_i32 s47, s42, s30
	global_load_lds_dwordx4 v[218:219], off
	v_lshl_add_u64 v[220:221], s[48:49], 0, v[156:157]
	s_mov_b32 m0, s47
	v_lshl_add_u64 v[222:223], s[28:29], 0, v[158:159]
	global_load_lds_dwordx4 v[220:221], off
	v_lshl_add_u64 v[220:221], s[48:49], 0, v[160:161]
	s_add_i32 m0, s47, 0x2000
	s_nop 0
	global_load_lds_dwordx4 v[220:221], off
	v_lshl_add_u64 v[220:221], s[28:29], 0, v[154:155]
	s_mov_b32 m0, s23
	s_nop 0
	global_load_lds_dwordx4 v[220:221], off
	s_mov_b32 m0, s31
	s_nop 0
	global_load_lds_dwordx4 v[222:223], off
	ds_read_b128 v[178:181], v192 offset:16384
	ds_read_b128 v[182:185], v192 offset:17408
	ds_read_b128 v[194:197], v192 offset:18432
	ds_read_b128 v[198:201], v192 offset:19456
	ds_read_b128 v[202:205], v192 offset:20480
	ds_read_b128 v[206:209], v192 offset:21504
	ds_read_b128 v[210:213], v192 offset:22528
	ds_read_b128 v[214:217], v192 offset:23552
	s_waitcnt vmcnt(8)
	s_waitcnt lgkmcnt(0)
	s_barrier
; #define PG8_STAGE(bufoff, gbase, voff) do { _Pragma("unroll") for (int _i = 0; _i < 2; ++_i) \
;         __builtin_amdgcn_global_load_lds((const unsigned*)((const char*)(gbase) + (voff)[_i]), (LAS unsigned*)(lds + (bufoff) + ldsw + _i * 8192), 16, 0, 0); } while (0)
; #define PG8_LDA(dst, b, h) do { _Pragma("unroll") for (int m = 0; m < 4; ++m) _Pragma("unroll") for (int k = 0; k < 2; ++k) dst[m][k] = *(const LAS bf16x8*)(lds + PG8_SA(b, h) + aoff + m * 2048 + k * 1024); } while (0)
; #define PG8_LDB(dst, b, h) do { _Pragma("unroll") for (int n = 0; n < 2; ++n) _Pragma("unroll") for (int k = 0; k < 2; ++k) dst[n][k] = *(const LAS bf16x8*)(lds + PG8_SB(b, h) + boff + n * 2048 + k * 1024); } while (0)
; #define PG8_MMA(ai, bj, At, Bt) do { __builtin_amdgcn_s_setprio(1); _Pragma("unroll") for (int m = 0; m < 4; ++m) _Pragma("unroll") for (int n = 0; n < 2; ++n) _Pragma("unroll") for (int k = 0; k < 2; ++k) \
;         acc[ai][bj][m][n] = __builtin_amdgcn_mfma_f32_16x16x32_bf16(Bt[n][k], At[m][k], acc[ai][bj][m][n], 0, 0, 0); __builtin_amdgcn_s_setprio(0); } while (0)
; #define PG8_WAIT_V(n) asm volatile("s_waitcnt vmcnt(" #n ")" ::: "memory")
; #define PG8_WAIT_L(n) asm volatile("s_waitcnt lgkmcnt(" #n ")" ::: "memory")
; #define PG8_BAR __builtin_amdgcn_s_barrier()
; #define PG8_SCHED __builtin_amdgcn_sched_barrier(0)
; template <class Epi, bool ALIGN_EPI>
; __device__ __forceinline__ void gemm_phase(LAS unsigned char* lds, const Gemm g, const StaticOrder& S, const Epi& E) {
;     ...
;             PG8_WAIT_V(8); PG8_WAIT_L(0); PG8_BAR; PG8_MMA(1, 0, At, B0); PG8_MMA(1, 1, At, B1); PG8_BAR; PG8_SCHED;
;             PG8_LDB(B0, 1, 0); PG8_LDB(B1, 1, 1); PG8_SCHED; PG8_LDA(At, 1, 0); PG8_STAGE(PG8_SA(0, 1), a2 + hsA, voffA);
;             PG8_WAIT_V(8); PG8_WAIT_L(0); PG8_BAR; PG8_MMA(0, 0, At, B0); PG8_MMA(0, 1, At, B1); PG8_BAR; PG8_SCHED;
	s_waitcnt lgkmcnt(0)
	v_mfma_f32_16x16x32_bf16 v[62:65], v[130:133], v[178:181], v[62:65]
	v_mfma_f32_16x16x32_bf16 v[58:61], v[138:141], v[178:181], v[58:61]
	v_mfma_f32_16x16x32_bf16 v[46:49], v[130:133], v[194:197], v[46:49]
	v_mfma_f32_16x16x32_bf16 v[42:45], v[138:141], v[194:197], v[42:45]
	v_mfma_f32_16x16x32_bf16 v[30:33], v[130:133], v[202:205], v[30:33]
	v_mfma_f32_16x16x32_bf16 v[26:29], v[138:141], v[202:205], v[26:29]
	v_mfma_f32_16x16x32_bf16 v[14:17], v[130:133], v[210:213], v[14:17]
	v_mfma_f32_16x16x32_bf16 v[10:13], v[138:141], v[210:213], v[10:13]
	v_mfma_f32_16x16x32_bf16 v[62:65], v[134:137], v[182:185], v[62:65]
	v_mfma_f32_16x16x32_bf16 v[58:61], v[142:145], v[182:185], v[58:61]
	v_mfma_f32_16x16x32_bf16 v[46:49], v[134:137], v[198:201], v[46:49]
	v_mfma_f32_16x16x32_bf16 v[42:45], v[142:145], v[198:201], v[42:45]
	v_mfma_f32_16x16x32_bf16 v[30:33], v[134:137], v[206:209], v[30:33]
	v_mfma_f32_16x16x32_bf16 v[26:29], v[142:145], v[206:209], v[26:29]
	v_mfma_f32_16x16x32_bf16 v[14:17], v[134:137], v[214:217], v[14:17]
	v_mfma_f32_16x16x32_bf16 v[10:13], v[142:145], v[214:217], v[10:13]
	v_mfma_f32_16x16x32_bf16 v[54:57], v[146:149], v[178:181], v[54:57]
	v_mfma_f32_16x16x32_bf16 v[50:53], v[170:173], v[178:181], v[50:53]
	v_mfma_f32_16x16x32_bf16 v[38:41], v[146:149], v[194:197], v[38:41]
	v_mfma_f32_16x16x32_bf16 v[34:37], v[170:173], v[194:197], v[34:37]
	v_mfma_f32_16x16x32_bf16 v[22:25], v[146:149], v[202:205], v[22:25]
	v_mfma_f32_16x16x32_bf16 v[18:21], v[170:173], v[202:205], v[18:21]
	v_mfma_f32_16x16x32_bf16 v[6:9], v[146:149], v[210:213], v[6:9]
	v_mfma_f32_16x16x32_bf16 v[2:5], v[170:173], v[210:213], v[2:5]
	v_mfma_f32_16x16x32_bf16 v[54:57], v[150:153], v[182:185], v[54:57]
	v_mfma_f32_16x16x32_bf16 v[50:53], v[174:177], v[182:185], v[50:53]
	v_mfma_f32_16x16x32_bf16 v[38:41], v[150:153], v[198:201], v[38:41]
	v_mfma_f32_16x16x32_bf16 v[34:37], v[174:177], v[198:201], v[34:37]
	v_mfma_f32_16x16x32_bf16 v[22:25], v[150:153], v[206:209], v[22:25]
	v_mfma_f32_16x16x32_bf16 v[18:21], v[174:177], v[206:209], v[18:21]
	v_mfma_f32_16x16x32_bf16 v[6:9], v[150:153], v[214:217], v[6:9]
	v_mfma_f32_16x16x32_bf16 v[2:5], v[174:177], v[214:217], v[2:5]
	s_barrier
	s_add_i32 s47, 0, 0x18000
	s_add_i32 s48, 0, 0x1c000
	s_add_u32 s28, s28, 0x40000
	s_addc_u32 s29, s29, 0
	s_mov_b32 m0, s33
	v_lshl_add_u64 v[224:225], s[28:29], 0, v[154:155]
	global_load_lds_dwordx4 v[224:225], off
	v_lshl_add_u64 v[224:225], s[28:29], 0, v[158:159]
	s_mov_b32 m0, s34
	s_nop 0
	global_load_lds_dwordx4 v[224:225], off
	v_add_u32_e32 v142, s47, v188
	v_add_u32_e32 v174, s48, v188
	ds_read_b128 v[130:133], v142
	ds_read_b128 v[134:137], v142 offset:1024
	ds_read_b128 v[138:141], v142 offset:2048
	ds_read_b128 v[142:145], v142 offset:3072
	ds_read_b128 v[146:149], v174
	ds_read_b128 v[150:153], v174 offset:1024
	ds_read_b128 v[170:173], v174 offset:2048
	ds_read_b128 v[174:177], v174 offset:3072
	ds_read_b128 v[178:181], v192 offset:32768
	ds_read_b128 v[182:185], v192 offset:33792
	ds_read_b128 v[194:197], v192 offset:34816
	ds_read_b128 v[198:201], v192 offset:35840
	ds_read_b128 v[202:205], v192 offset:36864
	ds_read_b128 v[206:209], v192 offset:37888
	ds_read_b128 v[210:213], v192 offset:38912
	ds_read_b128 v[214:217], v192 offset:39936
	s_waitcnt vmcnt(8)
	s_waitcnt lgkmcnt(0)
	s_barrier
	s_waitcnt lgkmcnt(0)
	v_mfma_f32_16x16x32_bf16 v[126:129], v[130:133], v[178:181], v[126:129]
	v_mfma_f32_16x16x32_bf16 v[122:125], v[138:141], v[178:181], v[122:125]
	v_mfma_f32_16x16x32_bf16 v[110:113], v[130:133], v[194:197], v[110:113]
	v_mfma_f32_16x16x32_bf16 v[106:109], v[138:141], v[194:197], v[106:109]
	v_mfma_f32_16x16x32_bf16 v[94:97], v[130:133], v[202:205], v[94:97]
	v_mfma_f32_16x16x32_bf16 v[90:93], v[138:141], v[202:205], v[90:93]
	v_mfma_f32_16x16x32_bf16 v[78:81], v[130:133], v[210:213], v[78:81]
	v_mfma_f32_16x16x32_bf16 v[74:77], v[138:141], v[210:213], v[74:77]
	v_mfma_f32_16x16x32_bf16 v[126:129], v[134:137], v[182:185], v[126:129]
	v_mfma_f32_16x16x32_bf16 v[122:125], v[142:145], v[182:185], v[122:125]
	v_mfma_f32_16x16x32_bf16 v[110:113], v[134:137], v[198:201], v[110:113]
	v_mfma_f32_16x16x32_bf16 v[106:109], v[142:145], v[198:201], v[106:109]
	v_mfma_f32_16x16x32_bf16 v[94:97], v[134:137], v[206:209], v[94:97]
	v_mfma_f32_16x16x32_bf16 v[90:93], v[142:145], v[206:209], v[90:93]
	v_mfma_f32_16x16x32_bf16 v[78:81], v[134:137], v[214:217], v[78:81]
	v_mfma_f32_16x16x32_bf16 v[74:77], v[142:145], v[214:217], v[74:77]
	v_mfma_f32_16x16x32_bf16 v[118:121], v[146:149], v[178:181], v[118:121]
	v_mfma_f32_16x16x32_bf16 v[114:117], v[170:173], v[178:181], v[114:117]
	v_mfma_f32_16x16x32_bf16 v[102:105], v[146:149], v[194:197], v[102:105]
	v_mfma_f32_16x16x32_bf16 v[98:101], v[170:173], v[194:197], v[98:101]
	v_mfma_f32_16x16x32_bf16 v[86:89], v[146:149], v[202:205], v[86:89]
	v_mfma_f32_16x16x32_bf16 v[82:85], v[170:173], v[202:205], v[82:85]
	v_mfma_f32_16x16x32_bf16 v[70:73], v[146:149], v[210:213], v[70:73]
	v_mfma_f32_16x16x32_bf16 v[66:69], v[170:173], v[210:213], v[66:69]
	v_mfma_f32_16x16x32_bf16 v[118:121], v[150:153], v[182:185], v[118:121]
	v_mfma_f32_16x16x32_bf16 v[114:117], v[174:177], v[182:185], v[114:117]
	v_mfma_f32_16x16x32_bf16 v[102:105], v[150:153], v[198:201], v[102:105]
	v_mfma_f32_16x16x32_bf16 v[98:101], v[174:177], v[198:201], v[98:101]
	v_mfma_f32_16x16x32_bf16 v[86:89], v[150:153], v[206:209], v[86:89]
	v_mfma_f32_16x16x32_bf16 v[82:85], v[174:177], v[206:209], v[82:85]
	v_mfma_f32_16x16x32_bf16 v[70:73], v[150:153], v[214:217], v[70:73]
	v_mfma_f32_16x16x32_bf16 v[66:69], v[174:177], v[214:217], v[66:69]
	s_barrier
; #define PG8_STAGE(bufoff, gbase, voff) do { _Pragma("unroll") for (int _i = 0; _i < 2; ++_i) \
;         __builtin_amdgcn_global_load_lds((const unsigned*)((const char*)(gbase) + (voff)[_i]), (LAS unsigned*)(lds + (bufoff) + ldsw + _i * 8192), 16, 0, 0); } while (0)
; #define PG8_LDA(dst, b, h) do { _Pragma("unroll") for (int m = 0; m < 4; ++m) _Pragma("unroll") for (int k = 0; k < 2; ++k) dst[m][k] = *(const LAS bf16x8*)(lds + PG8_SA(b, h) + aoff + m * 2048 + k * 1024); } while (0)
; #define PG8_MMA(ai, bj, At, Bt) do { __builtin_amdgcn_s_setprio(1); _Pragma("unroll") for (int m = 0; m < 4; ++m) _Pragma("unroll") for (int n = 0; n < 2; ++n) _Pragma("unroll") for (int k = 0; k < 2; ++k) \
;         acc[ai][bj][m][n] = __builtin_amdgcn_mfma_f32_16x16x32_bf16(Bt[n][k], At[m][k], acc[ai][bj][m][n], 0, 0, 0); __builtin_amdgcn_s_setprio(0); } while (0)
; #define PG8_WAIT_V(n) asm volatile("s_waitcnt vmcnt(" #n ")" ::: "memory")
; #define PG8_WAIT_L(n) asm volatile("s_waitcnt lgkmcnt(" #n ")" ::: "memory")
; #define PG8_BAR __builtin_amdgcn_s_barrier()
; #define PG8_SCHED __builtin_amdgcn_sched_barrier(0)
; template <class Epi, bool ALIGN_EPI>
; __device__ __forceinline__ void gemm_phase(LAS unsigned char* lds, const Gemm g, const StaticOrder& S, const Epi& E) {
;     ...
;             PG8_LDA(At, 1, 1); PG8_STAGE(PG8_SB(1, 0), b3, voffB); PG8_STAGE(PG8_SB(1, 1), b3 + hsB, voffB); PG8_STAGE(PG8_SA(1, 0), a3, voffA);
;             PG8_WAIT_V(8); PG8_WAIT_L(0); PG8_BAR; PG8_MMA(1, 0, At, B0); PG8_MMA(1, 1, At, B1); PG8_BAR; PG8_SCHED;
;         }
;         if constexpr (ALIGN_EPI) { if (wr == 0) PG8_BAR; }
	s_add_i32 s28, s47, s30
	v_lshl_add_u64 v[186:187], v[186:187], 0, s[8:9]
	s_mov_b32 m0, s28
	s_nop 0
	global_load_lds_dwordx4 v[186:187], off
	s_add_i32 m0, s28, 0x2000
	s_add_u32 s26, s26, 0x40080
	v_lshl_add_u64 v[186:187], v[218:219], 0, s[8:9]
	s_addc_u32 s27, s27, 0
	s_add_i32 s28, s48, s30
	global_load_lds_dwordx4 v[186:187], off
	v_lshl_add_u64 v[186:187], s[26:27], 0, v[156:157]
	s_mov_b32 m0, s28
	s_nop 0
	global_load_lds_dwordx4 v[186:187], off
	v_lshl_add_u64 v[186:187], s[26:27], 0, v[160:161]
	s_add_i32 m0, s28, 0x2000
	s_nop 0
	global_load_lds_dwordx4 v[186:187], off
	v_lshl_add_u64 v[186:187], v[220:221], 0, s[8:9]
	s_mov_b32 m0, s36
	s_nop 0
	global_load_lds_dwordx4 v[186:187], off
	v_lshl_add_u64 v[186:187], v[222:223], 0, s[8:9]
	s_mov_b32 m0, s37
	s_nop 0
	global_load_lds_dwordx4 v[186:187], off
	ds_read_b128 v[178:181], v192 offset:49152
	ds_read_b128 v[182:185], v192 offset:50176
	ds_read_b128 v[194:197], v192 offset:51200
	ds_read_b128 v[198:201], v192 offset:52224
	ds_read_b128 v[202:205], v192 offset:53248
	ds_read_b128 v[206:209], v192 offset:54272
	ds_read_b128 v[210:213], v192 offset:55296
	ds_read_b128 v[214:217], v192 offset:56320
	s_waitcnt vmcnt(8)
	s_waitcnt lgkmcnt(0)
	s_barrier
	s_waitcnt lgkmcnt(0)
	v_mfma_f32_16x16x32_bf16 v[62:65], v[130:133], v[178:181], v[62:65]
	v_mfma_f32_16x16x32_bf16 v[58:61], v[138:141], v[178:181], v[58:61]
	v_mfma_f32_16x16x32_bf16 v[46:49], v[130:133], v[194:197], v[46:49]
	v_mfma_f32_16x16x32_bf16 v[42:45], v[138:141], v[194:197], v[42:45]
	v_mfma_f32_16x16x32_bf16 v[30:33], v[130:133], v[202:205], v[30:33]
	v_mfma_f32_16x16x32_bf16 v[26:29], v[138:141], v[202:205], v[26:29]
	v_mfma_f32_16x16x32_bf16 v[14:17], v[130:133], v[210:213], v[14:17]
	v_mfma_f32_16x16x32_bf16 v[10:13], v[138:141], v[210:213], v[10:13]
	v_mfma_f32_16x16x32_bf16 v[62:65], v[134:137], v[182:185], v[62:65]
	v_mfma_f32_16x16x32_bf16 v[58:61], v[142:145], v[182:185], v[58:61]
	v_mfma_f32_16x16x32_bf16 v[46:49], v[134:137], v[198:201], v[46:49]
	v_mfma_f32_16x16x32_bf16 v[42:45], v[142:145], v[198:201], v[42:45]
	v_mfma_f32_16x16x32_bf16 v[30:33], v[134:137], v[206:209], v[30:33]
	v_mfma_f32_16x16x32_bf16 v[26:29], v[142:145], v[206:209], v[26:29]
	v_mfma_f32_16x16x32_bf16 v[14:17], v[134:137], v[214:217], v[14:17]
	v_mfma_f32_16x16x32_bf16 v[10:13], v[142:145], v[214:217], v[10:13]
	v_mfma_f32_16x16x32_bf16 v[54:57], v[146:149], v[178:181], v[54:57]
	v_mfma_f32_16x16x32_bf16 v[50:53], v[170:173], v[178:181], v[50:53]
	v_mfma_f32_16x16x32_bf16 v[38:41], v[146:149], v[194:197], v[38:41]
	v_mfma_f32_16x16x32_bf16 v[34:37], v[170:173], v[194:197], v[34:37]
	v_mfma_f32_16x16x32_bf16 v[22:25], v[146:149], v[202:205], v[22:25]
	v_mfma_f32_16x16x32_bf16 v[18:21], v[170:173], v[202:205], v[18:21]
	v_mfma_f32_16x16x32_bf16 v[6:9], v[146:149], v[210:213], v[6:9]
	v_mfma_f32_16x16x32_bf16 v[2:5], v[170:173], v[210:213], v[2:5]
	v_mfma_f32_16x16x32_bf16 v[54:57], v[150:153], v[182:185], v[54:57]
	v_mfma_f32_16x16x32_bf16 v[50:53], v[174:177], v[182:185], v[50:53]
	v_mfma_f32_16x16x32_bf16 v[38:41], v[150:153], v[198:201], v[38:41]
	v_mfma_f32_16x16x32_bf16 v[34:37], v[174:177], v[198:201], v[34:37]
	v_mfma_f32_16x16x32_bf16 v[22:25], v[150:153], v[206:209], v[22:25]
	v_mfma_f32_16x16x32_bf16 v[18:21], v[174:177], v[206:209], v[18:21]
	v_mfma_f32_16x16x32_bf16 v[6:9], v[150:153], v[214:217], v[6:9]
	v_mfma_f32_16x16x32_bf16 v[2:5], v[174:177], v[214:217], v[2:5]
	s_barrier
	s_add_i32 s46, s46, 2
	s_add_u32 s24, s24, 0x100
	s_addc_u32 s25, s25, 0
	s_add_u32 s44, s44, 0x100
	s_addc_u32 s45, s45, 0
	s_cmp_gt_u32 s46, 13
	s_cbranch_scc0 .LBB0_1212
	s_and_b64 vcc, exec, s[10:11]
	s_cbranch_vccz .LBB0_1215
	s_barrier

; #define PG8_STAGE(bufoff, gbase, voff) do { _Pragma("unroll") for (int _i = 0; _i < 2; ++_i) \
;         __builtin_amdgcn_global_load_lds((const unsigned*)((const char*)(gbase) + (voff)[_i]), (LAS unsigned*)(lds + (bufoff) + ldsw + _i * 8192), 16, 0, 0); } while (0)
; #define PG8_LDA(dst, b, h) do { _Pragma("unroll") for (int m = 0; m < 4; ++m) _Pragma("unroll") for (int k = 0; k < 2; ++k) dst[m][k] = *(const LAS bf16x8*)(lds + PG8_SA(b, h) + aoff + m * 2048 + k * 1024); } while (0)
; #define PG8_LDB(dst, b, h) do { _Pragma("unroll") for (int n = 0; n < 2; ++n) _Pragma("unroll") for (int k = 0; k < 2; ++k) dst[n][k] = *(const LAS bf16x8*)(lds + PG8_SB(b, h) + boff + n * 2048 + k * 1024); } while (0)
; #define PG8_MMA(ai, bj, At, Bt) do { __builtin_amdgcn_s_setprio(1); _Pragma("unroll") for (int m = 0; m < 4; ++m) _Pragma("unroll") for (int n = 0; n < 2; ++n) _Pragma("unroll") for (int k = 0; k < 2; ++k) \
;         acc[ai][bj][m][n] = __builtin_amdgcn_mfma_f32_16x16x32_bf16(Bt[n][k], At[m][k], acc[ai][bj][m][n], 0, 0, 0); __builtin_amdgcn_s_setprio(0); } while (0)
; #define PG8_WAIT_V(n) asm volatile("s_waitcnt vmcnt(" #n ")" ::: "memory")
; #define PG8_WAIT_L(n) asm volatile("s_waitcnt lgkmcnt(" #n ")" ::: "memory")
; #define PG8_BAR __builtin_amdgcn_s_barrier()
; #define PG8_SCHED __builtin_amdgcn_sched_barrier(0)
; template <class Epi, bool ALIGN_EPI>
; __device__ __forceinline__ void gemm_phase(LAS unsigned char* lds, const Gemm g, const StaticOrder& S, const Epi& E) {
;     ...
;             PG8_LDB(B0, 0, 0); PG8_LDB(B1, 0, 1); PG8_SCHED; PG8_LDA(At, 0, 0); PG8_STAGE(PG8_SA(1, 1), a1 + hsA, voffA);
;             PG8_WAIT_V(8); PG8_WAIT_L(0); PG8_BAR; PG8_MMA(0, 0, At, B0); PG8_MMA(0, 1, At, B1); PG8_BAR; PG8_SCHED;
;             PG8_LDA(At, 0, 1); PG8_STAGE(PG8_SB(0, 0), b2, voffB); PG8_STAGE(PG8_SB(0, 1), b2 + hsB, voffB); PG8_STAGE(PG8_SA(0, 0), a2, voffA);
;             PG8_WAIT_V(8); PG8_WAIT_L(0); PG8_BAR; PG8_MMA(1, 0, At, B0); PG8_MMA(1, 1, At, B1); PG8_BAR; PG8_SCHED;
.LBB0_1299:
	s_add_u32 s22, s20, 0xfffc0080
	s_addc_u32 s23, s21, -1
	s_cmp_eq_u32 s48, 12
	s_cselect_b32 s25, s11, s23
	s_cselect_b32 s24, s44, s22
	s_cselect_b32 s23, s13, s47
	s_cselect_b32 s22, s45, s46
	v_lshl_add_u64 v[220:221], s[20:21], 0, v[140:141]
	s_add_i32 m0, s19, 0xc000
	s_nop 0
	global_load_lds_dwordx4 v[220:221], off
	v_lshl_add_u64 v[220:221], s[20:21], 0, v[142:143]
	s_add_i32 m0, s19, 0xe000
	s_nop 0
	global_load_lds_dwordx4 v[220:221], off
	ds_read_b128 v[156:159], v151
	ds_read_b128 v[160:163], v151 offset:1024
	ds_read_b128 v[164:167], v151 offset:2048
	ds_read_b128 v[168:171], v151 offset:3072
	ds_read_b128 v[172:175], v152
	ds_read_b128 v[176:179], v152 offset:1024
	ds_read_b128 v[180:183], v152 offset:2048
	ds_read_b128 v[184:187], v152 offset:3072
	ds_read_b128 v[188:191], v153
	ds_read_b128 v[192:195], v153 offset:1024
	ds_read_b128 v[196:199], v153 offset:2048
	ds_read_b128 v[200:203], v153 offset:3072
	ds_read_b128 v[204:207], v153 offset:4096
	ds_read_b128 v[208:211], v153 offset:5120
	ds_read_b128 v[212:215], v153 offset:6144
	ds_read_b128 v[216:219], v153 offset:7168
	s_waitcnt vmcnt(8)
	s_waitcnt lgkmcnt(0)
	s_barrier
	s_waitcnt lgkmcnt(0)
	v_mfma_f32_16x16x32_bf16 v[118:121], v[156:159], v[188:191], v[118:121]
	v_mfma_f32_16x16x32_bf16 v[114:117], v[164:167], v[188:191], v[114:117]
	v_mfma_f32_16x16x32_bf16 v[106:109], v[156:159], v[196:199], v[106:109]
	v_mfma_f32_16x16x32_bf16 v[102:105], v[164:167], v[196:199], v[102:105]
	v_mfma_f32_16x16x32_bf16 v[94:97], v[156:159], v[204:207], v[94:97]
	v_mfma_f32_16x16x32_bf16 v[90:93], v[164:167], v[204:207], v[90:93]
	v_mfma_f32_16x16x32_bf16 v[78:81], v[156:159], v[212:215], v[78:81]
	v_mfma_f32_16x16x32_bf16 v[74:77], v[164:167], v[212:215], v[74:77]
	v_mfma_f32_16x16x32_bf16 v[118:121], v[160:163], v[192:195], v[118:121]
	v_mfma_f32_16x16x32_bf16 v[114:117], v[168:171], v[192:195], v[114:117]
	v_mfma_f32_16x16x32_bf16 v[106:109], v[160:163], v[200:203], v[106:109]
	v_mfma_f32_16x16x32_bf16 v[102:105], v[168:171], v[200:203], v[102:105]
	v_mfma_f32_16x16x32_bf16 v[94:97], v[160:163], v[208:211], v[94:97]
	v_mfma_f32_16x16x32_bf16 v[90:93], v[168:171], v[208:211], v[90:93]
	v_mfma_f32_16x16x32_bf16 v[78:81], v[160:163], v[216:219], v[78:81]
	v_mfma_f32_16x16x32_bf16 v[74:77], v[168:171], v[216:219], v[74:77]
	v_mfma_f32_16x16x32_bf16 v[126:129], v[172:175], v[188:191], v[126:129]
	v_mfma_f32_16x16x32_bf16 v[122:125], v[180:183], v[188:191], v[122:125]
	v_mfma_f32_16x16x32_bf16 v[110:113], v[172:175], v[196:199], v[110:113]
	v_mfma_f32_16x16x32_bf16 v[98:101], v[180:183], v[196:199], v[98:101]
	v_mfma_f32_16x16x32_bf16 v[86:89], v[172:175], v[204:207], v[86:89]
	v_mfma_f32_16x16x32_bf16 v[82:85], v[180:183], v[204:207], v[82:85]
	v_mfma_f32_16x16x32_bf16 v[70:73], v[172:175], v[212:215], v[70:73]
	v_mfma_f32_16x16x32_bf16 v[66:69], v[180:183], v[212:215], v[66:69]
	v_mfma_f32_16x16x32_bf16 v[126:129], v[176:179], v[192:195], v[126:129]
	v_mfma_f32_16x16x32_bf16 v[122:125], v[184:187], v[192:195], v[122:125]
	v_mfma_f32_16x16x32_bf16 v[110:113], v[176:179], v[200:203], v[110:113]
	v_mfma_f32_16x16x32_bf16 v[98:101], v[184:187], v[200:203], v[98:101]
	v_mfma_f32_16x16x32_bf16 v[86:89], v[176:179], v[208:211], v[86:89]
	v_mfma_f32_16x16x32_bf16 v[82:85], v[184:187], v[208:211], v[82:85]
	v_mfma_f32_16x16x32_bf16 v[70:73], v[176:179], v[216:219], v[70:73]
	v_mfma_f32_16x16x32_bf16 v[66:69], v[184:187], v[216:219], v[66:69]
	s_barrier
	s_add_i32 s49, s40, s26
	v_lshl_add_u64 v[220:221], s[22:23], 0, v[134:135]
	s_mov_b32 m0, s49
	s_nop 0
	global_load_lds_dwordx4 v[220:221], off
	s_add_i32 m0, s49, 0x2000
	s_add_u32 s50, s22, 0x40000
	v_lshl_add_u64 v[222:223], s[22:23], 0, v[130:131]
	s_addc_u32 s51, s23, 0
	s_add_i32 s49, s41, s26
	global_load_lds_dwordx4 v[222:223], off
	v_lshl_add_u64 v[224:225], s[50:51], 0, v[134:135]
	s_mov_b32 m0, s49
	v_lshl_add_u64 v[226:227], s[24:25], 0, v[132:133]
	global_load_lds_dwordx4 v[224:225], off
	v_lshl_add_u64 v[224:225], s[50:51], 0, v[130:131]
	s_add_i32 m0, s49, 0x2000
	s_nop 0
	global_load_lds_dwordx4 v[224:225], off
	v_lshl_add_u64 v[224:225], s[24:25], 0, v[136:137]
	s_mov_b32 m0, s19
	s_nop 0
	global_load_lds_dwordx4 v[224:225], off
	s_mov_b32 m0, s29
	s_nop 0
	global_load_lds_dwordx4 v[226:227], off
	ds_read_b128 v[188:191], v153 offset:16384
	ds_read_b128 v[192:195], v153 offset:17408
	ds_read_b128 v[196:199], v153 offset:18432
	ds_read_b128 v[200:203], v153 offset:19456
	ds_read_b128 v[204:207], v153 offset:20480
	ds_read_b128 v[208:211], v153 offset:21504
	ds_read_b128 v[212:215], v153 offset:22528
	ds_read_b128 v[216:219], v153 offset:23552
	s_waitcnt vmcnt(8)
	s_waitcnt lgkmcnt(0)
	s_barrier
; #define PG8_STAGE(bufoff, gbase, voff) do { _Pragma("unroll") for (int _i = 0; _i < 2; ++_i) \
;         __builtin_amdgcn_global_load_lds((const unsigned*)((const char*)(gbase) + (voff)[_i]), (LAS unsigned*)(lds + (bufoff) + ldsw + _i * 8192), 16, 0, 0); } while (0)
; #define PG8_LDA(dst, b, h) do { _Pragma("unroll") for (int m = 0; m < 4; ++m) _Pragma("unroll") for (int k = 0; k < 2; ++k) dst[m][k] = *(const LAS bf16x8*)(lds + PG8_SA(b, h) + aoff + m * 2048 + k * 1024); } while (0)
; #define PG8_LDB(dst, b, h) do { _Pragma("unroll") for (int n = 0; n < 2; ++n) _Pragma("unroll") for (int k = 0; k < 2; ++k) dst[n][k] = *(const LAS bf16x8*)(lds + PG8_SB(b, h) + boff + n * 2048 + k * 1024); } while (0)
; #define PG8_MMA(ai, bj, At, Bt) do { __builtin_amdgcn_s_setprio(1); _Pragma("unroll") for (int m = 0; m < 4; ++m) _Pragma("unroll") for (int n = 0; n < 2; ++n) _Pragma("unroll") for (int k = 0; k < 2; ++k) \
;         acc[ai][bj][m][n] = __builtin_amdgcn_mfma_f32_16x16x32_bf16(Bt[n][k], At[m][k], acc[ai][bj][m][n], 0, 0, 0); __builtin_amdgcn_s_setprio(0); } while (0)
; #define PG8_WAIT_V(n) asm volatile("s_waitcnt vmcnt(" #n ")" ::: "memory")
; #define PG8_WAIT_L(n) asm volatile("s_waitcnt lgkmcnt(" #n ")" ::: "memory")
; #define PG8_BAR __builtin_amdgcn_s_barrier()
; #define PG8_SCHED __builtin_amdgcn_sched_barrier(0)
; template <class Epi, bool ALIGN_EPI>
; __device__ __forceinline__ void gemm_phase(LAS unsigned char* lds, const Gemm g, const StaticOrder& S, const Epi& E) {
;     ...
;             PG8_WAIT_V(8); PG8_WAIT_L(0); PG8_BAR; PG8_MMA(1, 0, At, B0); PG8_MMA(1, 1, At, B1); PG8_BAR; PG8_SCHED;
;             PG8_LDB(B0, 1, 0); PG8_LDB(B1, 1, 1); PG8_SCHED; PG8_LDA(At, 1, 0); PG8_STAGE(PG8_SA(0, 1), a2 + hsA, voffA);
;             PG8_WAIT_V(8); PG8_WAIT_L(0); PG8_BAR; PG8_MMA(0, 0, At, B0); PG8_MMA(0, 1, At, B1); PG8_BAR; PG8_SCHED;
	s_waitcnt lgkmcnt(0)
	v_mfma_f32_16x16x32_bf16 v[62:65], v[156:159], v[188:191], v[62:65]
	v_mfma_f32_16x16x32_bf16 v[58:61], v[164:167], v[188:191], v[58:61]
	v_mfma_f32_16x16x32_bf16 v[46:49], v[156:159], v[196:199], v[46:49]
	v_mfma_f32_16x16x32_bf16 v[42:45], v[164:167], v[196:199], v[42:45]
	v_mfma_f32_16x16x32_bf16 v[30:33], v[156:159], v[204:207], v[30:33]
	v_mfma_f32_16x16x32_bf16 v[26:29], v[164:167], v[204:207], v[26:29]
	v_mfma_f32_16x16x32_bf16 v[14:17], v[156:159], v[212:215], v[14:17]
	v_mfma_f32_16x16x32_bf16 v[10:13], v[164:167], v[212:215], v[10:13]
	v_mfma_f32_16x16x32_bf16 v[62:65], v[160:163], v[192:195], v[62:65]
	v_mfma_f32_16x16x32_bf16 v[58:61], v[168:171], v[192:195], v[58:61]
	v_mfma_f32_16x16x32_bf16 v[46:49], v[160:163], v[200:203], v[46:49]
	v_mfma_f32_16x16x32_bf16 v[42:45], v[168:171], v[200:203], v[42:45]
	v_mfma_f32_16x16x32_bf16 v[30:33], v[160:163], v[208:211], v[30:33]
	v_mfma_f32_16x16x32_bf16 v[26:29], v[168:171], v[208:211], v[26:29]
	v_mfma_f32_16x16x32_bf16 v[14:17], v[160:163], v[216:219], v[14:17]
	v_mfma_f32_16x16x32_bf16 v[10:13], v[168:171], v[216:219], v[10:13]
	v_mfma_f32_16x16x32_bf16 v[54:57], v[172:175], v[188:191], v[54:57]
	v_mfma_f32_16x16x32_bf16 v[50:53], v[180:183], v[188:191], v[50:53]
	v_mfma_f32_16x16x32_bf16 v[38:41], v[172:175], v[196:199], v[38:41]
	v_mfma_f32_16x16x32_bf16 v[34:37], v[180:183], v[196:199], v[34:37]
	v_mfma_f32_16x16x32_bf16 v[22:25], v[172:175], v[204:207], v[22:25]
	v_mfma_f32_16x16x32_bf16 v[18:21], v[180:183], v[204:207], v[18:21]
	v_mfma_f32_16x16x32_bf16 v[6:9], v[172:175], v[212:215], v[6:9]
	v_mfma_f32_16x16x32_bf16 v[2:5], v[180:183], v[212:215], v[2:5]
	v_mfma_f32_16x16x32_bf16 v[54:57], v[176:179], v[192:195], v[54:57]
	v_mfma_f32_16x16x32_bf16 v[50:53], v[184:187], v[192:195], v[50:53]
	v_mfma_f32_16x16x32_bf16 v[38:41], v[176:179], v[200:203], v[38:41]
	v_mfma_f32_16x16x32_bf16 v[34:37], v[184:187], v[200:203], v[34:37]
	v_mfma_f32_16x16x32_bf16 v[22:25], v[176:179], v[208:211], v[22:25]
	v_mfma_f32_16x16x32_bf16 v[18:21], v[184:187], v[208:211], v[18:21]
	v_mfma_f32_16x16x32_bf16 v[6:9], v[176:179], v[216:219], v[6:9]
	v_mfma_f32_16x16x32_bf16 v[2:5], v[184:187], v[216:219], v[2:5]
	s_barrier
	s_add_i32 s49, 0, 0x18000
	s_add_i32 s50, 0, 0x1c000
	s_add_u32 s24, s24, 0x40000
	s_addc_u32 s25, s25, 0
	s_mov_b32 m0, s30
	v_lshl_add_u64 v[228:229], s[24:25], 0, v[136:137]
	global_load_lds_dwordx4 v[228:229], off
	v_lshl_add_u64 v[228:229], s[24:25], 0, v[132:133]
	s_mov_b32 m0, s31
	s_nop 0
	global_load_lds_dwordx4 v[228:229], off
	v_add_u32_e32 v138, s49, v150
	ds_read_b128 v[156:159], v138
	ds_read_b128 v[160:163], v138 offset:1024
	ds_read_b128 v[164:167], v138 offset:2048
	ds_read_b128 v[168:171], v138 offset:3072
	v_add_u32_e32 v138, s50, v150
	ds_read_b128 v[172:175], v138
	ds_read_b128 v[176:179], v138 offset:1024
	ds_read_b128 v[180:183], v138 offset:2048
	ds_read_b128 v[184:187], v138 offset:3072
	ds_read_b128 v[188:191], v153 offset:32768
	ds_read_b128 v[192:195], v153 offset:33792
	ds_read_b128 v[196:199], v153 offset:34816
	ds_read_b128 v[200:203], v153 offset:35840
	ds_read_b128 v[204:207], v153 offset:36864
	ds_read_b128 v[208:211], v153 offset:37888
	ds_read_b128 v[212:215], v153 offset:38912
	ds_read_b128 v[216:219], v153 offset:39936
	s_waitcnt vmcnt(8)
	s_waitcnt lgkmcnt(0)
	s_barrier
	s_waitcnt lgkmcnt(0)
	v_mfma_f32_16x16x32_bf16 v[118:121], v[156:159], v[188:191], v[118:121]
	v_mfma_f32_16x16x32_bf16 v[114:117], v[164:167], v[188:191], v[114:117]
	v_mfma_f32_16x16x32_bf16 v[106:109], v[156:159], v[196:199], v[106:109]
	v_mfma_f32_16x16x32_bf16 v[102:105], v[164:167], v[196:199], v[102:105]
	v_mfma_f32_16x16x32_bf16 v[94:97], v[156:159], v[204:207], v[94:97]
	v_mfma_f32_16x16x32_bf16 v[90:93], v[164:167], v[204:207], v[90:93]
	v_mfma_f32_16x16x32_bf16 v[78:81], v[156:159], v[212:215], v[78:81]
	v_mfma_f32_16x16x32_bf16 v[74:77], v[164:167], v[212:215], v[74:77]
	v_mfma_f32_16x16x32_bf16 v[118:121], v[160:163], v[192:195], v[118:121]
	v_mfma_f32_16x16x32_bf16 v[114:117], v[168:171], v[192:195], v[114:117]
	v_mfma_f32_16x16x32_bf16 v[106:109], v[160:163], v[200:203], v[106:109]
	v_mfma_f32_16x16x32_bf16 v[102:105], v[168:171], v[200:203], v[102:105]
	v_mfma_f32_16x16x32_bf16 v[94:97], v[160:163], v[208:211], v[94:97]
	v_mfma_f32_16x16x32_bf16 v[90:93], v[168:171], v[208:211], v[90:93]
	v_mfma_f32_16x16x32_bf16 v[78:81], v[160:163], v[216:219], v[78:81]
	v_mfma_f32_16x16x32_bf16 v[74:77], v[168:171], v[216:219], v[74:77]
	v_mfma_f32_16x16x32_bf16 v[126:129], v[172:175], v[188:191], v[126:129]
	v_mfma_f32_16x16x32_bf16 v[122:125], v[180:183], v[188:191], v[122:125]
	v_mfma_f32_16x16x32_bf16 v[110:113], v[172:175], v[196:199], v[110:113]
	v_mfma_f32_16x16x32_bf16 v[98:101], v[180:183], v[196:199], v[98:101]
	v_mfma_f32_16x16x32_bf16 v[86:89], v[172:175], v[204:207], v[86:89]
	v_mfma_f32_16x16x32_bf16 v[82:85], v[180:183], v[204:207], v[82:85]
	v_mfma_f32_16x16x32_bf16 v[70:73], v[172:175], v[212:215], v[70:73]
	v_mfma_f32_16x16x32_bf16 v[66:69], v[180:183], v[212:215], v[66:69]
	v_mfma_f32_16x16x32_bf16 v[126:129], v[176:179], v[192:195], v[126:129]
	v_mfma_f32_16x16x32_bf16 v[122:125], v[184:187], v[192:195], v[122:125]
	v_mfma_f32_16x16x32_bf16 v[110:113], v[176:179], v[200:203], v[110:113]
	v_mfma_f32_16x16x32_bf16 v[98:101], v[184:187], v[200:203], v[98:101]
	v_mfma_f32_16x16x32_bf16 v[86:89], v[176:179], v[208:211], v[86:89]
	v_mfma_f32_16x16x32_bf16 v[82:85], v[184:187], v[208:211], v[82:85]
	v_mfma_f32_16x16x32_bf16 v[70:73], v[176:179], v[216:219], v[70:73]
	v_mfma_f32_16x16x32_bf16 v[66:69], v[184:187], v[216:219], v[66:69]
	s_barrier
; #define PG8_STAGE(bufoff, gbase, voff) do { _Pragma("unroll") for (int _i = 0; _i < 2; ++_i) \
;         __builtin_amdgcn_global_load_lds((const unsigned*)((const char*)(gbase) + (voff)[_i]), (LAS unsigned*)(lds + (bufoff) + ldsw + _i * 8192), 16, 0, 0); } while (0)
; #define PG8_LDA(dst, b, h) do { _Pragma("unroll") for (int m = 0; m < 4; ++m) _Pragma("unroll") for (int k = 0; k < 2; ++k) dst[m][k] = *(const LAS bf16x8*)(lds + PG8_SA(b, h) + aoff + m * 2048 + k * 1024); } while (0)
; #define PG8_MMA(ai, bj, At, Bt) do { __builtin_amdgcn_s_setprio(1); _Pragma("unroll") for (int m = 0; m < 4; ++m) _Pragma("unroll") for (int n = 0; n < 2; ++n) _Pragma("unroll") for (int k = 0; k < 2; ++k) \
;         acc[ai][bj][m][n] = __builtin_amdgcn_mfma_f32_16x16x32_bf16(Bt[n][k], At[m][k], acc[ai][bj][m][n], 0, 0, 0); __builtin_amdgcn_s_setprio(0); } while (0)
; #define PG8_WAIT_V(n) asm volatile("s_waitcnt vmcnt(" #n ")" ::: "memory")
; #define PG8_WAIT_L(n) asm volatile("s_waitcnt lgkmcnt(" #n ")" ::: "memory")
; #define PG8_BAR __builtin_amdgcn_s_barrier()
; #define PG8_SCHED __builtin_amdgcn_sched_barrier(0)
; template <class Epi, bool ALIGN_EPI>
; __device__ __forceinline__ void gemm_phase(LAS unsigned char* lds, const Gemm g, const StaticOrder& S, const Epi& E) {
;     ...
;             PG8_LDA(At, 1, 1); PG8_STAGE(PG8_SB(1, 0), b3, voffB); PG8_STAGE(PG8_SB(1, 1), b3 + hsB, voffB); PG8_STAGE(PG8_SA(1, 0), a3, voffA);
;             PG8_WAIT_V(8); PG8_WAIT_L(0); PG8_BAR; PG8_MMA(1, 0, At, B0); PG8_MMA(1, 1, At, B1); PG8_BAR; PG8_SCHED;
;         }
;         if constexpr (ALIGN_EPI) { if (wr == 0) PG8_BAR; }
	s_add_i32 s24, s49, s26
	v_lshl_add_u64 v[220:221], v[220:221], 0, s[6:7]
	s_mov_b32 m0, s24
	s_nop 0
	global_load_lds_dwordx4 v[220:221], off
	s_add_i32 m0, s24, 0x2000
	s_add_u32 s22, s22, 0x40080
	v_lshl_add_u64 v[220:221], v[222:223], 0, s[6:7]
	s_addc_u32 s23, s23, 0
	s_add_i32 s24, s50, s26
	global_load_lds_dwordx4 v[220:221], off
	v_lshl_add_u64 v[220:221], s[22:23], 0, v[134:135]
	s_mov_b32 m0, s24
	s_nop 0
	global_load_lds_dwordx4 v[220:221], off
	v_lshl_add_u64 v[220:221], s[22:23], 0, v[130:131]
	s_add_i32 m0, s24, 0x2000
	s_nop 0
	global_load_lds_dwordx4 v[220:221], off
	v_lshl_add_u64 v[220:221], v[224:225], 0, s[6:7]
	s_mov_b32 m0, s36
	s_nop 0
	global_load_lds_dwordx4 v[220:221], off
	v_lshl_add_u64 v[220:221], v[226:227], 0, s[6:7]
	s_mov_b32 m0, s37
	s_nop 0
	global_load_lds_dwordx4 v[220:221], off
	ds_read_b128 v[188:191], v153 offset:49152
	ds_read_b128 v[192:195], v153 offset:50176
	ds_read_b128 v[196:199], v153 offset:51200
	ds_read_b128 v[200:203], v153 offset:52224
	ds_read_b128 v[204:207], v153 offset:53248
	ds_read_b128 v[208:211], v153 offset:54272
	ds_read_b128 v[212:215], v153 offset:55296
	ds_read_b128 v[216:219], v153 offset:56320
	s_waitcnt vmcnt(8)
	s_waitcnt lgkmcnt(0)
	s_barrier
	s_waitcnt lgkmcnt(0)
	v_mfma_f32_16x16x32_bf16 v[62:65], v[156:159], v[188:191], v[62:65]
	v_mfma_f32_16x16x32_bf16 v[58:61], v[164:167], v[188:191], v[58:61]
	v_mfma_f32_16x16x32_bf16 v[46:49], v[156:159], v[196:199], v[46:49]
	v_mfma_f32_16x16x32_bf16 v[42:45], v[164:167], v[196:199], v[42:45]
	v_mfma_f32_16x16x32_bf16 v[30:33], v[156:159], v[204:207], v[30:33]
	v_mfma_f32_16x16x32_bf16 v[26:29], v[164:167], v[204:207], v[26:29]
	v_mfma_f32_16x16x32_bf16 v[14:17], v[156:159], v[212:215], v[14:17]
	v_mfma_f32_16x16x32_bf16 v[10:13], v[164:167], v[212:215], v[10:13]
	v_mfma_f32_16x16x32_bf16 v[62:65], v[160:163], v[192:195], v[62:65]
	v_mfma_f32_16x16x32_bf16 v[58:61], v[168:171], v[192:195], v[58:61]
	v_mfma_f32_16x16x32_bf16 v[46:49], v[160:163], v[200:203], v[46:49]
	v_mfma_f32_16x16x32_bf16 v[42:45], v[168:171], v[200:203], v[42:45]
	v_mfma_f32_16x16x32_bf16 v[30:33], v[160:163], v[208:211], v[30:33]
	v_mfma_f32_16x16x32_bf16 v[26:29], v[168:171], v[208:211], v[26:29]
	v_mfma_f32_16x16x32_bf16 v[14:17], v[160:163], v[216:219], v[14:17]
	v_mfma_f32_16x16x32_bf16 v[10:13], v[168:171], v[216:219], v[10:13]
	v_mfma_f32_16x16x32_bf16 v[54:57], v[172:175], v[188:191], v[54:57]
	v_mfma_f32_16x16x32_bf16 v[50:53], v[180:183], v[188:191], v[50:53]
	v_mfma_f32_16x16x32_bf16 v[38:41], v[172:175], v[196:199], v[38:41]
	v_mfma_f32_16x16x32_bf16 v[34:37], v[180:183], v[196:199], v[34:37]
	v_mfma_f32_16x16x32_bf16 v[22:25], v[172:175], v[204:207], v[22:25]
	v_mfma_f32_16x16x32_bf16 v[18:21], v[180:183], v[204:207], v[18:21]
	v_mfma_f32_16x16x32_bf16 v[6:9], v[172:175], v[212:215], v[6:9]
	v_mfma_f32_16x16x32_bf16 v[2:5], v[180:183], v[212:215], v[2:5]
	v_mfma_f32_16x16x32_bf16 v[54:57], v[176:179], v[192:195], v[54:57]
	v_mfma_f32_16x16x32_bf16 v[50:53], v[184:187], v[192:195], v[50:53]
	v_mfma_f32_16x16x32_bf16 v[38:41], v[176:179], v[200:203], v[38:41]
	v_mfma_f32_16x16x32_bf16 v[34:37], v[184:187], v[200:203], v[34:37]
	v_mfma_f32_16x16x32_bf16 v[22:25], v[176:179], v[208:211], v[22:25]
	v_mfma_f32_16x16x32_bf16 v[18:21], v[184:187], v[208:211], v[18:21]
	v_mfma_f32_16x16x32_bf16 v[6:9], v[176:179], v[216:219], v[6:9]
	v_mfma_f32_16x16x32_bf16 v[2:5], v[184:187], v[216:219], v[2:5]
	s_barrier
	s_add_i32 s48, s48, 2
	s_add_u32 s20, s20, 0x100
	s_addc_u32 s21, s21, 0
	s_add_u32 s46, s46, 0x100
	s_addc_u32 s47, s47, 0
	s_cmp_gt_u32 s48, 13
	s_cbranch_scc0 .LBB0_1299
	s_and_b64 vcc, exec, s[8:9]
	s_cbranch_vccz .LBB0_1302
	s_barrier

; #define PG8_STAGE(bufoff, gbase, voff) do { _Pragma("unroll") for (int _i = 0; _i < 2; ++_i) \
;         __builtin_amdgcn_global_load_lds((const unsigned*)((const char*)(gbase) + (voff)[_i]), (LAS unsigned*)(lds + (bufoff) + ldsw + _i * 8192), 16, 0, 0); } while (0)
; #define PG8_LDA(dst, b, h) do { _Pragma("unroll") for (int m = 0; m < 4; ++m) _Pragma("unroll") for (int k = 0; k < 2; ++k) dst[m][k] = *(const LAS bf16x8*)(lds + PG8_SA(b, h) + aoff + m * 2048 + k * 1024); } while (0)
; #define PG8_LDB(dst, b, h) do { _Pragma("unroll") for (int n = 0; n < 2; ++n) _Pragma("unroll") for (int k = 0; k < 2; ++k) dst[n][k] = *(const LAS bf16x8*)(lds + PG8_SB(b, h) + boff + n * 2048 + k * 1024); } while (0)
; #define PG8_MMA(ai, bj, At, Bt) do { __builtin_amdgcn_s_setprio(1); _Pragma("unroll") for (int m = 0; m < 4; ++m) _Pragma("unroll") for (int n = 0; n < 2; ++n) _Pragma("unroll") for (int k = 0; k < 2; ++k) \
;         acc[ai][bj][m][n] = __builtin_amdgcn_mfma_f32_16x16x32_bf16(Bt[n][k], At[m][k], acc[ai][bj][m][n], 0, 0, 0); __builtin_amdgcn_s_setprio(0); } while (0)
; #define PG8_WAIT_V(n) asm volatile("s_waitcnt vmcnt(" #n ")" ::: "memory")
; #define PG8_WAIT_L(n) asm volatile("s_waitcnt lgkmcnt(" #n ")" ::: "memory")
; #define PG8_BAR __builtin_amdgcn_s_barrier()
; #define PG8_SCHED __builtin_amdgcn_sched_barrier(0)
; template <class Epi, bool ALIGN_EPI>
; __device__ __forceinline__ void gemm_phase(LAS unsigned char* lds, const Gemm g, const StaticOrder& S, const Epi& E) {
;     ...
;             PG8_LDB(B0, 0, 0); PG8_LDB(B1, 0, 1); PG8_SCHED; PG8_LDA(At, 0, 0); PG8_STAGE(PG8_SA(1, 1), a1 + hsA, voffA);
;             PG8_WAIT_V(8); PG8_WAIT_L(0); PG8_BAR; PG8_MMA(0, 0, At, B0); PG8_MMA(0, 1, At, B1); PG8_BAR; PG8_SCHED;
;             PG8_LDA(At, 0, 1); PG8_STAGE(PG8_SB(0, 0), b2, voffB); PG8_STAGE(PG8_SB(0, 1), b2 + hsB, voffB); PG8_STAGE(PG8_SA(0, 0), a2, voffA);
;             PG8_WAIT_V(8); PG8_WAIT_L(0); PG8_BAR; PG8_MMA(1, 0, At, B0); PG8_MMA(1, 1, At, B1); PG8_BAR; PG8_SCHED;
.LBB0_1405:
	s_add_u32 s18, s16, 0x4000
	s_addc_u32 s19, s17, 0
	s_cmp_eq_u32 s44, 40
	s_cselect_b32 s22, s6, s18
	s_cselect_b32 s23, s7, s19
	s_cselect_b32 s20, s14, s42
	s_cselect_b32 s21, s15, s43
	s_add_u32 s18, s22, 0x8000
	s_addc_u32 s19, s23, 0
	v_lshl_add_u64 v[186:187], s[16:17], 0, v[162:163]
	s_add_i32 m0, s25, 0xc000
	s_nop 0
	global_load_lds_dwordx4 v[186:187], off
	v_lshl_add_u64 v[186:187], s[16:17], 0, v[164:165]
	s_add_i32 m0, s25, 0xe000
	s_nop 0
	global_load_lds_dwordx4 v[186:187], off
	ds_read_b128 v[130:133], v190
	ds_read_b128 v[134:137], v190 offset:1024
	ds_read_b128 v[138:141], v190 offset:2048
	ds_read_b128 v[142:145], v190 offset:3072
	ds_read_b128 v[146:149], v191
	ds_read_b128 v[150:153], v191 offset:1024
	ds_read_b128 v[170:173], v191 offset:2048
	ds_read_b128 v[174:177], v191 offset:3072
	ds_read_b128 v[178:181], v192
	ds_read_b128 v[182:185], v192 offset:1024
	ds_read_b128 v[194:197], v192 offset:2048
	ds_read_b128 v[198:201], v192 offset:3072
	ds_read_b128 v[202:205], v192 offset:4096
	ds_read_b128 v[206:209], v192 offset:5120
	ds_read_b128 v[210:213], v192 offset:6144
	ds_read_b128 v[214:217], v192 offset:7168
	s_waitcnt vmcnt(8)
	s_waitcnt lgkmcnt(0)
	s_barrier
	s_waitcnt lgkmcnt(0)
	v_mfma_f32_16x16x32_bf16 v[126:129], v[130:133], v[178:181], v[126:129]
	v_mfma_f32_16x16x32_bf16 v[122:125], v[138:141], v[178:181], v[122:125]
	v_mfma_f32_16x16x32_bf16 v[110:113], v[130:133], v[194:197], v[110:113]
	v_mfma_f32_16x16x32_bf16 v[106:109], v[138:141], v[194:197], v[106:109]
	v_mfma_f32_16x16x32_bf16 v[94:97], v[130:133], v[202:205], v[94:97]
	v_mfma_f32_16x16x32_bf16 v[90:93], v[138:141], v[202:205], v[90:93]
	v_mfma_f32_16x16x32_bf16 v[78:81], v[130:133], v[210:213], v[78:81]
	v_mfma_f32_16x16x32_bf16 v[74:77], v[138:141], v[210:213], v[74:77]
	v_mfma_f32_16x16x32_bf16 v[126:129], v[134:137], v[182:185], v[126:129]
	v_mfma_f32_16x16x32_bf16 v[122:125], v[142:145], v[182:185], v[122:125]
	v_mfma_f32_16x16x32_bf16 v[110:113], v[134:137], v[198:201], v[110:113]
	v_mfma_f32_16x16x32_bf16 v[106:109], v[142:145], v[198:201], v[106:109]
	v_mfma_f32_16x16x32_bf16 v[94:97], v[134:137], v[206:209], v[94:97]
	v_mfma_f32_16x16x32_bf16 v[90:93], v[142:145], v[206:209], v[90:93]
	v_mfma_f32_16x16x32_bf16 v[78:81], v[134:137], v[214:217], v[78:81]
	v_mfma_f32_16x16x32_bf16 v[74:77], v[142:145], v[214:217], v[74:77]
	v_mfma_f32_16x16x32_bf16 v[118:121], v[146:149], v[178:181], v[118:121]
	v_mfma_f32_16x16x32_bf16 v[114:117], v[170:173], v[178:181], v[114:117]
	v_mfma_f32_16x16x32_bf16 v[102:105], v[146:149], v[194:197], v[102:105]
	v_mfma_f32_16x16x32_bf16 v[98:101], v[170:173], v[194:197], v[98:101]
	v_mfma_f32_16x16x32_bf16 v[86:89], v[146:149], v[202:205], v[86:89]
	v_mfma_f32_16x16x32_bf16 v[82:85], v[170:173], v[202:205], v[82:85]
	v_mfma_f32_16x16x32_bf16 v[70:73], v[146:149], v[210:213], v[70:73]
	v_mfma_f32_16x16x32_bf16 v[66:69], v[170:173], v[210:213], v[66:69]
	v_mfma_f32_16x16x32_bf16 v[118:121], v[150:153], v[182:185], v[118:121]
	v_mfma_f32_16x16x32_bf16 v[114:117], v[174:177], v[182:185], v[114:117]
	v_mfma_f32_16x16x32_bf16 v[102:105], v[150:153], v[198:201], v[102:105]
	v_mfma_f32_16x16x32_bf16 v[98:101], v[174:177], v[198:201], v[98:101]
	v_mfma_f32_16x16x32_bf16 v[86:89], v[150:153], v[206:209], v[86:89]
	v_mfma_f32_16x16x32_bf16 v[82:85], v[174:177], v[206:209], v[82:85]
	v_mfma_f32_16x16x32_bf16 v[70:73], v[150:153], v[214:217], v[70:73]
	v_mfma_f32_16x16x32_bf16 v[66:69], v[174:177], v[214:217], v[66:69]
	s_barrier
	s_add_i32 s45, s36, s24
	v_lshl_add_u64 v[186:187], s[20:21], 0, v[156:157]
	s_mov_b32 m0, s45
	s_nop 0
	global_load_lds_dwordx4 v[186:187], off
	s_add_i32 m0, s45, 0x2000
	s_add_u32 s46, s20, 0xb0000
	v_lshl_add_u64 v[218:219], s[20:21], 0, v[160:161]
	s_addc_u32 s47, s21, 0
	s_add_i32 s45, s37, s24
	global_load_lds_dwordx4 v[218:219], off
	v_lshl_add_u64 v[220:221], s[46:47], 0, v[156:157]
	s_mov_b32 m0, s45
	s_nop 0
	global_load_lds_dwordx4 v[220:221], off
	v_lshl_add_u64 v[220:221], s[46:47], 0, v[160:161]
	s_add_i32 m0, s45, 0x2000
	s_nop 0
	global_load_lds_dwordx4 v[220:221], off
	v_lshl_add_u64 v[220:221], s[22:23], 0, v[154:155]
	s_mov_b32 m0, s25
	s_nop 0
	global_load_lds_dwordx4 v[220:221], off
	v_lshl_add_u64 v[220:221], s[22:23], 0, v[158:159]
	s_mov_b32 m0, s26
	s_nop 0
	global_load_lds_dwordx4 v[220:221], off
	ds_read_b128 v[178:181], v192 offset:16384
	ds_read_b128 v[182:185], v192 offset:17408
	ds_read_b128 v[194:197], v192 offset:18432
	ds_read_b128 v[198:201], v192 offset:19456
	ds_read_b128 v[202:205], v192 offset:20480
	ds_read_b128 v[206:209], v192 offset:21504
	ds_read_b128 v[210:213], v192 offset:22528
	ds_read_b128 v[214:217], v192 offset:23552
	s_waitcnt vmcnt(8)
	s_waitcnt lgkmcnt(0)
	s_barrier
; #define PG8_STAGE(bufoff, gbase, voff) do { _Pragma("unroll") for (int _i = 0; _i < 2; ++_i) \
;         __builtin_amdgcn_global_load_lds((const unsigned*)((const char*)(gbase) + (voff)[_i]), (LAS unsigned*)(lds + (bufoff) + ldsw + _i * 8192), 16, 0, 0); } while (0)
; #define PG8_LDA(dst, b, h) do { _Pragma("unroll") for (int m = 0; m < 4; ++m) _Pragma("unroll") for (int k = 0; k < 2; ++k) dst[m][k] = *(const LAS bf16x8*)(lds + PG8_SA(b, h) + aoff + m * 2048 + k * 1024); } while (0)
; #define PG8_LDB(dst, b, h) do { _Pragma("unroll") for (int n = 0; n < 2; ++n) _Pragma("unroll") for (int k = 0; k < 2; ++k) dst[n][k] = *(const LAS bf16x8*)(lds + PG8_SB(b, h) + boff + n * 2048 + k * 1024); } while (0)
; #define PG8_MMA(ai, bj, At, Bt) do { __builtin_amdgcn_s_setprio(1); _Pragma("unroll") for (int m = 0; m < 4; ++m) _Pragma("unroll") for (int n = 0; n < 2; ++n) _Pragma("unroll") for (int k = 0; k < 2; ++k) \
;         acc[ai][bj][m][n] = __builtin_amdgcn_mfma_f32_16x16x32_bf16(Bt[n][k], At[m][k], acc[ai][bj][m][n], 0, 0, 0); __builtin_amdgcn_s_setprio(0); } while (0)
; #define PG8_WAIT_V(n) asm volatile("s_waitcnt vmcnt(" #n ")" ::: "memory")
; #define PG8_WAIT_L(n) asm volatile("s_waitcnt lgkmcnt(" #n ")" ::: "memory")
; #define PG8_BAR __builtin_amdgcn_s_barrier()
; #define PG8_SCHED __builtin_amdgcn_sched_barrier(0)
; template <class Epi, bool ALIGN_EPI>
; __device__ __forceinline__ void gemm_phase(LAS unsigned char* lds, const Gemm g, const StaticOrder& S, const Epi& E) {
;     ...
;             PG8_WAIT_V(8); PG8_WAIT_L(0); PG8_BAR; PG8_MMA(1, 0, At, B0); PG8_MMA(1, 1, At, B1); PG8_BAR; PG8_SCHED;
;             PG8_LDB(B0, 1, 0); PG8_LDB(B1, 1, 1); PG8_SCHED; PG8_LDA(At, 1, 0); PG8_STAGE(PG8_SA(0, 1), a2 + hsA, voffA);
;             PG8_WAIT_V(8); PG8_WAIT_L(0); PG8_BAR; PG8_MMA(0, 0, At, B0); PG8_MMA(0, 1, At, B1); PG8_BAR; PG8_SCHED;
	s_waitcnt lgkmcnt(0)
	v_mfma_f32_16x16x32_bf16 v[62:65], v[130:133], v[178:181], v[62:65]
	v_mfma_f32_16x16x32_bf16 v[58:61], v[138:141], v[178:181], v[58:61]
	v_mfma_f32_16x16x32_bf16 v[46:49], v[130:133], v[194:197], v[46:49]
	v_mfma_f32_16x16x32_bf16 v[42:45], v[138:141], v[194:197], v[42:45]
	v_mfma_f32_16x16x32_bf16 v[30:33], v[130:133], v[202:205], v[30:33]
	v_mfma_f32_16x16x32_bf16 v[26:29], v[138:141], v[202:205], v[26:29]
	v_mfma_f32_16x16x32_bf16 v[14:17], v[130:133], v[210:213], v[14:17]
	v_mfma_f32_16x16x32_bf16 v[10:13], v[138:141], v[210:213], v[10:13]
	v_mfma_f32_16x16x32_bf16 v[62:65], v[134:137], v[182:185], v[62:65]
	v_mfma_f32_16x16x32_bf16 v[58:61], v[142:145], v[182:185], v[58:61]
	v_mfma_f32_16x16x32_bf16 v[46:49], v[134:137], v[198:201], v[46:49]
	v_mfma_f32_16x16x32_bf16 v[42:45], v[142:145], v[198:201], v[42:45]
	v_mfma_f32_16x16x32_bf16 v[30:33], v[134:137], v[206:209], v[30:33]
	v_mfma_f32_16x16x32_bf16 v[26:29], v[142:145], v[206:209], v[26:29]
	v_mfma_f32_16x16x32_bf16 v[14:17], v[134:137], v[214:217], v[14:17]
	v_mfma_f32_16x16x32_bf16 v[10:13], v[142:145], v[214:217], v[10:13]
	v_mfma_f32_16x16x32_bf16 v[54:57], v[146:149], v[178:181], v[54:57]
	v_mfma_f32_16x16x32_bf16 v[50:53], v[170:173], v[178:181], v[50:53]
	v_mfma_f32_16x16x32_bf16 v[38:41], v[146:149], v[194:197], v[38:41]
	v_mfma_f32_16x16x32_bf16 v[34:37], v[170:173], v[194:197], v[34:37]
	v_mfma_f32_16x16x32_bf16 v[22:25], v[146:149], v[202:205], v[22:25]
	v_mfma_f32_16x16x32_bf16 v[18:21], v[170:173], v[202:205], v[18:21]
	v_mfma_f32_16x16x32_bf16 v[6:9], v[146:149], v[210:213], v[6:9]
	v_mfma_f32_16x16x32_bf16 v[2:5], v[170:173], v[210:213], v[2:5]
	v_mfma_f32_16x16x32_bf16 v[54:57], v[150:153], v[182:185], v[54:57]
	v_mfma_f32_16x16x32_bf16 v[50:53], v[174:177], v[182:185], v[50:53]
	v_mfma_f32_16x16x32_bf16 v[38:41], v[150:153], v[198:201], v[38:41]
	v_mfma_f32_16x16x32_bf16 v[34:37], v[174:177], v[198:201], v[34:37]
	v_mfma_f32_16x16x32_bf16 v[22:25], v[150:153], v[206:209], v[22:25]
	v_mfma_f32_16x16x32_bf16 v[18:21], v[174:177], v[206:209], v[18:21]
	v_mfma_f32_16x16x32_bf16 v[6:9], v[150:153], v[214:217], v[6:9]
	v_mfma_f32_16x16x32_bf16 v[2:5], v[174:177], v[214:217], v[2:5]
	s_barrier
	s_add_i32 s45, 0, 0x18000
	s_add_i32 s46, 0, 0x1c000
	s_add_u32 s22, s22, 0x4000
	s_addc_u32 s23, s23, 0
	s_mov_b32 m0, s27
	v_lshl_add_u64 v[220:221], s[22:23], 0, v[154:155]
	global_load_lds_dwordx4 v[220:221], off
	v_lshl_add_u64 v[220:221], s[22:23], 0, v[158:159]
	s_mov_b32 m0, s28
	s_nop 0
	global_load_lds_dwordx4 v[220:221], off
	v_add_u32_e32 v142, s45, v188
	v_add_u32_e32 v174, s46, v188
	ds_read_b128 v[130:133], v142
	ds_read_b128 v[134:137], v142 offset:1024
	ds_read_b128 v[138:141], v142 offset:2048
	ds_read_b128 v[142:145], v142 offset:3072
	ds_read_b128 v[146:149], v174
	ds_read_b128 v[150:153], v174 offset:1024
	ds_read_b128 v[170:173], v174 offset:2048
	ds_read_b128 v[174:177], v174 offset:3072
	ds_read_b128 v[178:181], v192 offset:32768
	ds_read_b128 v[182:185], v192 offset:33792
	ds_read_b128 v[194:197], v192 offset:34816
	ds_read_b128 v[198:201], v192 offset:35840
	ds_read_b128 v[202:205], v192 offset:36864
	ds_read_b128 v[206:209], v192 offset:37888
	ds_read_b128 v[210:213], v192 offset:38912
	ds_read_b128 v[214:217], v192 offset:39936
	s_waitcnt vmcnt(8)
	s_waitcnt lgkmcnt(0)
	s_barrier
	s_waitcnt lgkmcnt(0)
	v_mfma_f32_16x16x32_bf16 v[126:129], v[130:133], v[178:181], v[126:129]
	v_mfma_f32_16x16x32_bf16 v[122:125], v[138:141], v[178:181], v[122:125]
	v_mfma_f32_16x16x32_bf16 v[110:113], v[130:133], v[194:197], v[110:113]
	v_mfma_f32_16x16x32_bf16 v[106:109], v[138:141], v[194:197], v[106:109]
	v_mfma_f32_16x16x32_bf16 v[94:97], v[130:133], v[202:205], v[94:97]
	v_mfma_f32_16x16x32_bf16 v[90:93], v[138:141], v[202:205], v[90:93]
	v_mfma_f32_16x16x32_bf16 v[78:81], v[130:133], v[210:213], v[78:81]
	v_mfma_f32_16x16x32_bf16 v[74:77], v[138:141], v[210:213], v[74:77]
	v_mfma_f32_16x16x32_bf16 v[126:129], v[134:137], v[182:185], v[126:129]
	v_mfma_f32_16x16x32_bf16 v[122:125], v[142:145], v[182:185], v[122:125]
	v_mfma_f32_16x16x32_bf16 v[110:113], v[134:137], v[198:201], v[110:113]
	v_mfma_f32_16x16x32_bf16 v[106:109], v[142:145], v[198:201], v[106:109]
	v_mfma_f32_16x16x32_bf16 v[94:97], v[134:137], v[206:209], v[94:97]
	v_mfma_f32_16x16x32_bf16 v[90:93], v[142:145], v[206:209], v[90:93]
	v_mfma_f32_16x16x32_bf16 v[78:81], v[134:137], v[214:217], v[78:81]
	v_mfma_f32_16x16x32_bf16 v[74:77], v[142:145], v[214:217], v[74:77]
	v_mfma_f32_16x16x32_bf16 v[118:121], v[146:149], v[178:181], v[118:121]
	v_mfma_f32_16x16x32_bf16 v[114:117], v[170:173], v[178:181], v[114:117]
	v_mfma_f32_16x16x32_bf16 v[102:105], v[146:149], v[194:197], v[102:105]
	v_mfma_f32_16x16x32_bf16 v[98:101], v[170:173], v[194:197], v[98:101]
	v_mfma_f32_16x16x32_bf16 v[86:89], v[146:149], v[202:205], v[86:89]
	v_mfma_f32_16x16x32_bf16 v[82:85], v[170:173], v[202:205], v[82:85]
	v_mfma_f32_16x16x32_bf16 v[70:73], v[146:149], v[210:213], v[70:73]
	v_mfma_f32_16x16x32_bf16 v[66:69], v[170:173], v[210:213], v[66:69]
	v_mfma_f32_16x16x32_bf16 v[118:121], v[150:153], v[182:185], v[118:121]
	v_mfma_f32_16x16x32_bf16 v[114:117], v[174:177], v[182:185], v[114:117]
	v_mfma_f32_16x16x32_bf16 v[102:105], v[150:153], v[198:201], v[102:105]
	v_mfma_f32_16x16x32_bf16 v[98:101], v[174:177], v[198:201], v[98:101]
	v_mfma_f32_16x16x32_bf16 v[86:89], v[150:153], v[206:209], v[86:89]
	v_mfma_f32_16x16x32_bf16 v[82:85], v[174:177], v[206:209], v[82:85]
	v_mfma_f32_16x16x32_bf16 v[70:73], v[150:153], v[214:217], v[70:73]
	v_mfma_f32_16x16x32_bf16 v[66:69], v[174:177], v[214:217], v[66:69]
	s_barrier
; #define PG8_STAGE(bufoff, gbase, voff) do { _Pragma("unroll") for (int _i = 0; _i < 2; ++_i) \
;         __builtin_amdgcn_global_load_lds((const unsigned*)((const char*)(gbase) + (voff)[_i]), (LAS unsigned*)(lds + (bufoff) + ldsw + _i * 8192), 16, 0, 0); } while (0)
; #define PG8_LDA(dst, b, h) do { _Pragma("unroll") for (int m = 0; m < 4; ++m) _Pragma("unroll") for (int k = 0; k < 2; ++k) dst[m][k] = *(const LAS bf16x8*)(lds + PG8_SA(b, h) + aoff + m * 2048 + k * 1024); } while (0)
; #define PG8_MMA(ai, bj, At, Bt) do { __builtin_amdgcn_s_setprio(1); _Pragma("unroll") for (int m = 0; m < 4; ++m) _Pragma("unroll") for (int n = 0; n < 2; ++n) _Pragma("unroll") for (int k = 0; k < 2; ++k) \
;         acc[ai][bj][m][n] = __builtin_amdgcn_mfma_f32_16x16x32_bf16(Bt[n][k], At[m][k], acc[ai][bj][m][n], 0, 0, 0); __builtin_amdgcn_s_setprio(0); } while (0)
; #define PG8_WAIT_V(n) asm volatile("s_waitcnt vmcnt(" #n ")" ::: "memory")
; #define PG8_WAIT_L(n) asm volatile("s_waitcnt lgkmcnt(" #n ")" ::: "memory")
; #define PG8_BAR __builtin_amdgcn_s_barrier()
; #define PG8_SCHED __builtin_amdgcn_sched_barrier(0)
; template <class Epi, bool ALIGN_EPI>
; __device__ __forceinline__ void gemm_phase(LAS unsigned char* lds, const Gemm g, const StaticOrder& S, const Epi& E) {
;     ...
;             PG8_LDA(At, 1, 1); PG8_STAGE(PG8_SB(1, 0), b3, voffB); PG8_STAGE(PG8_SB(1, 1), b3 + hsB, voffB); PG8_STAGE(PG8_SA(1, 0), a3, voffA);
;             PG8_WAIT_V(8); PG8_WAIT_L(0); PG8_BAR; PG8_MMA(1, 0, At, B0); PG8_MMA(1, 1, At, B1); PG8_BAR; PG8_SCHED;
;         }
;         if constexpr (ALIGN_EPI) { if (wr == 0) PG8_BAR; }
	s_add_i32 s22, s45, s24
	v_lshl_add_u64 v[186:187], v[186:187], 0, s[10:11]
	s_mov_b32 m0, s22
	s_nop 0
	global_load_lds_dwordx4 v[186:187], off
	s_add_i32 m0, s22, 0x2000
	s_add_u32 s20, s20, 0xb0080
	v_lshl_add_u64 v[186:187], v[218:219], 0, s[10:11]
	s_addc_u32 s21, s21, 0
	s_add_i32 s22, s46, s24
	global_load_lds_dwordx4 v[186:187], off
	v_lshl_add_u64 v[186:187], s[20:21], 0, v[156:157]
	s_mov_b32 m0, s22
	s_nop 0
	global_load_lds_dwordx4 v[186:187], off
	v_lshl_add_u64 v[186:187], s[20:21], 0, v[160:161]
	s_add_i32 m0, s22, 0x2000
	s_nop 0
	global_load_lds_dwordx4 v[186:187], off
	v_lshl_add_u64 v[186:187], s[18:19], 0, v[154:155]
	s_mov_b32 m0, s30
	s_nop 0
	global_load_lds_dwordx4 v[186:187], off
	v_lshl_add_u64 v[186:187], s[18:19], 0, v[158:159]
	s_mov_b32 m0, s31
	s_nop 0
	global_load_lds_dwordx4 v[186:187], off
	ds_read_b128 v[178:181], v192 offset:49152
	ds_read_b128 v[182:185], v192 offset:50176
	ds_read_b128 v[194:197], v192 offset:51200
	ds_read_b128 v[198:201], v192 offset:52224
	ds_read_b128 v[202:205], v192 offset:53248
	ds_read_b128 v[206:209], v192 offset:54272
	ds_read_b128 v[210:213], v192 offset:55296
	ds_read_b128 v[214:217], v192 offset:56320
	s_waitcnt vmcnt(8)
	s_waitcnt lgkmcnt(0)
	s_barrier
	s_waitcnt lgkmcnt(0)
	v_mfma_f32_16x16x32_bf16 v[62:65], v[130:133], v[178:181], v[62:65]
	v_mfma_f32_16x16x32_bf16 v[58:61], v[138:141], v[178:181], v[58:61]
	v_mfma_f32_16x16x32_bf16 v[46:49], v[130:133], v[194:197], v[46:49]
	v_mfma_f32_16x16x32_bf16 v[42:45], v[138:141], v[194:197], v[42:45]
	v_mfma_f32_16x16x32_bf16 v[30:33], v[130:133], v[202:205], v[30:33]
	v_mfma_f32_16x16x32_bf16 v[26:29], v[138:141], v[202:205], v[26:29]
	v_mfma_f32_16x16x32_bf16 v[14:17], v[130:133], v[210:213], v[14:17]
	v_mfma_f32_16x16x32_bf16 v[10:13], v[138:141], v[210:213], v[10:13]
	v_mfma_f32_16x16x32_bf16 v[62:65], v[134:137], v[182:185], v[62:65]
	v_mfma_f32_16x16x32_bf16 v[58:61], v[142:145], v[182:185], v[58:61]
	v_mfma_f32_16x16x32_bf16 v[46:49], v[134:137], v[198:201], v[46:49]
	v_mfma_f32_16x16x32_bf16 v[42:45], v[142:145], v[198:201], v[42:45]
	v_mfma_f32_16x16x32_bf16 v[30:33], v[134:137], v[206:209], v[30:33]
	v_mfma_f32_16x16x32_bf16 v[26:29], v[142:145], v[206:209], v[26:29]
	v_mfma_f32_16x16x32_bf16 v[14:17], v[134:137], v[214:217], v[14:17]
	v_mfma_f32_16x16x32_bf16 v[10:13], v[142:145], v[214:217], v[10:13]
	v_mfma_f32_16x16x32_bf16 v[54:57], v[146:149], v[178:181], v[54:57]
	v_mfma_f32_16x16x32_bf16 v[50:53], v[170:173], v[178:181], v[50:53]
	v_mfma_f32_16x16x32_bf16 v[38:41], v[146:149], v[194:197], v[38:41]
	v_mfma_f32_16x16x32_bf16 v[34:37], v[170:173], v[194:197], v[34:37]
	v_mfma_f32_16x16x32_bf16 v[22:25], v[146:149], v[202:205], v[22:25]
	v_mfma_f32_16x16x32_bf16 v[18:21], v[170:173], v[202:205], v[18:21]
	v_mfma_f32_16x16x32_bf16 v[6:9], v[146:149], v[210:213], v[6:9]
	v_mfma_f32_16x16x32_bf16 v[2:5], v[170:173], v[210:213], v[2:5]
	v_mfma_f32_16x16x32_bf16 v[54:57], v[150:153], v[182:185], v[54:57]
	v_mfma_f32_16x16x32_bf16 v[50:53], v[174:177], v[182:185], v[50:53]
	v_mfma_f32_16x16x32_bf16 v[38:41], v[150:153], v[198:201], v[38:41]
	v_mfma_f32_16x16x32_bf16 v[34:37], v[174:177], v[198:201], v[34:37]
	v_mfma_f32_16x16x32_bf16 v[22:25], v[150:153], v[206:209], v[22:25]
	v_mfma_f32_16x16x32_bf16 v[18:21], v[174:177], v[206:209], v[18:21]
	v_mfma_f32_16x16x32_bf16 v[6:9], v[150:153], v[214:217], v[6:9]
	v_mfma_f32_16x16x32_bf16 v[2:5], v[174:177], v[214:217], v[2:5]
	s_barrier
	s_add_i32 s44, s44, 2
	s_add_u32 s16, s16, 0x10000
	s_addc_u32 s17, s17, 0
	s_add_u32 s42, s42, 0x100
	s_addc_u32 s43, s43, 0
	s_cmp_gt_u32 s44, 41
	s_cbranch_scc0 .LBB0_1405
	s_and_b64 vcc, exec, s[12:13]
	s_cbranch_vccz .LBB0_1408
	s_barrier

; #define PG8_STAGE(bufoff, gbase, voff) do { _Pragma("unroll") for (int _i = 0; _i < 2; ++_i) \
;         __builtin_amdgcn_global_load_lds((const unsigned*)((const char*)(gbase) + (voff)[_i]), (LAS unsigned*)(lds + (bufoff) + ldsw + _i * 8192), 16, 0, 0); } while (0)
; #define PG8_LDA(dst, b, h) do { _Pragma("unroll") for (int m = 0; m < 4; ++m) _Pragma("unroll") for (int k = 0; k < 2; ++k) dst[m][k] = *(const LAS bf16x8*)(lds + PG8_SA(b, h) + aoff + m * 2048 + k * 1024); } while (0)
; #define PG8_LDB(dst, b, h) do { _Pragma("unroll") for (int n = 0; n < 2; ++n) _Pragma("unroll") for (int k = 0; k < 2; ++k) dst[n][k] = *(const LAS bf16x8*)(lds + PG8_SB(b, h) + boff + n * 2048 + k * 1024); } while (0)
; #define PG8_MMA(ai, bj, At, Bt) do { __builtin_amdgcn_s_setprio(1); _Pragma("unroll") for (int m = 0; m < 4; ++m) _Pragma("unroll") for (int n = 0; n < 2; ++n) _Pragma("unroll") for (int k = 0; k < 2; ++k) \
;         acc[ai][bj][m][n] = __builtin_amdgcn_mfma_f32_16x16x32_bf16(Bt[n][k], At[m][k], acc[ai][bj][m][n], 0, 0, 0); __builtin_amdgcn_s_setprio(0); } while (0)
; #define PG8_WAIT_V(n) asm volatile("s_waitcnt vmcnt(" #n ")" ::: "memory")
; #define PG8_WAIT_L(n) asm volatile("s_waitcnt lgkmcnt(" #n ")" ::: "memory")
; #define PG8_BAR __builtin_amdgcn_s_barrier()
; #define PG8_SCHED __builtin_amdgcn_sched_barrier(0)
; template <class Epi, bool ALIGN_EPI>
; __device__ __forceinline__ void gemm_phase(LAS unsigned char* lds, const Gemm g, const StaticOrder& S, const Epi& E) {
;     ...
;             PG8_LDB(B0, 0, 0); PG8_LDB(B1, 0, 1); PG8_SCHED; PG8_LDA(At, 0, 0); PG8_STAGE(PG8_SA(1, 1), a1 + hsA, voffA);
;             PG8_WAIT_V(8); PG8_WAIT_L(0); PG8_BAR; PG8_MMA(0, 0, At, B0); PG8_MMA(0, 1, At, B1); PG8_BAR; PG8_SCHED;
;             PG8_LDA(At, 0, 1); PG8_STAGE(PG8_SB(0, 0), b2, voffB); PG8_STAGE(PG8_SB(0, 1), b2 + hsB, voffB); PG8_STAGE(PG8_SA(0, 0), a2, voffA);
;             PG8_WAIT_V(8); PG8_WAIT_L(0); PG8_BAR; PG8_MMA(1, 0, At, B0); PG8_MMA(1, 1, At, B1); PG8_BAR; PG8_SCHED;
.LBB0_1501:
	s_add_u32 s28, s24, 0xfffc0080
	s_addc_u32 s29, s25, -1
	s_cmp_eq_u32 s49, 12
	s_cselect_b32 s31, s19, s29
	s_cselect_b32 s30, s45, s28
	s_cselect_b32 s29, s21, s48
	s_cselect_b32 s28, s46, s47
	v_lshl_add_u64 v[216:217], s[24:25], 0, v[184:185]
	s_add_i32 m0, s9, 0xc000
	s_nop 0
	global_load_lds_dwordx4 v[216:217], off
	v_lshl_add_u64 v[216:217], s[24:25], 0, v[186:187]
	s_add_i32 m0, s9, 0xe000
	s_nop 0
	global_load_lds_dwordx4 v[216:217], off
	ds_read_b128 v[128:131], v203
	ds_read_b128 v[132:135], v203 offset:1024
	ds_read_b128 v[136:139], v203 offset:2048
	ds_read_b128 v[140:143], v203 offset:3072
	ds_read_b128 v[144:147], v204
	ds_read_b128 v[148:151], v204 offset:1024
	ds_read_b128 v[152:155], v204 offset:2048
	ds_read_b128 v[156:159], v204 offset:3072
	ds_read_b128 v[160:163], v205
	ds_read_b128 v[164:167], v205 offset:1024
	ds_read_b128 v[168:171], v205 offset:2048
	ds_read_b128 v[172:175], v205 offset:3072
	ds_read_b128 v[192:195], v205 offset:4096
	ds_read_b128 v[196:199], v205 offset:5120
	ds_read_b128 v[208:211], v205 offset:6144
	ds_read_b128 v[212:215], v205 offset:7168
	s_waitcnt vmcnt(8)
	s_waitcnt lgkmcnt(0)
	s_barrier
	s_waitcnt lgkmcnt(0)
	v_mfma_f32_16x16x32_bf16 v[124:127], v[128:131], v[160:163], v[124:127]
	v_mfma_f32_16x16x32_bf16 v[120:123], v[136:139], v[160:163], v[120:123]
	v_mfma_f32_16x16x32_bf16 v[108:111], v[128:131], v[168:171], v[108:111]
	v_mfma_f32_16x16x32_bf16 v[104:107], v[136:139], v[168:171], v[104:107]
	v_mfma_f32_16x16x32_bf16 v[92:95], v[128:131], v[192:195], v[92:95]
	v_mfma_f32_16x16x32_bf16 v[88:91], v[136:139], v[192:195], v[88:91]
	v_mfma_f32_16x16x32_bf16 v[76:79], v[128:131], v[208:211], v[76:79]
	v_mfma_f32_16x16x32_bf16 v[72:75], v[136:139], v[208:211], v[72:75]
	v_mfma_f32_16x16x32_bf16 v[124:127], v[132:135], v[164:167], v[124:127]
	v_mfma_f32_16x16x32_bf16 v[120:123], v[140:143], v[164:167], v[120:123]
	v_mfma_f32_16x16x32_bf16 v[108:111], v[132:135], v[172:175], v[108:111]
	v_mfma_f32_16x16x32_bf16 v[104:107], v[140:143], v[172:175], v[104:107]
	v_mfma_f32_16x16x32_bf16 v[92:95], v[132:135], v[196:199], v[92:95]
	v_mfma_f32_16x16x32_bf16 v[88:91], v[140:143], v[196:199], v[88:91]
	v_mfma_f32_16x16x32_bf16 v[76:79], v[132:135], v[212:215], v[76:79]
	v_mfma_f32_16x16x32_bf16 v[72:75], v[140:143], v[212:215], v[72:75]
	v_mfma_f32_16x16x32_bf16 v[116:119], v[144:147], v[160:163], v[116:119]
	v_mfma_f32_16x16x32_bf16 v[112:115], v[152:155], v[160:163], v[112:115]
	v_mfma_f32_16x16x32_bf16 v[100:103], v[144:147], v[168:171], v[100:103]
	v_mfma_f32_16x16x32_bf16 v[96:99], v[152:155], v[168:171], v[96:99]
	v_mfma_f32_16x16x32_bf16 v[84:87], v[144:147], v[192:195], v[84:87]
	v_mfma_f32_16x16x32_bf16 v[80:83], v[152:155], v[192:195], v[80:83]
	v_mfma_f32_16x16x32_bf16 v[68:71], v[144:147], v[208:211], v[68:71]
	v_mfma_f32_16x16x32_bf16 v[64:67], v[152:155], v[208:211], v[64:67]
	v_mfma_f32_16x16x32_bf16 v[116:119], v[148:151], v[164:167], v[116:119]
	v_mfma_f32_16x16x32_bf16 v[112:115], v[156:159], v[164:167], v[112:115]
	v_mfma_f32_16x16x32_bf16 v[100:103], v[148:151], v[172:175], v[100:103]
	v_mfma_f32_16x16x32_bf16 v[96:99], v[156:159], v[172:175], v[96:99]
	v_mfma_f32_16x16x32_bf16 v[84:87], v[148:151], v[196:199], v[84:87]
	v_mfma_f32_16x16x32_bf16 v[80:83], v[156:159], v[196:199], v[80:83]
	v_mfma_f32_16x16x32_bf16 v[68:71], v[148:151], v[212:215], v[68:71]
	v_mfma_f32_16x16x32_bf16 v[64:67], v[156:159], v[212:215], v[64:67]
	s_barrier
	s_add_i32 s50, s42, s34
	v_lshl_add_u64 v[216:217], s[28:29], 0, v[178:179]
	s_mov_b32 m0, s50
	s_nop 0
	global_load_lds_dwordx4 v[216:217], off
	s_add_i32 m0, s50, 0x2000
	s_add_u32 s50, s28, 0x40000
	v_lshl_add_u64 v[218:219], s[28:29], 0, v[182:183]
	s_addc_u32 s51, s29, 0
	s_add_i32 s52, s43, s34
	global_load_lds_dwordx4 v[218:219], off
	v_lshl_add_u64 v[220:221], s[50:51], 0, v[178:179]
	s_mov_b32 m0, s52
	v_lshl_add_u64 v[222:223], s[30:31], 0, v[180:181]
	global_load_lds_dwordx4 v[220:221], off
	v_lshl_add_u64 v[220:221], s[50:51], 0, v[182:183]
	s_add_i32 m0, s52, 0x2000
	s_nop 0
	global_load_lds_dwordx4 v[220:221], off
	v_lshl_add_u64 v[220:221], s[30:31], 0, v[176:177]
	s_mov_b32 m0, s9
	s_nop 0
	global_load_lds_dwordx4 v[220:221], off
	s_mov_b32 m0, s35
	s_nop 0
	global_load_lds_dwordx4 v[222:223], off
	ds_read_b128 v[160:163], v205 offset:16384
	ds_read_b128 v[164:167], v205 offset:17408
	ds_read_b128 v[168:171], v205 offset:18432
	ds_read_b128 v[172:175], v205 offset:19456
	ds_read_b128 v[192:195], v205 offset:20480
	ds_read_b128 v[196:199], v205 offset:21504
	ds_read_b128 v[208:211], v205 offset:22528
	ds_read_b128 v[212:215], v205 offset:23552
	s_waitcnt vmcnt(8)
	s_waitcnt lgkmcnt(0)
	s_barrier
; #define PG8_STAGE(bufoff, gbase, voff) do { _Pragma("unroll") for (int _i = 0; _i < 2; ++_i) \
;         __builtin_amdgcn_global_load_lds((const unsigned*)((const char*)(gbase) + (voff)[_i]), (LAS unsigned*)(lds + (bufoff) + ldsw + _i * 8192), 16, 0, 0); } while (0)
; #define PG8_LDA(dst, b, h) do { _Pragma("unroll") for (int m = 0; m < 4; ++m) _Pragma("unroll") for (int k = 0; k < 2; ++k) dst[m][k] = *(const LAS bf16x8*)(lds + PG8_SA(b, h) + aoff + m * 2048 + k * 1024); } while (0)
; #define PG8_LDB(dst, b, h) do { _Pragma("unroll") for (int n = 0; n < 2; ++n) _Pragma("unroll") for (int k = 0; k < 2; ++k) dst[n][k] = *(const LAS bf16x8*)(lds + PG8_SB(b, h) + boff + n * 2048 + k * 1024); } while (0)
; #define PG8_MMA(ai, bj, At, Bt) do { __builtin_amdgcn_s_setprio(1); _Pragma("unroll") for (int m = 0; m < 4; ++m) _Pragma("unroll") for (int n = 0; n < 2; ++n) _Pragma("unroll") for (int k = 0; k < 2; ++k) \
;         acc[ai][bj][m][n] = __builtin_amdgcn_mfma_f32_16x16x32_bf16(Bt[n][k], At[m][k], acc[ai][bj][m][n], 0, 0, 0); __builtin_amdgcn_s_setprio(0); } while (0)
; #define PG8_WAIT_V(n) asm volatile("s_waitcnt vmcnt(" #n ")" ::: "memory")
; #define PG8_WAIT_L(n) asm volatile("s_waitcnt lgkmcnt(" #n ")" ::: "memory")
; #define PG8_BAR __builtin_amdgcn_s_barrier()
; #define PG8_SCHED __builtin_amdgcn_sched_barrier(0)
; template <class Epi, bool ALIGN_EPI>
; __device__ __forceinline__ void gemm_phase(LAS unsigned char* lds, const Gemm g, const StaticOrder& S, const Epi& E) {
;     ...
;             PG8_WAIT_V(8); PG8_WAIT_L(0); PG8_BAR; PG8_MMA(1, 0, At, B0); PG8_MMA(1, 1, At, B1); PG8_BAR; PG8_SCHED;
;             PG8_LDB(B0, 1, 0); PG8_LDB(B1, 1, 1); PG8_SCHED; PG8_LDA(At, 1, 0); PG8_STAGE(PG8_SA(0, 1), a2 + hsA, voffA);
;             PG8_WAIT_V(8); PG8_WAIT_L(0); PG8_BAR; PG8_MMA(0, 0, At, B0); PG8_MMA(0, 1, At, B1); PG8_BAR; PG8_SCHED;
	s_waitcnt lgkmcnt(0)
	v_mfma_f32_16x16x32_bf16 v[60:63], v[128:131], v[160:163], v[60:63]
	v_mfma_f32_16x16x32_bf16 v[56:59], v[136:139], v[160:163], v[56:59]
	v_mfma_f32_16x16x32_bf16 v[44:47], v[128:131], v[168:171], v[44:47]
	v_mfma_f32_16x16x32_bf16 v[40:43], v[136:139], v[168:171], v[40:43]
	v_mfma_f32_16x16x32_bf16 v[28:31], v[128:131], v[192:195], v[28:31]
	v_mfma_f32_16x16x32_bf16 v[24:27], v[136:139], v[192:195], v[24:27]
	v_mfma_f32_16x16x32_bf16 v[12:15], v[128:131], v[208:211], v[12:15]
	v_mfma_f32_16x16x32_bf16 v[8:11], v[136:139], v[208:211], v[8:11]
	v_mfma_f32_16x16x32_bf16 v[60:63], v[132:135], v[164:167], v[60:63]
	v_mfma_f32_16x16x32_bf16 v[56:59], v[140:143], v[164:167], v[56:59]
	v_mfma_f32_16x16x32_bf16 v[44:47], v[132:135], v[172:175], v[44:47]
	v_mfma_f32_16x16x32_bf16 v[40:43], v[140:143], v[172:175], v[40:43]
	v_mfma_f32_16x16x32_bf16 v[28:31], v[132:135], v[196:199], v[28:31]
	v_mfma_f32_16x16x32_bf16 v[24:27], v[140:143], v[196:199], v[24:27]
	v_mfma_f32_16x16x32_bf16 v[12:15], v[132:135], v[212:215], v[12:15]
	v_mfma_f32_16x16x32_bf16 v[8:11], v[140:143], v[212:215], v[8:11]
	v_mfma_f32_16x16x32_bf16 v[52:55], v[144:147], v[160:163], v[52:55]
	v_mfma_f32_16x16x32_bf16 v[48:51], v[152:155], v[160:163], v[48:51]
	v_mfma_f32_16x16x32_bf16 v[36:39], v[144:147], v[168:171], v[36:39]
	v_mfma_f32_16x16x32_bf16 v[32:35], v[152:155], v[168:171], v[32:35]
	v_mfma_f32_16x16x32_bf16 v[20:23], v[144:147], v[192:195], v[20:23]
	v_mfma_f32_16x16x32_bf16 v[16:19], v[152:155], v[192:195], v[16:19]
	v_mfma_f32_16x16x32_bf16 v[4:7], v[144:147], v[208:211], v[4:7]
	v_mfma_f32_16x16x32_bf16 v[0:3], v[152:155], v[208:211], v[0:3]
	v_mfma_f32_16x16x32_bf16 v[52:55], v[148:151], v[164:167], v[52:55]
	v_mfma_f32_16x16x32_bf16 v[48:51], v[156:159], v[164:167], v[48:51]
	v_mfma_f32_16x16x32_bf16 v[36:39], v[148:151], v[172:175], v[36:39]
	v_mfma_f32_16x16x32_bf16 v[32:35], v[156:159], v[172:175], v[32:35]
	v_mfma_f32_16x16x32_bf16 v[20:23], v[148:151], v[196:199], v[20:23]
	v_mfma_f32_16x16x32_bf16 v[16:19], v[156:159], v[196:199], v[16:19]
	v_mfma_f32_16x16x32_bf16 v[4:7], v[148:151], v[212:215], v[4:7]
	v_mfma_f32_16x16x32_bf16 v[0:3], v[156:159], v[212:215], v[0:3]
	s_barrier
	s_add_i32 s50, 0, 0x18000
	s_add_i32 s51, 0, 0x1c000
	s_add_u32 s30, s30, 0x40000
	s_addc_u32 s31, s31, 0
	s_mov_b32 m0, s36
	v_lshl_add_u64 v[224:225], s[30:31], 0, v[176:177]
	global_load_lds_dwordx4 v[224:225], off
	v_lshl_add_u64 v[224:225], s[30:31], 0, v[180:181]
	s_mov_b32 m0, s37
	s_nop 0
	global_load_lds_dwordx4 v[224:225], off
	v_add_u32_e32 v140, s50, v201
	v_add_u32_e32 v156, s51, v201
	ds_read_b128 v[128:131], v140
	ds_read_b128 v[132:135], v140 offset:1024
	ds_read_b128 v[136:139], v140 offset:2048
	ds_read_b128 v[140:143], v140 offset:3072
	ds_read_b128 v[144:147], v156
	ds_read_b128 v[148:151], v156 offset:1024
	ds_read_b128 v[152:155], v156 offset:2048
	ds_read_b128 v[156:159], v156 offset:3072
	ds_read_b128 v[160:163], v205 offset:32768
	ds_read_b128 v[164:167], v205 offset:33792
	ds_read_b128 v[168:171], v205 offset:34816
	ds_read_b128 v[172:175], v205 offset:35840
	ds_read_b128 v[192:195], v205 offset:36864
	ds_read_b128 v[196:199], v205 offset:37888
	ds_read_b128 v[208:211], v205 offset:38912
	ds_read_b128 v[212:215], v205 offset:39936
	s_waitcnt vmcnt(8)
	s_waitcnt lgkmcnt(0)
	s_barrier
	s_waitcnt lgkmcnt(0)
	v_mfma_f32_16x16x32_bf16 v[124:127], v[128:131], v[160:163], v[124:127]
	v_mfma_f32_16x16x32_bf16 v[120:123], v[136:139], v[160:163], v[120:123]
	v_mfma_f32_16x16x32_bf16 v[108:111], v[128:131], v[168:171], v[108:111]
	v_mfma_f32_16x16x32_bf16 v[104:107], v[136:139], v[168:171], v[104:107]
	v_mfma_f32_16x16x32_bf16 v[92:95], v[128:131], v[192:195], v[92:95]
	v_mfma_f32_16x16x32_bf16 v[88:91], v[136:139], v[192:195], v[88:91]
	v_mfma_f32_16x16x32_bf16 v[76:79], v[128:131], v[208:211], v[76:79]
	v_mfma_f32_16x16x32_bf16 v[72:75], v[136:139], v[208:211], v[72:75]
	v_mfma_f32_16x16x32_bf16 v[124:127], v[132:135], v[164:167], v[124:127]
	v_mfma_f32_16x16x32_bf16 v[120:123], v[140:143], v[164:167], v[120:123]
	v_mfma_f32_16x16x32_bf16 v[108:111], v[132:135], v[172:175], v[108:111]
	v_mfma_f32_16x16x32_bf16 v[104:107], v[140:143], v[172:175], v[104:107]
	v_mfma_f32_16x16x32_bf16 v[92:95], v[132:135], v[196:199], v[92:95]
	v_mfma_f32_16x16x32_bf16 v[88:91], v[140:143], v[196:199], v[88:91]
	v_mfma_f32_16x16x32_bf16 v[76:79], v[132:135], v[212:215], v[76:79]
	v_mfma_f32_16x16x32_bf16 v[72:75], v[140:143], v[212:215], v[72:75]
	v_mfma_f32_16x16x32_bf16 v[116:119], v[144:147], v[160:163], v[116:119]
	v_mfma_f32_16x16x32_bf16 v[112:115], v[152:155], v[160:163], v[112:115]
	v_mfma_f32_16x16x32_bf16 v[100:103], v[144:147], v[168:171], v[100:103]
	v_mfma_f32_16x16x32_bf16 v[96:99], v[152:155], v[168:171], v[96:99]
	v_mfma_f32_16x16x32_bf16 v[84:87], v[144:147], v[192:195], v[84:87]
	v_mfma_f32_16x16x32_bf16 v[80:83], v[152:155], v[192:195], v[80:83]
	v_mfma_f32_16x16x32_bf16 v[68:71], v[144:147], v[208:211], v[68:71]
	v_mfma_f32_16x16x32_bf16 v[64:67], v[152:155], v[208:211], v[64:67]
	v_mfma_f32_16x16x32_bf16 v[116:119], v[148:151], v[164:167], v[116:119]
	v_mfma_f32_16x16x32_bf16 v[112:115], v[156:159], v[164:167], v[112:115]
	v_mfma_f32_16x16x32_bf16 v[100:103], v[148:151], v[172:175], v[100:103]
	v_mfma_f32_16x16x32_bf16 v[96:99], v[156:159], v[172:175], v[96:99]
	v_mfma_f32_16x16x32_bf16 v[84:87], v[148:151], v[196:199], v[84:87]
	v_mfma_f32_16x16x32_bf16 v[80:83], v[156:159], v[196:199], v[80:83]
	v_mfma_f32_16x16x32_bf16 v[68:71], v[148:151], v[212:215], v[68:71]
	v_mfma_f32_16x16x32_bf16 v[64:67], v[156:159], v[212:215], v[64:67]
	s_barrier
; #define PG8_STAGE(bufoff, gbase, voff) do { _Pragma("unroll") for (int _i = 0; _i < 2; ++_i) \
;         __builtin_amdgcn_global_load_lds((const unsigned*)((const char*)(gbase) + (voff)[_i]), (LAS unsigned*)(lds + (bufoff) + ldsw + _i * 8192), 16, 0, 0); } while (0)
; #define PG8_LDA(dst, b, h) do { _Pragma("unroll") for (int m = 0; m < 4; ++m) _Pragma("unroll") for (int k = 0; k < 2; ++k) dst[m][k] = *(const LAS bf16x8*)(lds + PG8_SA(b, h) + aoff + m * 2048 + k * 1024); } while (0)
; #define PG8_MMA(ai, bj, At, Bt) do { __builtin_amdgcn_s_setprio(1); _Pragma("unroll") for (int m = 0; m < 4; ++m) _Pragma("unroll") for (int n = 0; n < 2; ++n) _Pragma("unroll") for (int k = 0; k < 2; ++k) \
;         acc[ai][bj][m][n] = __builtin_amdgcn_mfma_f32_16x16x32_bf16(Bt[n][k], At[m][k], acc[ai][bj][m][n], 0, 0, 0); __builtin_amdgcn_s_setprio(0); } while (0)
; #define PG8_WAIT_V(n) asm volatile("s_waitcnt vmcnt(" #n ")" ::: "memory")
; #define PG8_WAIT_L(n) asm volatile("s_waitcnt lgkmcnt(" #n ")" ::: "memory")
; #define PG8_BAR __builtin_amdgcn_s_barrier()
; #define PG8_SCHED __builtin_amdgcn_sched_barrier(0)
; template <class Epi, bool ALIGN_EPI>
; __device__ __forceinline__ void gemm_phase(LAS unsigned char* lds, const Gemm g, const StaticOrder& S, const Epi& E) {
;     ...
;             PG8_LDA(At, 1, 1); PG8_STAGE(PG8_SB(1, 0), b3, voffB); PG8_STAGE(PG8_SB(1, 1), b3 + hsB, voffB); PG8_STAGE(PG8_SA(1, 0), a3, voffA);
;             PG8_WAIT_V(8); PG8_WAIT_L(0); PG8_BAR; PG8_MMA(1, 0, At, B0); PG8_MMA(1, 1, At, B1); PG8_BAR; PG8_SCHED;
;         }
;         if constexpr (ALIGN_EPI) { if (wr == 0) PG8_BAR; }
	s_add_i32 s30, s50, s34
	v_lshl_add_u64 v[216:217], v[216:217], 0, s[4:5]
	s_mov_b32 m0, s30
	s_nop 0
	global_load_lds_dwordx4 v[216:217], off
	s_add_i32 m0, s30, 0x2000
	s_add_u32 s28, s28, 0x40080
	v_lshl_add_u64 v[216:217], v[218:219], 0, s[4:5]
	s_addc_u32 s29, s29, 0
	s_add_i32 s30, s51, s34
	global_load_lds_dwordx4 v[216:217], off
	v_lshl_add_u64 v[216:217], s[28:29], 0, v[178:179]
	s_mov_b32 m0, s30
	s_nop 0
	global_load_lds_dwordx4 v[216:217], off
	v_lshl_add_u64 v[216:217], s[28:29], 0, v[182:183]
	s_add_i32 m0, s30, 0x2000
	s_nop 0
	global_load_lds_dwordx4 v[216:217], off
	v_lshl_add_u64 v[216:217], v[220:221], 0, s[4:5]
	s_mov_b32 m0, s39
	s_nop 0
	global_load_lds_dwordx4 v[216:217], off
	v_lshl_add_u64 v[216:217], v[222:223], 0, s[4:5]
	s_mov_b32 m0, s40
	s_nop 0
	global_load_lds_dwordx4 v[216:217], off
	ds_read_b128 v[160:163], v205 offset:49152
	ds_read_b128 v[164:167], v205 offset:50176
	ds_read_b128 v[168:171], v205 offset:51200
	ds_read_b128 v[172:175], v205 offset:52224
	ds_read_b128 v[192:195], v205 offset:53248
	ds_read_b128 v[196:199], v205 offset:54272
	ds_read_b128 v[208:211], v205 offset:55296
	ds_read_b128 v[212:215], v205 offset:56320
	s_waitcnt vmcnt(8)
	s_waitcnt lgkmcnt(0)
	s_barrier
	s_waitcnt lgkmcnt(0)
	v_mfma_f32_16x16x32_bf16 v[60:63], v[128:131], v[160:163], v[60:63]
	v_mfma_f32_16x16x32_bf16 v[56:59], v[136:139], v[160:163], v[56:59]
	v_mfma_f32_16x16x32_bf16 v[44:47], v[128:131], v[168:171], v[44:47]
	v_mfma_f32_16x16x32_bf16 v[40:43], v[136:139], v[168:171], v[40:43]
	v_mfma_f32_16x16x32_bf16 v[28:31], v[128:131], v[192:195], v[28:31]
	v_mfma_f32_16x16x32_bf16 v[24:27], v[136:139], v[192:195], v[24:27]
	v_mfma_f32_16x16x32_bf16 v[12:15], v[128:131], v[208:211], v[12:15]
	v_mfma_f32_16x16x32_bf16 v[8:11], v[136:139], v[208:211], v[8:11]
	v_mfma_f32_16x16x32_bf16 v[60:63], v[132:135], v[164:167], v[60:63]
	v_mfma_f32_16x16x32_bf16 v[56:59], v[140:143], v[164:167], v[56:59]
	v_mfma_f32_16x16x32_bf16 v[44:47], v[132:135], v[172:175], v[44:47]
	v_mfma_f32_16x16x32_bf16 v[40:43], v[140:143], v[172:175], v[40:43]
	v_mfma_f32_16x16x32_bf16 v[28:31], v[132:135], v[196:199], v[28:31]
	v_mfma_f32_16x16x32_bf16 v[24:27], v[140:143], v[196:199], v[24:27]
	v_mfma_f32_16x16x32_bf16 v[12:15], v[132:135], v[212:215], v[12:15]
	v_mfma_f32_16x16x32_bf16 v[8:11], v[140:143], v[212:215], v[8:11]
	v_mfma_f32_16x16x32_bf16 v[52:55], v[144:147], v[160:163], v[52:55]
	v_mfma_f32_16x16x32_bf16 v[48:51], v[152:155], v[160:163], v[48:51]
	v_mfma_f32_16x16x32_bf16 v[36:39], v[144:147], v[168:171], v[36:39]
	v_mfma_f32_16x16x32_bf16 v[32:35], v[152:155], v[168:171], v[32:35]
	v_mfma_f32_16x16x32_bf16 v[20:23], v[144:147], v[192:195], v[20:23]
	v_mfma_f32_16x16x32_bf16 v[16:19], v[152:155], v[192:195], v[16:19]
	v_mfma_f32_16x16x32_bf16 v[4:7], v[144:147], v[208:211], v[4:7]
	v_mfma_f32_16x16x32_bf16 v[0:3], v[152:155], v[208:211], v[0:3]
	v_mfma_f32_16x16x32_bf16 v[52:55], v[148:151], v[164:167], v[52:55]
	v_mfma_f32_16x16x32_bf16 v[48:51], v[156:159], v[164:167], v[48:51]
	v_mfma_f32_16x16x32_bf16 v[36:39], v[148:151], v[172:175], v[36:39]
	v_mfma_f32_16x16x32_bf16 v[32:35], v[156:159], v[172:175], v[32:35]
	v_mfma_f32_16x16x32_bf16 v[20:23], v[148:151], v[196:199], v[20:23]
	v_mfma_f32_16x16x32_bf16 v[16:19], v[156:159], v[196:199], v[16:19]
	v_mfma_f32_16x16x32_bf16 v[4:7], v[148:151], v[212:215], v[4:7]
	v_mfma_f32_16x16x32_bf16 v[0:3], v[156:159], v[212:215], v[0:3]
	s_barrier
	s_add_i32 s49, s49, 2
	s_add_u32 s24, s24, 0x100
	s_addc_u32 s25, s25, 0
	s_add_u32 s47, s47, 0x100
	s_addc_u32 s48, s48, 0
	s_cmp_gt_u32 s49, 13
	s_cbranch_scc0 .LBB0_1501
	s_and_b64 vcc, exec, s[6:7]
	s_cbranch_vccz .LBB0_1504
	s_barrier
